# indexer keys staged via coalesced LDS-DMA (8 full rows per wave-instruction, XOR-swizzled) + ds_read_b128, ring of 4 slots per wave
# speedup vs baseline: 1.0118x; 1.0073x over previous
; #define MFMA(a, b, c) __builtin_amdgcn_mfma_f32_32x32x16_bf16((a), (b), (c), 0, 0, 0)
; DI float bf2f(unsigned b) { return __uint_as_float(b << 16); }
; DI void indexer_phase(const u16* __restrict__ P, unsigned* __restrict__ mask) {
;     ...
;     const int b = item & 7, t0 = (1023 - (item >> 3)) * 2;
;     const size_t brow = (size_t)b * SEQ;
;     const int g = (r32 >> 2) & 1, head = 4 * (r32 >> 3) + (r32 & 3);
;     bf16x8 aq[4];
; #pragma unroll
;     for (int s = 0; s < 4; ++s) aq[s] = *(const bf16x8*)(P + (brow + t0 + g) * 7808 + 2560 + head * 64 + 16 * s + 8 * hi);
;     float wv[16];
;     {
;       const u32x4 w0 = *(const u32x4*)(P + (brow + t0 + hi) * 7808 + 3648), w1 = *(const u32x4*)(P + (brow + t0 + hi) * 7808 + 3656);
; #pragma unroll
;       for (int j = 0; j < 4; ++j) { wv[2 * j] = bf2f(w0[j] & 0xffffu); wv[2 * j + 1] = bf2f(w0[j] >> 16); wv[8 + 2 * j] = bf2f(w1[j] & 0xffffu); wv[8 + 2 * j + 1] = bf2f(w1[j] >> 16); }
;     }
;     const int tme = t0 + hi, kbmax = (t0 + 1) >> 5;
;     unsigned sc[64];
; #pragma unroll
;     for (int kb = 0; kb < 64; ++kb) {
;       unsigned u = 0u;
;       if (kb <= kbmax) {
;         f32x16 a;
; #pragma unroll
;         for (int r = 0; r < 16; ++r) a[r] = 0.f;
;         const u16* kp = P + (brow + 32 * kb + r32) * 7808 + 3584 + 8 * hi;
; #pragma unroll
;         for (int s = 0; s < 4; ++s) { const bf16x8 bk = *(const bf16x8*)(kp + 16 * s); a = MFMA(aq[s], bk, a); }
.LBB0_846:
	s_bitcmp0_b32 s87, 0
	s_cselect_b64 vcc, -1, 0
	v_cndmask_b32_e32 v2, v55, v53, vcc
	v_add_u32_e32 v3, s89, v2
	v_cmp_gt_i32_e32 vcc, s2, v3
	s_and_saveexec_b64 s[8:9], vcc
	s_cbranch_execz .LBB0_845
	v_ashrrev_i32_e32 v3, 2, v3
	v_and_b32_e32 v3, -2, v3
	v_lshlrev_b32_e32 v2, 11, v2
	v_sub_u32_e32 v144, 0x7fe, v3
	v_and_b32_e32 v126, 0x3800, v2
	v_add_u32_e32 v8, v144, v126
	v_or_b32_e32 v4, v8, v52
	v_mov_b64_e32 v[2:3], s[96:97]
	s_movk_i32 s23, 0x3d00
	v_mad_u64_u32 v[4:5], s[0:1], v4, s23, v[2:3]
	v_lshl_add_u64 v[4:5], v[4:5], 0, v[0:1]
	v_lshlrev_b32_e32 v60, 1, v54
	v_mov_b32_e32 v61, v1
	v_lshl_add_u64 v[4:5], v[4:5], 0, v[60:61]
	s_mov_b64 s[0:1], 0x1400
	s_movk_i32 s22, 0x1000
	v_lshl_add_u64 v[6:7], v[4:5], 0, s[0:1]
	v_add_co_u32_e32 v4, vcc, s22, v4
	v_writelane_b32 v255, s8, 56
	s_nop 0
	v_addc_co_u32_e32 v5, vcc, 0, v5, vcc
	global_load_dwordx4 v[46:49], v[4:5], off offset:1024
	global_load_dwordx4 v[42:45], v[6:7], off offset:32
	global_load_dwordx4 v[38:41], v[6:7], off offset:64
	global_load_dwordx4 v[34:37], v[6:7], off offset:96
	v_or_b32_e32 v4, v8, v50
	v_mad_u64_u32 v[2:3], s[0:1], v4, s23, v[2:3]
	s_mov_b64 s[0:1], 0x1c80
	s_nop 0
	v_lshl_add_u64 v[6:7], v[2:3], 0, s[0:1]
	v_add_co_u32_e32 v2, vcc, s22, v2
	s_mov_b64 s[0:1], 0x1c00
	s_nop 0
	v_addc_co_u32_e32 v3, vcc, 0, v3, vcc
	global_load_dwordx4 v[2:5], v[2:3], off offset:3200
	s_nop 0
	global_load_dwordx4 v[6:9], v[6:7], off offset:16
	v_writelane_b32 v255, s9, 57
	v_or_b32_e32 v127, v144, v50
	s_brev_b32 s8, 1
	v_mul_u32_u24_e32 v10, 0x1e80, v126
	v_readfirstlane_b32 s0, v144
	v_lshlrev_b32_e32 v10, 1, v10
	v_readfirstlane_b32 s1, v179
	v_add_u32_e32 v10, 0x1c00, v10
	v_mov_b32_e32 v11, v1
	v_lshl_add_u64 v[10:11], s[96:97], 0, v[10:11]
	s_lshr_b32 s1, s1, 6
	v_and_b32_e32 v12, 63, v179
	v_readfirstlane_b32 s22, v10
	v_readfirstlane_b32 s23, v11
	s_lshl_b32 s1, s1, 14
	v_lshrrev_b32_e32 v13, 3, v12
	v_lshrrev_b32_e32 v14, 4, v12
	v_mul_u32_u24_e32 v13, 0x3d00, v13
	v_xor_b32_e32 v14, v14, v12
	v_and_b32_e32 v14, 7, v14
	v_lshl_add_u32 v112, v14, 4, v13
	v_xor_b32_e32 v113, 64, v112
	v_bfe_u32 v13, v12, 1, 3
	v_xor_b32_e32 v13, v13, v50
	v_lshlrev_b32_e32 v13, 4, v13
	v_lshl_add_u32 v13, v51, 7, v13
	v_add_u32_e32 v114, s1, v13
	v_xor_b32_e32 v115, 32, v114
	v_xor_b32_e32 v116, 64, v114
	v_xor_b32_e32 v117, 0x60, v114
	v_sub_u32_e32 v16, v127, v51
	s_add_u32 m0, s1, 0
	s_nop 0
	global_load_lds_dwordx4 v112, s[22:23]
	s_add_u32 s22, s22, 0x1e800
	s_addc_u32 s23, s23, 0
	s_add_u32 m0, s1, 0x400
	s_nop 0
	global_load_lds_dwordx4 v113, s[22:23]
	s_add_u32 s22, s22, 0x1e800
	s_addc_u32 s23, s23, 0
	s_add_u32 m0, s1, 0x800
	s_nop 0
	global_load_lds_dwordx4 v112, s[22:23]
	s_add_u32 s22, s22, 0x1e800
	s_addc_u32 s23, s23, 0
	s_add_u32 m0, s1, 0xc00
	s_nop 0
	global_load_lds_dwordx4 v113, s[22:23]
	s_add_u32 s22, s22, 0x1e800
	s_addc_u32 s23, s23, 0
	s_cmp_lt_u32 s0, 32
	s_cbranch_scc1 .Lix_pro_done
	s_add_u32 m0, s1, 0x1000
	s_nop 0
	global_load_lds_dwordx4 v112, s[22:23]
	s_add_u32 s22, s22, 0x1e800
	s_addc_u32 s23, s23, 0
	s_add_u32 m0, s1, 0x1400
	s_nop 0
	global_load_lds_dwordx4 v113, s[22:23]
	s_add_u32 s22, s22, 0x1e800
	s_addc_u32 s23, s23, 0
	s_add_u32 m0, s1, 0x1800
	s_nop 0
	global_load_lds_dwordx4 v112, s[22:23]
	s_add_u32 s22, s22, 0x1e800
	s_addc_u32 s23, s23, 0
	s_add_u32 m0, s1, 0x1c00
	s_nop 0
	global_load_lds_dwordx4 v113, s[22:23]
	s_add_u32 s22, s22, 0x1e800
	s_addc_u32 s23, s23, 0
	s_cmp_lt_u32 s0, 64
	s_cbranch_scc1 .Lix_pro_done
	s_add_u32 m0, s1, 0x2000
	s_nop 0
	global_load_lds_dwordx4 v112, s[22:23]
	s_add_u32 s22, s22, 0x1e800
	s_addc_u32 s23, s23, 0
	s_add_u32 m0, s1, 0x2400
	s_nop 0
	global_load_lds_dwordx4 v113, s[22:23]
	s_add_u32 s22, s22, 0x1e800
	s_addc_u32 s23, s23, 0
	s_add_u32 m0, s1, 0x2800
	s_nop 0
	global_load_lds_dwordx4 v112, s[22:23]
	s_add_u32 s22, s22, 0x1e800
	s_addc_u32 s23, s23, 0
	s_add_u32 m0, s1, 0x2c00
	s_nop 0
	global_load_lds_dwordx4 v113, s[22:23]
	s_add_u32 s22, s22, 0x1e800
	s_addc_u32 s23, s23, 0
.Lix_pro_done:
	s_waitcnt vmcnt(0)
	v_lshlrev_b32_e32 v143, 16, v2
	v_and_b32_e32 v142, 0xffff0000, v2
	v_lshlrev_b32_e32 v141, 16, v3
	v_and_b32_e32 v140, 0xffff0000, v3
	v_lshlrev_b32_e32 v139, 16, v4
	v_and_b32_e32 v138, 0xffff0000, v4
	v_lshlrev_b32_e32 v137, 16, v5
	v_and_b32_e32 v136, 0xffff0000, v5
	v_lshlrev_b32_e32 v135, 16, v6
	v_and_b32_e32 v134, 0xffff0000, v6
	v_lshlrev_b32_e32 v133, 16, v7
	v_and_b32_e32 v132, 0xffff0000, v7
	v_lshlrev_b32_e32 v131, 16, v8
	v_and_b32_e32 v130, 0xffff0000, v8
	v_lshlrev_b32_e32 v129, 16, v9
	v_and_b32_e32 v128, 0xffff0000, v9
	ds_read_b128 v[64:67], v114
	ds_read_b128 v[68:71], v115
	ds_read_b128 v[72:75], v116
	ds_read_b128 v[76:79], v117
.Lix_b0:
	s_cmp_lt_u32 s0, 0x60
	s_cbranch_scc1 .Lix_w0
	s_add_u32 m0, s1, 0x3000
	s_nop 0
	global_load_lds_dwordx4 v112, s[22:23]
	s_add_u32 s22, s22, 0x1e800
	s_addc_u32 s23, s23, 0
	s_add_u32 m0, s1, 0x3400
	s_nop 0
	global_load_lds_dwordx4 v113, s[22:23]
	s_add_u32 s22, s22, 0x1e800
	s_addc_u32 s23, s23, 0
	s_add_u32 m0, s1, 0x3800
	s_nop 0
	global_load_lds_dwordx4 v112, s[22:23]
	s_add_u32 s22, s22, 0x1e800
	s_addc_u32 s23, s23, 0
	s_add_u32 m0, s1, 0x3c00
	s_nop 0
	global_load_lds_dwordx4 v113, s[22:23]
	s_add_u32 s22, s22, 0x1e800
	s_addc_u32 s23, s23, 0
	s_waitcnt vmcnt(8)
	s_branch .Lix_r0

; #define MFMA(a, b, c) __builtin_amdgcn_mfma_f32_32x32x16_bf16((a), (b), (c), 0, 0, 0)
; DI void indexer_phase(const u16* __restrict__ P, unsigned* __restrict__ mask) {
;     ...
;         const u16* kp = P + (brow + 32 * kb + r32) * 7808 + 3584 + 8 * hi;
; #pragma unroll
;         for (int s = 0; s < 4; ++s) { const bf16x8 bk = *(const bf16x8*)(kp + 16 * s); a = MFMA(aq[s], bk, a); }
.Lix_r0:
	s_cmp_lt_u32 s0, 32
	s_cbranch_scc1 .Lix_n0
	ds_read_b128 v[80:83], v114 offset:4096
	ds_read_b128 v[84:87], v115 offset:4096
	ds_read_b128 v[88:91], v116 offset:4096
	ds_read_b128 v[92:95], v117 offset:4096
	s_waitcnt lgkmcnt(4)
	s_branch .Lix_m0

; #define MFMA(a, b, c) __builtin_amdgcn_mfma_f32_32x32x16_bf16((a), (b), (c), 0, 0, 0)
; DI unsigned ordkey(float f) { const unsigned b = __float_as_uint(f); return b ^ ((unsigned)((int)b >> 31) | 0x80000000u); }
; DI void indexer_phase(const u16* __restrict__ P, unsigned* __restrict__ mask) {
;     ...
;     for (int kb = 0; kb < 64; ++kb) {
;       unsigned u = 0u;
;       if (kb <= kbmax) {
;         f32x16 a;
; #pragma unroll
;         for (int r = 0; r < 16; ++r) a[r] = 0.f;
;         const u16* kp = P + (brow + 32 * kb + r32) * 7808 + 3584 + 8 * hi;
; #pragma unroll
;         for (int s = 0; s < 4; ++s) { const bf16x8 bk = *(const bf16x8*)(kp + 16 * s); a = MFMA(aq[s], bk, a); }
;         float v = 0.f;
; #pragma unroll
;         for (int i = 0; i < 16; ++i) v = fmaf(wv[i], fmaxf(a[i], 0.f), v);
;         u = (32 * kb + r32 <= tme) ? ordkey(v) : 0u;
;       }
;       sc[kb] = u;
.Lix_m0:
	v_cmp_le_i32_e32 vcc, 0, v16
	v_mfma_f32_32x32x16_bf16 v[18:33], v[46:49], v[64:67], 0
	v_mfma_f32_32x32x16_bf16 v[18:33], v[42:45], v[68:71], v[18:33]
	v_mfma_f32_32x32x16_bf16 v[18:33], v[38:41], v[72:75], v[18:33]
	v_mfma_f32_32x32x16_bf16 v[18:33], v[34:37], v[76:79], v[18:33]
	s_nop 11
	v_max_f32_e32 v18, 0, v18
	v_max_f32_e32 v19, 0, v19
	v_fma_f32 v18, v143, v18, 0
	v_fmac_f32_e32 v18, v142, v19
	v_max_f32_e32 v19, 0, v20
	v_fmac_f32_e32 v18, v141, v19
	v_max_f32_e32 v19, 0, v21
	v_fmac_f32_e32 v18, v140, v19
	v_max_f32_e32 v19, 0, v22
	v_fmac_f32_e32 v18, v139, v19
	v_max_f32_e32 v19, 0, v23
	v_fmac_f32_e32 v18, v138, v19
	v_max_f32_e32 v19, 0, v24
	v_fmac_f32_e32 v18, v137, v19
	v_max_f32_e32 v19, 0, v25
	v_fmac_f32_e32 v18, v136, v19
	v_max_f32_e32 v19, 0, v26
	v_fmac_f32_e32 v18, v135, v19
	v_max_f32_e32 v19, 0, v27
	v_fmac_f32_e32 v18, v134, v19
	v_max_f32_e32 v19, 0, v28
	v_fmac_f32_e32 v18, v133, v19
	v_max_f32_e32 v19, 0, v29
	v_fmac_f32_e32 v18, v132, v19
	v_max_f32_e32 v19, 0, v30
	v_fmac_f32_e32 v18, v131, v19
	v_max_f32_e32 v19, 0, v31
	v_fmac_f32_e32 v18, v130, v19
	v_max_f32_e32 v19, 0, v32
	v_fmac_f32_e32 v18, v129, v19
	v_max_f32_e32 v19, 0, v33
	v_fmac_f32_e32 v18, v128, v19
	v_ashrrev_i32_e32 v19, 31, v18
	v_bitop3_b32 v18, v19, v18, s8 bitop3:0x36
	v_cndmask_b32_e32 v2, 0, v18, vcc
	s_cmp_lt_u32 s0, 32
	s_cbranch_scc1 .Lix_z1
.Lix_b1:
	s_cmp_lt_u32 s0, 0x80
	s_cbranch_scc1 .Lix_w1
	s_add_u32 m0, s1, 0
	s_nop 0
	global_load_lds_dwordx4 v112, s[22:23]
	s_add_u32 s22, s22, 0x1e800
	s_addc_u32 s23, s23, 0
	s_add_u32 m0, s1, 0x400
	s_nop 0
	global_load_lds_dwordx4 v113, s[22:23]
	s_add_u32 s22, s22, 0x1e800
	s_addc_u32 s23, s23, 0
	s_add_u32 m0, s1, 0x800
	s_nop 0
	global_load_lds_dwordx4 v112, s[22:23]
	s_add_u32 s22, s22, 0x1e800
	s_addc_u32 s23, s23, 0
	s_add_u32 m0, s1, 0xc00
	s_nop 0
	global_load_lds_dwordx4 v113, s[22:23]
	s_add_u32 s22, s22, 0x1e800
	s_addc_u32 s23, s23, 0
	s_waitcnt vmcnt(8)
	s_branch .Lix_r1

; #define MFMA(a, b, c) __builtin_amdgcn_mfma_f32_32x32x16_bf16((a), (b), (c), 0, 0, 0)
; DI void indexer_phase(const u16* __restrict__ P, unsigned* __restrict__ mask) {
;     ...
;         const u16* kp = P + (brow + 32 * kb + r32) * 7808 + 3584 + 8 * hi;
; #pragma unroll
;         for (int s = 0; s < 4; ++s) { const bf16x8 bk = *(const bf16x8*)(kp + 16 * s); a = MFMA(aq[s], bk, a); }
.Lix_r1:
	s_cmp_lt_u32 s0, 64
	s_cbranch_scc1 .Lix_n1
	ds_read_b128 v[64:67], v114 offset:8192
	ds_read_b128 v[68:71], v115 offset:8192
	ds_read_b128 v[72:75], v116 offset:8192
	ds_read_b128 v[76:79], v117 offset:8192
	s_waitcnt lgkmcnt(4)
	s_branch .Lix_m1

; #define MFMA(a, b, c) __builtin_amdgcn_mfma_f32_32x32x16_bf16((a), (b), (c), 0, 0, 0)
; DI unsigned ordkey(float f) { const unsigned b = __float_as_uint(f); return b ^ ((unsigned)((int)b >> 31) | 0x80000000u); }
; DI void indexer_phase(const u16* __restrict__ P, unsigned* __restrict__ mask) {
;     ...
;     for (int kb = 0; kb < 64; ++kb) {
;       unsigned u = 0u;
;       if (kb <= kbmax) {
;         f32x16 a;
; #pragma unroll
;         for (int r = 0; r < 16; ++r) a[r] = 0.f;
;         const u16* kp = P + (brow + 32 * kb + r32) * 7808 + 3584 + 8 * hi;
; #pragma unroll
;         for (int s = 0; s < 4; ++s) { const bf16x8 bk = *(const bf16x8*)(kp + 16 * s); a = MFMA(aq[s], bk, a); }
;         float v = 0.f;
; #pragma unroll
;         for (int i = 0; i < 16; ++i) v = fmaf(wv[i], fmaxf(a[i], 0.f), v);
;         u = (32 * kb + r32 <= tme) ? ordkey(v) : 0u;
;       }
;       sc[kb] = u;
.Lix_m1:
	v_cmp_le_i32_e32 vcc, 32, v16
	v_mfma_f32_32x32x16_bf16 v[18:33], v[46:49], v[80:83], 0
	v_mfma_f32_32x32x16_bf16 v[18:33], v[42:45], v[84:87], v[18:33]
	v_mfma_f32_32x32x16_bf16 v[18:33], v[38:41], v[88:91], v[18:33]
	v_mfma_f32_32x32x16_bf16 v[18:33], v[34:37], v[92:95], v[18:33]
	s_nop 11
	v_max_f32_e32 v18, 0, v18
	v_max_f32_e32 v19, 0, v19
	v_fma_f32 v18, v143, v18, 0
	v_fmac_f32_e32 v18, v142, v19
	v_max_f32_e32 v19, 0, v20
	v_fmac_f32_e32 v18, v141, v19
	v_max_f32_e32 v19, 0, v21
	v_fmac_f32_e32 v18, v140, v19
	v_max_f32_e32 v19, 0, v22
	v_fmac_f32_e32 v18, v139, v19
	v_max_f32_e32 v19, 0, v23
	v_fmac_f32_e32 v18, v138, v19
	v_max_f32_e32 v19, 0, v24
	v_fmac_f32_e32 v18, v137, v19
	v_max_f32_e32 v19, 0, v25
	v_fmac_f32_e32 v18, v136, v19
	v_max_f32_e32 v19, 0, v26
	v_fmac_f32_e32 v18, v135, v19
	v_max_f32_e32 v19, 0, v27
	v_fmac_f32_e32 v18, v134, v19
	v_max_f32_e32 v19, 0, v28
	v_fmac_f32_e32 v18, v133, v19
	v_max_f32_e32 v19, 0, v29
	v_fmac_f32_e32 v18, v132, v19
	v_max_f32_e32 v19, 0, v30
	v_fmac_f32_e32 v18, v131, v19
	v_max_f32_e32 v19, 0, v31
	v_fmac_f32_e32 v18, v130, v19
	v_max_f32_e32 v19, 0, v32
	v_fmac_f32_e32 v18, v129, v19
	v_max_f32_e32 v19, 0, v33
	v_fmac_f32_e32 v18, v128, v19
	v_ashrrev_i32_e32 v19, 31, v18
	v_bitop3_b32 v18, v19, v18, s8 bitop3:0x36
	v_cndmask_b32_e32 v146, 0, v18, vcc
	s_cmp_lt_u32 s0, 64
	s_cbranch_scc1 .Lix_z2
.Lix_b2:
	s_cmp_lt_u32 s0, 0xa0
	s_cbranch_scc1 .Lix_w2
	s_add_u32 m0, s1, 0x1000
	s_nop 0
	global_load_lds_dwordx4 v112, s[22:23]
	s_add_u32 s22, s22, 0x1e800
	s_addc_u32 s23, s23, 0
	s_add_u32 m0, s1, 0x1400
	s_nop 0
	global_load_lds_dwordx4 v113, s[22:23]
	s_add_u32 s22, s22, 0x1e800
	s_addc_u32 s23, s23, 0
	s_add_u32 m0, s1, 0x1800
	s_nop 0
	global_load_lds_dwordx4 v112, s[22:23]
	s_add_u32 s22, s22, 0x1e800
	s_addc_u32 s23, s23, 0
	s_add_u32 m0, s1, 0x1c00
	s_nop 0
	global_load_lds_dwordx4 v113, s[22:23]
	s_add_u32 s22, s22, 0x1e800
	s_addc_u32 s23, s23, 0
	s_waitcnt vmcnt(8)
	s_branch .Lix_r2

; #define MFMA(a, b, c) __builtin_amdgcn_mfma_f32_32x32x16_bf16((a), (b), (c), 0, 0, 0)
; DI void indexer_phase(const u16* __restrict__ P, unsigned* __restrict__ mask) {
;     ...
;         const u16* kp = P + (brow + 32 * kb + r32) * 7808 + 3584 + 8 * hi;
; #pragma unroll
;         for (int s = 0; s < 4; ++s) { const bf16x8 bk = *(const bf16x8*)(kp + 16 * s); a = MFMA(aq[s], bk, a); }
.Lix_r2:
	s_cmp_lt_u32 s0, 0x60
	s_cbranch_scc1 .Lix_n2
	ds_read_b128 v[80:83], v114 offset:12288
	ds_read_b128 v[84:87], v115 offset:12288
	ds_read_b128 v[88:91], v116 offset:12288
	ds_read_b128 v[92:95], v117 offset:12288
	s_waitcnt lgkmcnt(4)
	s_branch .Lix_m2

; #define MFMA(a, b, c) __builtin_amdgcn_mfma_f32_32x32x16_bf16((a), (b), (c), 0, 0, 0)
; DI unsigned ordkey(float f) { const unsigned b = __float_as_uint(f); return b ^ ((unsigned)((int)b >> 31) | 0x80000000u); }
; DI void indexer_phase(const u16* __restrict__ P, unsigned* __restrict__ mask) {
;     ...
;     for (int kb = 0; kb < 64; ++kb) {
;       unsigned u = 0u;
;       if (kb <= kbmax) {
;         f32x16 a;
; #pragma unroll
;         for (int r = 0; r < 16; ++r) a[r] = 0.f;
;         const u16* kp = P + (brow + 32 * kb + r32) * 7808 + 3584 + 8 * hi;
; #pragma unroll
;         for (int s = 0; s < 4; ++s) { const bf16x8 bk = *(const bf16x8*)(kp + 16 * s); a = MFMA(aq[s], bk, a); }
;         float v = 0.f;
; #pragma unroll
;         for (int i = 0; i < 16; ++i) v = fmaf(wv[i], fmaxf(a[i], 0.f), v);
;         u = (32 * kb + r32 <= tme) ? ordkey(v) : 0u;
;       }
;       sc[kb] = u;
.Lix_m2:
	v_cmp_le_i32_e32 vcc, 64, v16
	v_mfma_f32_32x32x16_bf16 v[18:33], v[46:49], v[64:67], 0
	v_mfma_f32_32x32x16_bf16 v[18:33], v[42:45], v[68:71], v[18:33]
	v_mfma_f32_32x32x16_bf16 v[18:33], v[38:41], v[72:75], v[18:33]
	v_mfma_f32_32x32x16_bf16 v[18:33], v[34:37], v[76:79], v[18:33]
	s_nop 11
	v_max_f32_e32 v18, 0, v18
	v_max_f32_e32 v19, 0, v19
	v_fma_f32 v18, v143, v18, 0
	v_fmac_f32_e32 v18, v142, v19
	v_max_f32_e32 v19, 0, v20
	v_fmac_f32_e32 v18, v141, v19
	v_max_f32_e32 v19, 0, v21
	v_fmac_f32_e32 v18, v140, v19
	v_max_f32_e32 v19, 0, v22
	v_fmac_f32_e32 v18, v139, v19
	v_max_f32_e32 v19, 0, v23
	v_fmac_f32_e32 v18, v138, v19
	v_max_f32_e32 v19, 0, v24
	v_fmac_f32_e32 v18, v137, v19
	v_max_f32_e32 v19, 0, v25
	v_fmac_f32_e32 v18, v136, v19
	v_max_f32_e32 v19, 0, v26
	v_fmac_f32_e32 v18, v135, v19
	v_max_f32_e32 v19, 0, v27
	v_fmac_f32_e32 v18, v134, v19
	v_max_f32_e32 v19, 0, v28
	v_fmac_f32_e32 v18, v133, v19
	v_max_f32_e32 v19, 0, v29
	v_fmac_f32_e32 v18, v132, v19
	v_max_f32_e32 v19, 0, v30
	v_fmac_f32_e32 v18, v131, v19
	v_max_f32_e32 v19, 0, v31
	v_fmac_f32_e32 v18, v130, v19
	v_max_f32_e32 v19, 0, v32
	v_fmac_f32_e32 v18, v129, v19
	v_max_f32_e32 v19, 0, v33
	v_fmac_f32_e32 v18, v128, v19
	v_ashrrev_i32_e32 v19, 31, v18
	v_bitop3_b32 v18, v19, v18, s8 bitop3:0x36
	v_cndmask_b32_e32 v145, 0, v18, vcc
	s_cmp_lt_u32 s0, 0x60
	s_cbranch_scc1 .Lix_z3
.Lix_b3:
	s_cmp_lt_u32 s0, 0xc0
	s_cbranch_scc1 .Lix_w3
	s_add_u32 m0, s1, 0x2000
	s_nop 0
	global_load_lds_dwordx4 v112, s[22:23]
	s_add_u32 s22, s22, 0x1e800
	s_addc_u32 s23, s23, 0
	s_add_u32 m0, s1, 0x2400
	s_nop 0
	global_load_lds_dwordx4 v113, s[22:23]
	s_add_u32 s22, s22, 0x1e800
	s_addc_u32 s23, s23, 0
	s_add_u32 m0, s1, 0x2800
	s_nop 0
	global_load_lds_dwordx4 v112, s[22:23]
	s_add_u32 s22, s22, 0x1e800
	s_addc_u32 s23, s23, 0
	s_add_u32 m0, s1, 0x2c00
	s_nop 0
	global_load_lds_dwordx4 v113, s[22:23]
	s_add_u32 s22, s22, 0x1e800
	s_addc_u32 s23, s23, 0
	s_waitcnt vmcnt(8)
	s_branch .Lix_r3

; #define MFMA(a, b, c) __builtin_amdgcn_mfma_f32_32x32x16_bf16((a), (b), (c), 0, 0, 0)
; DI void indexer_phase(const u16* __restrict__ P, unsigned* __restrict__ mask) {
;     ...
;         const u16* kp = P + (brow + 32 * kb + r32) * 7808 + 3584 + 8 * hi;
; #pragma unroll
;         for (int s = 0; s < 4; ++s) { const bf16x8 bk = *(const bf16x8*)(kp + 16 * s); a = MFMA(aq[s], bk, a); }
.Lix_r3:
	s_cmp_lt_u32 s0, 0x80
	s_cbranch_scc1 .Lix_n3
	ds_read_b128 v[64:67], v114
	ds_read_b128 v[68:71], v115
	ds_read_b128 v[72:75], v116
	ds_read_b128 v[76:79], v117
	s_waitcnt lgkmcnt(4)
	s_branch .Lix_m3

; #define MFMA(a, b, c) __builtin_amdgcn_mfma_f32_32x32x16_bf16((a), (b), (c), 0, 0, 0)
; DI unsigned ordkey(float f) { const unsigned b = __float_as_uint(f); return b ^ ((unsigned)((int)b >> 31) | 0x80000000u); }
; DI void indexer_phase(const u16* __restrict__ P, unsigned* __restrict__ mask) {
;     ...
;     for (int kb = 0; kb < 64; ++kb) {
;       unsigned u = 0u;
;       if (kb <= kbmax) {
;         f32x16 a;
; #pragma unroll
;         for (int r = 0; r < 16; ++r) a[r] = 0.f;
;         const u16* kp = P + (brow + 32 * kb + r32) * 7808 + 3584 + 8 * hi;
; #pragma unroll
;         for (int s = 0; s < 4; ++s) { const bf16x8 bk = *(const bf16x8*)(kp + 16 * s); a = MFMA(aq[s], bk, a); }
;         float v = 0.f;
; #pragma unroll
;         for (int i = 0; i < 16; ++i) v = fmaf(wv[i], fmaxf(a[i], 0.f), v);
;         u = (32 * kb + r32 <= tme) ? ordkey(v) : 0u;
;       }
;       sc[kb] = u;
.Lix_m3:
	v_cmp_le_i32_e32 vcc, 0x60, v16
	v_mfma_f32_32x32x16_bf16 v[18:33], v[46:49], v[80:83], 0
	v_mfma_f32_32x32x16_bf16 v[18:33], v[42:45], v[84:87], v[18:33]
	v_mfma_f32_32x32x16_bf16 v[18:33], v[38:41], v[88:91], v[18:33]
	v_mfma_f32_32x32x16_bf16 v[18:33], v[34:37], v[92:95], v[18:33]
	s_nop 11
	v_max_f32_e32 v18, 0, v18
	v_max_f32_e32 v19, 0, v19
	v_fma_f32 v18, v143, v18, 0
	v_fmac_f32_e32 v18, v142, v19
	v_max_f32_e32 v19, 0, v20
	v_fmac_f32_e32 v18, v141, v19
	v_max_f32_e32 v19, 0, v21
	v_fmac_f32_e32 v18, v140, v19
	v_max_f32_e32 v19, 0, v22
	v_fmac_f32_e32 v18, v139, v19
	v_max_f32_e32 v19, 0, v23
	v_fmac_f32_e32 v18, v138, v19
	v_max_f32_e32 v19, 0, v24
	v_fmac_f32_e32 v18, v137, v19
	v_max_f32_e32 v19, 0, v25
	v_fmac_f32_e32 v18, v136, v19
	v_max_f32_e32 v19, 0, v26
	v_fmac_f32_e32 v18, v135, v19
	v_max_f32_e32 v19, 0, v27
	v_fmac_f32_e32 v18, v134, v19
	v_max_f32_e32 v19, 0, v28
	v_fmac_f32_e32 v18, v133, v19
	v_max_f32_e32 v19, 0, v29
	v_fmac_f32_e32 v18, v132, v19
	v_max_f32_e32 v19, 0, v30
	v_fmac_f32_e32 v18, v131, v19
	v_max_f32_e32 v19, 0, v31
	v_fmac_f32_e32 v18, v130, v19
	v_max_f32_e32 v19, 0, v32
	v_fmac_f32_e32 v18, v129, v19
	v_max_f32_e32 v19, 0, v33
	v_fmac_f32_e32 v18, v128, v19
	v_ashrrev_i32_e32 v19, 31, v18
	v_bitop3_b32 v18, v19, v18, s8 bitop3:0x36
	v_cndmask_b32_e32 v148, 0, v18, vcc
	s_cmp_lt_u32 s0, 0x80
	s_cbranch_scc1 .Lix_z4
.Lix_b4:
	s_cmp_lt_u32 s0, 0xe0
	s_cbranch_scc1 .Lix_w4
	s_add_u32 m0, s1, 0x3000
	s_nop 0
	global_load_lds_dwordx4 v112, s[22:23]
	s_add_u32 s22, s22, 0x1e800
	s_addc_u32 s23, s23, 0
	s_add_u32 m0, s1, 0x3400
	s_nop 0
	global_load_lds_dwordx4 v113, s[22:23]
	s_add_u32 s22, s22, 0x1e800
	s_addc_u32 s23, s23, 0
	s_add_u32 m0, s1, 0x3800
	s_nop 0
	global_load_lds_dwordx4 v112, s[22:23]
	s_add_u32 s22, s22, 0x1e800
	s_addc_u32 s23, s23, 0
	s_add_u32 m0, s1, 0x3c00
	s_nop 0
	global_load_lds_dwordx4 v113, s[22:23]
	s_add_u32 s22, s22, 0x1e800
	s_addc_u32 s23, s23, 0
	s_waitcnt vmcnt(8)
	s_branch .Lix_r4

; #define MFMA(a, b, c) __builtin_amdgcn_mfma_f32_32x32x16_bf16((a), (b), (c), 0, 0, 0)
; DI void indexer_phase(const u16* __restrict__ P, unsigned* __restrict__ mask) {
;     ...
;         const u16* kp = P + (brow + 32 * kb + r32) * 7808 + 3584 + 8 * hi;
; #pragma unroll
;         for (int s = 0; s < 4; ++s) { const bf16x8 bk = *(const bf16x8*)(kp + 16 * s); a = MFMA(aq[s], bk, a); }
.Lix_r4:
	s_cmp_lt_u32 s0, 0xa0
	s_cbranch_scc1 .Lix_n4
	ds_read_b128 v[80:83], v114 offset:4096
	ds_read_b128 v[84:87], v115 offset:4096
	ds_read_b128 v[88:91], v116 offset:4096
	ds_read_b128 v[92:95], v117 offset:4096
	s_waitcnt lgkmcnt(4)
	s_branch .Lix_m4

; #define MFMA(a, b, c) __builtin_amdgcn_mfma_f32_32x32x16_bf16((a), (b), (c), 0, 0, 0)
; DI unsigned ordkey(float f) { const unsigned b = __float_as_uint(f); return b ^ ((unsigned)((int)b >> 31) | 0x80000000u); }
; DI void indexer_phase(const u16* __restrict__ P, unsigned* __restrict__ mask) {
;     ...
;     for (int kb = 0; kb < 64; ++kb) {
;       unsigned u = 0u;
;       if (kb <= kbmax) {
;         f32x16 a;
; #pragma unroll
;         for (int r = 0; r < 16; ++r) a[r] = 0.f;
;         const u16* kp = P + (brow + 32 * kb + r32) * 7808 + 3584 + 8 * hi;
; #pragma unroll
;         for (int s = 0; s < 4; ++s) { const bf16x8 bk = *(const bf16x8*)(kp + 16 * s); a = MFMA(aq[s], bk, a); }
;         float v = 0.f;
; #pragma unroll
;         for (int i = 0; i < 16; ++i) v = fmaf(wv[i], fmaxf(a[i], 0.f), v);
;         u = (32 * kb + r32 <= tme) ? ordkey(v) : 0u;
;       }
;       sc[kb] = u;
.Lix_m4:
	v_cmp_le_i32_e32 vcc, 0x80, v16
	v_mfma_f32_32x32x16_bf16 v[18:33], v[46:49], v[64:67], 0
	v_mfma_f32_32x32x16_bf16 v[18:33], v[42:45], v[68:71], v[18:33]
	v_mfma_f32_32x32x16_bf16 v[18:33], v[38:41], v[72:75], v[18:33]
	v_mfma_f32_32x32x16_bf16 v[18:33], v[34:37], v[76:79], v[18:33]
	s_nop 11
	v_max_f32_e32 v18, 0, v18
	v_max_f32_e32 v19, 0, v19
	v_fma_f32 v18, v143, v18, 0
	v_fmac_f32_e32 v18, v142, v19
	v_max_f32_e32 v19, 0, v20
	v_fmac_f32_e32 v18, v141, v19
	v_max_f32_e32 v19, 0, v21
	v_fmac_f32_e32 v18, v140, v19
	v_max_f32_e32 v19, 0, v22
	v_fmac_f32_e32 v18, v139, v19
	v_max_f32_e32 v19, 0, v23
	v_fmac_f32_e32 v18, v138, v19
	v_max_f32_e32 v19, 0, v24
	v_fmac_f32_e32 v18, v137, v19
	v_max_f32_e32 v19, 0, v25
	v_fmac_f32_e32 v18, v136, v19
	v_max_f32_e32 v19, 0, v26
	v_fmac_f32_e32 v18, v135, v19
	v_max_f32_e32 v19, 0, v27
	v_fmac_f32_e32 v18, v134, v19
	v_max_f32_e32 v19, 0, v28
	v_fmac_f32_e32 v18, v133, v19
	v_max_f32_e32 v19, 0, v29
	v_fmac_f32_e32 v18, v132, v19
	v_max_f32_e32 v19, 0, v30
	v_fmac_f32_e32 v18, v131, v19
	v_max_f32_e32 v19, 0, v31
	v_fmac_f32_e32 v18, v130, v19
	v_max_f32_e32 v19, 0, v32
	v_fmac_f32_e32 v18, v129, v19
	v_max_f32_e32 v19, 0, v33
	v_fmac_f32_e32 v18, v128, v19
	v_ashrrev_i32_e32 v19, 31, v18
	v_bitop3_b32 v18, v19, v18, s8 bitop3:0x36
	v_cndmask_b32_e32 v147, 0, v18, vcc
	s_cmp_lt_u32 s0, 0xa0
	s_cbranch_scc1 .Lix_z5
.Lix_b5:
	s_cmp_lt_u32 s0, 0x100
	s_cbranch_scc1 .Lix_w5
	s_add_u32 m0, s1, 0
	s_nop 0
	global_load_lds_dwordx4 v112, s[22:23]
	s_add_u32 s22, s22, 0x1e800
	s_addc_u32 s23, s23, 0
	s_add_u32 m0, s1, 0x400
	s_nop 0
	global_load_lds_dwordx4 v113, s[22:23]
	s_add_u32 s22, s22, 0x1e800
	s_addc_u32 s23, s23, 0
	s_add_u32 m0, s1, 0x800
	s_nop 0
	global_load_lds_dwordx4 v112, s[22:23]
	s_add_u32 s22, s22, 0x1e800
	s_addc_u32 s23, s23, 0
	s_add_u32 m0, s1, 0xc00
	s_nop 0
	global_load_lds_dwordx4 v113, s[22:23]
	s_add_u32 s22, s22, 0x1e800
	s_addc_u32 s23, s23, 0
	s_waitcnt vmcnt(8)
	s_branch .Lix_r5

; #define MFMA(a, b, c) __builtin_amdgcn_mfma_f32_32x32x16_bf16((a), (b), (c), 0, 0, 0)
; DI void indexer_phase(const u16* __restrict__ P, unsigned* __restrict__ mask) {
;     ...
;         const u16* kp = P + (brow + 32 * kb + r32) * 7808 + 3584 + 8 * hi;
; #pragma unroll
;         for (int s = 0; s < 4; ++s) { const bf16x8 bk = *(const bf16x8*)(kp + 16 * s); a = MFMA(aq[s], bk, a); }
.Lix_r5:
	s_cmp_lt_u32 s0, 0xc0
	s_cbranch_scc1 .Lix_n5
	ds_read_b128 v[64:67], v114 offset:8192
	ds_read_b128 v[68:71], v115 offset:8192
	ds_read_b128 v[72:75], v116 offset:8192
	ds_read_b128 v[76:79], v117 offset:8192
	s_waitcnt lgkmcnt(4)
	s_branch .Lix_m5

; #define MFMA(a, b, c) __builtin_amdgcn_mfma_f32_32x32x16_bf16((a), (b), (c), 0, 0, 0)
; DI unsigned ordkey(float f) { const unsigned b = __float_as_uint(f); return b ^ ((unsigned)((int)b >> 31) | 0x80000000u); }
; DI void indexer_phase(const u16* __restrict__ P, unsigned* __restrict__ mask) {
;     ...
;     for (int kb = 0; kb < 64; ++kb) {
;       unsigned u = 0u;
;       if (kb <= kbmax) {
;         f32x16 a;
; #pragma unroll
;         for (int r = 0; r < 16; ++r) a[r] = 0.f;
;         const u16* kp = P + (brow + 32 * kb + r32) * 7808 + 3584 + 8 * hi;
; #pragma unroll
;         for (int s = 0; s < 4; ++s) { const bf16x8 bk = *(const bf16x8*)(kp + 16 * s); a = MFMA(aq[s], bk, a); }
;         float v = 0.f;
; #pragma unroll
;         for (int i = 0; i < 16; ++i) v = fmaf(wv[i], fmaxf(a[i], 0.f), v);
;         u = (32 * kb + r32 <= tme) ? ordkey(v) : 0u;
;       }
;       sc[kb] = u;
.Lix_m5:
	v_cmp_le_i32_e32 vcc, 0xa0, v16
	v_mfma_f32_32x32x16_bf16 v[18:33], v[46:49], v[80:83], 0
	v_mfma_f32_32x32x16_bf16 v[18:33], v[42:45], v[84:87], v[18:33]
	v_mfma_f32_32x32x16_bf16 v[18:33], v[38:41], v[88:91], v[18:33]
	v_mfma_f32_32x32x16_bf16 v[18:33], v[34:37], v[92:95], v[18:33]
	s_nop 11
	v_max_f32_e32 v18, 0, v18
	v_max_f32_e32 v19, 0, v19
	v_fma_f32 v18, v143, v18, 0
	v_fmac_f32_e32 v18, v142, v19
	v_max_f32_e32 v19, 0, v20
	v_fmac_f32_e32 v18, v141, v19
	v_max_f32_e32 v19, 0, v21
	v_fmac_f32_e32 v18, v140, v19
	v_max_f32_e32 v19, 0, v22
	v_fmac_f32_e32 v18, v139, v19
	v_max_f32_e32 v19, 0, v23
	v_fmac_f32_e32 v18, v138, v19
	v_max_f32_e32 v19, 0, v24
	v_fmac_f32_e32 v18, v137, v19
	v_max_f32_e32 v19, 0, v25
	v_fmac_f32_e32 v18, v136, v19
	v_max_f32_e32 v19, 0, v26
	v_fmac_f32_e32 v18, v135, v19
	v_max_f32_e32 v19, 0, v27
	v_fmac_f32_e32 v18, v134, v19
	v_max_f32_e32 v19, 0, v28
	v_fmac_f32_e32 v18, v133, v19
	v_max_f32_e32 v19, 0, v29
	v_fmac_f32_e32 v18, v132, v19
	v_max_f32_e32 v19, 0, v30
	v_fmac_f32_e32 v18, v131, v19
	v_max_f32_e32 v19, 0, v31
	v_fmac_f32_e32 v18, v130, v19
	v_max_f32_e32 v19, 0, v32
	v_fmac_f32_e32 v18, v129, v19
	v_max_f32_e32 v19, 0, v33
	v_fmac_f32_e32 v18, v128, v19
	v_ashrrev_i32_e32 v19, 31, v18
	v_bitop3_b32 v18, v19, v18, s8 bitop3:0x36
	v_cndmask_b32_e32 v150, 0, v18, vcc
	s_cmp_lt_u32 s0, 0xc0
	s_cbranch_scc1 .Lix_z6
.Lix_b6:
	s_cmp_lt_u32 s0, 0x120
	s_cbranch_scc1 .Lix_w6
	s_add_u32 m0, s1, 0x1000
	s_nop 0
	global_load_lds_dwordx4 v112, s[22:23]
	s_add_u32 s22, s22, 0x1e800
	s_addc_u32 s23, s23, 0
	s_add_u32 m0, s1, 0x1400
	s_nop 0
	global_load_lds_dwordx4 v113, s[22:23]
	s_add_u32 s22, s22, 0x1e800
	s_addc_u32 s23, s23, 0
	s_add_u32 m0, s1, 0x1800
	s_nop 0
	global_load_lds_dwordx4 v112, s[22:23]
	s_add_u32 s22, s22, 0x1e800
	s_addc_u32 s23, s23, 0
	s_add_u32 m0, s1, 0x1c00
	s_nop 0
	global_load_lds_dwordx4 v113, s[22:23]
	s_add_u32 s22, s22, 0x1e800
	s_addc_u32 s23, s23, 0
	s_waitcnt vmcnt(8)
	s_branch .Lix_r6

; #define MFMA(a, b, c) __builtin_amdgcn_mfma_f32_32x32x16_bf16((a), (b), (c), 0, 0, 0)
; DI void indexer_phase(const u16* __restrict__ P, unsigned* __restrict__ mask) {
;     ...
;         const u16* kp = P + (brow + 32 * kb + r32) * 7808 + 3584 + 8 * hi;
; #pragma unroll
;         for (int s = 0; s < 4; ++s) { const bf16x8 bk = *(const bf16x8*)(kp + 16 * s); a = MFMA(aq[s], bk, a); }
.Lix_r6:
	s_cmp_lt_u32 s0, 0xe0
	s_cbranch_scc1 .Lix_n6
	ds_read_b128 v[80:83], v114 offset:12288
	ds_read_b128 v[84:87], v115 offset:12288
	ds_read_b128 v[88:91], v116 offset:12288
	ds_read_b128 v[92:95], v117 offset:12288
	s_waitcnt lgkmcnt(4)
	s_branch .Lix_m6

; #define MFMA(a, b, c) __builtin_amdgcn_mfma_f32_32x32x16_bf16((a), (b), (c), 0, 0, 0)
; DI unsigned ordkey(float f) { const unsigned b = __float_as_uint(f); return b ^ ((unsigned)((int)b >> 31) | 0x80000000u); }
; DI void indexer_phase(const u16* __restrict__ P, unsigned* __restrict__ mask) {
;     ...
;     for (int kb = 0; kb < 64; ++kb) {
;       unsigned u = 0u;
;       if (kb <= kbmax) {
;         f32x16 a;
; #pragma unroll
;         for (int r = 0; r < 16; ++r) a[r] = 0.f;
;         const u16* kp = P + (brow + 32 * kb + r32) * 7808 + 3584 + 8 * hi;
; #pragma unroll
;         for (int s = 0; s < 4; ++s) { const bf16x8 bk = *(const bf16x8*)(kp + 16 * s); a = MFMA(aq[s], bk, a); }
;         float v = 0.f;
; #pragma unroll
;         for (int i = 0; i < 16; ++i) v = fmaf(wv[i], fmaxf(a[i], 0.f), v);
;         u = (32 * kb + r32 <= tme) ? ordkey(v) : 0u;
;       }
;       sc[kb] = u;
.Lix_m6:
	v_cmp_le_i32_e32 vcc, 0xc0, v16
	v_mfma_f32_32x32x16_bf16 v[18:33], v[46:49], v[64:67], 0
	v_mfma_f32_32x32x16_bf16 v[18:33], v[42:45], v[68:71], v[18:33]
	v_mfma_f32_32x32x16_bf16 v[18:33], v[38:41], v[72:75], v[18:33]
	v_mfma_f32_32x32x16_bf16 v[18:33], v[34:37], v[76:79], v[18:33]
	s_nop 11
	v_max_f32_e32 v18, 0, v18
	v_max_f32_e32 v19, 0, v19
	v_fma_f32 v18, v143, v18, 0
	v_fmac_f32_e32 v18, v142, v19
	v_max_f32_e32 v19, 0, v20
	v_fmac_f32_e32 v18, v141, v19
	v_max_f32_e32 v19, 0, v21
	v_fmac_f32_e32 v18, v140, v19
	v_max_f32_e32 v19, 0, v22
	v_fmac_f32_e32 v18, v139, v19
	v_max_f32_e32 v19, 0, v23
	v_fmac_f32_e32 v18, v138, v19
	v_max_f32_e32 v19, 0, v24
	v_fmac_f32_e32 v18, v137, v19
	v_max_f32_e32 v19, 0, v25
	v_fmac_f32_e32 v18, v136, v19
	v_max_f32_e32 v19, 0, v26
	v_fmac_f32_e32 v18, v135, v19
	v_max_f32_e32 v19, 0, v27
	v_fmac_f32_e32 v18, v134, v19
	v_max_f32_e32 v19, 0, v28
	v_fmac_f32_e32 v18, v133, v19
	v_max_f32_e32 v19, 0, v29
	v_fmac_f32_e32 v18, v132, v19
	v_max_f32_e32 v19, 0, v30
	v_fmac_f32_e32 v18, v131, v19
	v_max_f32_e32 v19, 0, v31
	v_fmac_f32_e32 v18, v130, v19
	v_max_f32_e32 v19, 0, v32
	v_fmac_f32_e32 v18, v129, v19
	v_max_f32_e32 v19, 0, v33
	v_fmac_f32_e32 v18, v128, v19
	v_ashrrev_i32_e32 v19, 31, v18
	v_bitop3_b32 v18, v19, v18, s8 bitop3:0x36
	v_cndmask_b32_e32 v149, 0, v18, vcc
	s_cmp_lt_u32 s0, 0xe0
	s_cbranch_scc1 .Lix_z7
.Lix_b7:
	s_cmp_lt_u32 s0, 0x140
	s_cbranch_scc1 .Lix_w7
	s_add_u32 m0, s1, 0x2000
	s_nop 0
	global_load_lds_dwordx4 v112, s[22:23]
	s_add_u32 s22, s22, 0x1e800
	s_addc_u32 s23, s23, 0
	s_add_u32 m0, s1, 0x2400
	s_nop 0
	global_load_lds_dwordx4 v113, s[22:23]
	s_add_u32 s22, s22, 0x1e800
	s_addc_u32 s23, s23, 0
	s_add_u32 m0, s1, 0x2800
	s_nop 0
	global_load_lds_dwordx4 v112, s[22:23]
	s_add_u32 s22, s22, 0x1e800
	s_addc_u32 s23, s23, 0
	s_add_u32 m0, s1, 0x2c00
	s_nop 0
	global_load_lds_dwordx4 v113, s[22:23]
	s_add_u32 s22, s22, 0x1e800
	s_addc_u32 s23, s23, 0
	s_waitcnt vmcnt(8)
	s_branch .Lix_r7

; #define MFMA(a, b, c) __builtin_amdgcn_mfma_f32_32x32x16_bf16((a), (b), (c), 0, 0, 0)
; DI void indexer_phase(const u16* __restrict__ P, unsigned* __restrict__ mask) {
;     ...
;         const u16* kp = P + (brow + 32 * kb + r32) * 7808 + 3584 + 8 * hi;
; #pragma unroll
;         for (int s = 0; s < 4; ++s) { const bf16x8 bk = *(const bf16x8*)(kp + 16 * s); a = MFMA(aq[s], bk, a); }
.Lix_r7:
	s_cmp_lt_u32 s0, 0x100
	s_cbranch_scc1 .Lix_n7
	ds_read_b128 v[64:67], v114
	ds_read_b128 v[68:71], v115
	ds_read_b128 v[72:75], v116
	ds_read_b128 v[76:79], v117
	s_waitcnt lgkmcnt(4)
	s_branch .Lix_m7

; #define MFMA(a, b, c) __builtin_amdgcn_mfma_f32_32x32x16_bf16((a), (b), (c), 0, 0, 0)
; DI unsigned ordkey(float f) { const unsigned b = __float_as_uint(f); return b ^ ((unsigned)((int)b >> 31) | 0x80000000u); }
; DI void indexer_phase(const u16* __restrict__ P, unsigned* __restrict__ mask) {
;     ...
;     for (int kb = 0; kb < 64; ++kb) {
;       unsigned u = 0u;
;       if (kb <= kbmax) {
;         f32x16 a;
; #pragma unroll
;         for (int r = 0; r < 16; ++r) a[r] = 0.f;
;         const u16* kp = P + (brow + 32 * kb + r32) * 7808 + 3584 + 8 * hi;
; #pragma unroll
;         for (int s = 0; s < 4; ++s) { const bf16x8 bk = *(const bf16x8*)(kp + 16 * s); a = MFMA(aq[s], bk, a); }
;         float v = 0.f;
; #pragma unroll
;         for (int i = 0; i < 16; ++i) v = fmaf(wv[i], fmaxf(a[i], 0.f), v);
;         u = (32 * kb + r32 <= tme) ? ordkey(v) : 0u;
;       }
;       sc[kb] = u;
.Lix_m7:
	v_cmp_le_i32_e32 vcc, 0xe0, v16
	v_mfma_f32_32x32x16_bf16 v[18:33], v[46:49], v[80:83], 0
	v_mfma_f32_32x32x16_bf16 v[18:33], v[42:45], v[84:87], v[18:33]
	v_mfma_f32_32x32x16_bf16 v[18:33], v[38:41], v[88:91], v[18:33]
	v_mfma_f32_32x32x16_bf16 v[18:33], v[34:37], v[92:95], v[18:33]
	s_nop 11
	v_max_f32_e32 v18, 0, v18
	v_max_f32_e32 v19, 0, v19
	v_fma_f32 v18, v143, v18, 0
	v_fmac_f32_e32 v18, v142, v19
	v_max_f32_e32 v19, 0, v20
	v_fmac_f32_e32 v18, v141, v19
	v_max_f32_e32 v19, 0, v21
	v_fmac_f32_e32 v18, v140, v19
	v_max_f32_e32 v19, 0, v22
	v_fmac_f32_e32 v18, v139, v19
	v_max_f32_e32 v19, 0, v23
	v_fmac_f32_e32 v18, v138, v19
	v_max_f32_e32 v19, 0, v24
	v_fmac_f32_e32 v18, v137, v19
	v_max_f32_e32 v19, 0, v25
	v_fmac_f32_e32 v18, v136, v19
	v_max_f32_e32 v19, 0, v26
	v_fmac_f32_e32 v18, v135, v19
	v_max_f32_e32 v19, 0, v27
	v_fmac_f32_e32 v18, v134, v19
	v_max_f32_e32 v19, 0, v28
	v_fmac_f32_e32 v18, v133, v19
	v_max_f32_e32 v19, 0, v29
	v_fmac_f32_e32 v18, v132, v19
	v_max_f32_e32 v19, 0, v30
	v_fmac_f32_e32 v18, v131, v19
	v_max_f32_e32 v19, 0, v31
	v_fmac_f32_e32 v18, v130, v19
	v_max_f32_e32 v19, 0, v32
	v_fmac_f32_e32 v18, v129, v19
	v_max_f32_e32 v19, 0, v33
	v_fmac_f32_e32 v18, v128, v19
	v_ashrrev_i32_e32 v19, 31, v18
	v_bitop3_b32 v18, v19, v18, s8 bitop3:0x36
	v_cndmask_b32_e32 v152, 0, v18, vcc
	s_cmp_lt_u32 s0, 0x100
	s_cbranch_scc1 .Lix_z8
.Lix_b8:
	s_cmp_lt_u32 s0, 0x160
	s_cbranch_scc1 .Lix_w8
	s_add_u32 m0, s1, 0x3000
	s_nop 0
	global_load_lds_dwordx4 v112, s[22:23]
	s_add_u32 s22, s22, 0x1e800
	s_addc_u32 s23, s23, 0
	s_add_u32 m0, s1, 0x3400
	s_nop 0
	global_load_lds_dwordx4 v113, s[22:23]
	s_add_u32 s22, s22, 0x1e800
	s_addc_u32 s23, s23, 0
	s_add_u32 m0, s1, 0x3800
	s_nop 0
	global_load_lds_dwordx4 v112, s[22:23]
	s_add_u32 s22, s22, 0x1e800
	s_addc_u32 s23, s23, 0
	s_add_u32 m0, s1, 0x3c00
	s_nop 0
	global_load_lds_dwordx4 v113, s[22:23]
	s_add_u32 s22, s22, 0x1e800
	s_addc_u32 s23, s23, 0
	s_waitcnt vmcnt(8)
	s_branch .Lix_r8

; #define MFMA(a, b, c) __builtin_amdgcn_mfma_f32_32x32x16_bf16((a), (b), (c), 0, 0, 0)
; DI void indexer_phase(const u16* __restrict__ P, unsigned* __restrict__ mask) {
;     ...
;         const u16* kp = P + (brow + 32 * kb + r32) * 7808 + 3584 + 8 * hi;
; #pragma unroll
;         for (int s = 0; s < 4; ++s) { const bf16x8 bk = *(const bf16x8*)(kp + 16 * s); a = MFMA(aq[s], bk, a); }
.Lix_r8:
	s_cmp_lt_u32 s0, 0x120
	s_cbranch_scc1 .Lix_n8
	ds_read_b128 v[80:83], v114 offset:4096
	ds_read_b128 v[84:87], v115 offset:4096
	ds_read_b128 v[88:91], v116 offset:4096
	ds_read_b128 v[92:95], v117 offset:4096
	s_waitcnt lgkmcnt(4)
	s_branch .Lix_m8

; #define MFMA(a, b, c) __builtin_amdgcn_mfma_f32_32x32x16_bf16((a), (b), (c), 0, 0, 0)
; DI unsigned ordkey(float f) { const unsigned b = __float_as_uint(f); return b ^ ((unsigned)((int)b >> 31) | 0x80000000u); }
; DI void indexer_phase(const u16* __restrict__ P, unsigned* __restrict__ mask) {
;     ...
;     for (int kb = 0; kb < 64; ++kb) {
;       unsigned u = 0u;
;       if (kb <= kbmax) {
;         f32x16 a;
; #pragma unroll
;         for (int r = 0; r < 16; ++r) a[r] = 0.f;
;         const u16* kp = P + (brow + 32 * kb + r32) * 7808 + 3584 + 8 * hi;
; #pragma unroll
;         for (int s = 0; s < 4; ++s) { const bf16x8 bk = *(const bf16x8*)(kp + 16 * s); a = MFMA(aq[s], bk, a); }
;         float v = 0.f;
; #pragma unroll
;         for (int i = 0; i < 16; ++i) v = fmaf(wv[i], fmaxf(a[i], 0.f), v);
;         u = (32 * kb + r32 <= tme) ? ordkey(v) : 0u;
;       }
;       sc[kb] = u;
.Lix_m8:
	v_cmp_le_i32_e32 vcc, 0x100, v16
	v_mfma_f32_32x32x16_bf16 v[18:33], v[46:49], v[64:67], 0
	v_mfma_f32_32x32x16_bf16 v[18:33], v[42:45], v[68:71], v[18:33]
	v_mfma_f32_32x32x16_bf16 v[18:33], v[38:41], v[72:75], v[18:33]
	v_mfma_f32_32x32x16_bf16 v[18:33], v[34:37], v[76:79], v[18:33]
	s_nop 11
	v_max_f32_e32 v18, 0, v18
	v_max_f32_e32 v19, 0, v19
	v_fma_f32 v18, v143, v18, 0
	v_fmac_f32_e32 v18, v142, v19
	v_max_f32_e32 v19, 0, v20
	v_fmac_f32_e32 v18, v141, v19
	v_max_f32_e32 v19, 0, v21
	v_fmac_f32_e32 v18, v140, v19
	v_max_f32_e32 v19, 0, v22
	v_fmac_f32_e32 v18, v139, v19
	v_max_f32_e32 v19, 0, v23
	v_fmac_f32_e32 v18, v138, v19
	v_max_f32_e32 v19, 0, v24
	v_fmac_f32_e32 v18, v137, v19
	v_max_f32_e32 v19, 0, v25
	v_fmac_f32_e32 v18, v136, v19
	v_max_f32_e32 v19, 0, v26
	v_fmac_f32_e32 v18, v135, v19
	v_max_f32_e32 v19, 0, v27
	v_fmac_f32_e32 v18, v134, v19
	v_max_f32_e32 v19, 0, v28
	v_fmac_f32_e32 v18, v133, v19
	v_max_f32_e32 v19, 0, v29
	v_fmac_f32_e32 v18, v132, v19
	v_max_f32_e32 v19, 0, v30
	v_fmac_f32_e32 v18, v131, v19
	v_max_f32_e32 v19, 0, v31
	v_fmac_f32_e32 v18, v130, v19
	v_max_f32_e32 v19, 0, v32
	v_fmac_f32_e32 v18, v129, v19
	v_max_f32_e32 v19, 0, v33
	v_fmac_f32_e32 v18, v128, v19
	v_ashrrev_i32_e32 v19, 31, v18
	v_bitop3_b32 v18, v19, v18, s8 bitop3:0x36
	v_cndmask_b32_e32 v151, 0, v18, vcc
	s_cmp_lt_u32 s0, 0x120
	s_cbranch_scc1 .Lix_z9
.Lix_b9:
	s_cmp_lt_u32 s0, 0x180
	s_cbranch_scc1 .Lix_w9
	s_add_u32 m0, s1, 0
	s_nop 0
	global_load_lds_dwordx4 v112, s[22:23]
	s_add_u32 s22, s22, 0x1e800
	s_addc_u32 s23, s23, 0
	s_add_u32 m0, s1, 0x400
	s_nop 0
	global_load_lds_dwordx4 v113, s[22:23]
	s_add_u32 s22, s22, 0x1e800
	s_addc_u32 s23, s23, 0
	s_add_u32 m0, s1, 0x800
	s_nop 0
	global_load_lds_dwordx4 v112, s[22:23]
	s_add_u32 s22, s22, 0x1e800
	s_addc_u32 s23, s23, 0
	s_add_u32 m0, s1, 0xc00
	s_nop 0
	global_load_lds_dwordx4 v113, s[22:23]
	s_add_u32 s22, s22, 0x1e800
	s_addc_u32 s23, s23, 0
	s_waitcnt vmcnt(8)
	s_branch .Lix_r9

; #define MFMA(a, b, c) __builtin_amdgcn_mfma_f32_32x32x16_bf16((a), (b), (c), 0, 0, 0)
; DI void indexer_phase(const u16* __restrict__ P, unsigned* __restrict__ mask) {
;     ...
;         const u16* kp = P + (brow + 32 * kb + r32) * 7808 + 3584 + 8 * hi;
; #pragma unroll
;         for (int s = 0; s < 4; ++s) { const bf16x8 bk = *(const bf16x8*)(kp + 16 * s); a = MFMA(aq[s], bk, a); }
.Lix_r9:
	s_cmp_lt_u32 s0, 0x140
	s_cbranch_scc1 .Lix_n9
	ds_read_b128 v[64:67], v114 offset:8192
	ds_read_b128 v[68:71], v115 offset:8192
	ds_read_b128 v[72:75], v116 offset:8192
	ds_read_b128 v[76:79], v117 offset:8192
	s_waitcnt lgkmcnt(4)
	s_branch .Lix_m9

; #define MFMA(a, b, c) __builtin_amdgcn_mfma_f32_32x32x16_bf16((a), (b), (c), 0, 0, 0)
; DI unsigned ordkey(float f) { const unsigned b = __float_as_uint(f); return b ^ ((unsigned)((int)b >> 31) | 0x80000000u); }
; DI void indexer_phase(const u16* __restrict__ P, unsigned* __restrict__ mask) {
;     ...
;     for (int kb = 0; kb < 64; ++kb) {
;       unsigned u = 0u;
;       if (kb <= kbmax) {
;         f32x16 a;
; #pragma unroll
;         for (int r = 0; r < 16; ++r) a[r] = 0.f;
;         const u16* kp = P + (brow + 32 * kb + r32) * 7808 + 3584 + 8 * hi;
; #pragma unroll
;         for (int s = 0; s < 4; ++s) { const bf16x8 bk = *(const bf16x8*)(kp + 16 * s); a = MFMA(aq[s], bk, a); }
;         float v = 0.f;
; #pragma unroll
;         for (int i = 0; i < 16; ++i) v = fmaf(wv[i], fmaxf(a[i], 0.f), v);
;         u = (32 * kb + r32 <= tme) ? ordkey(v) : 0u;
;       }
;       sc[kb] = u;
.Lix_m9:
	v_cmp_le_i32_e32 vcc, 0x120, v16
	v_mfma_f32_32x32x16_bf16 v[18:33], v[46:49], v[80:83], 0
	v_mfma_f32_32x32x16_bf16 v[18:33], v[42:45], v[84:87], v[18:33]
	v_mfma_f32_32x32x16_bf16 v[18:33], v[38:41], v[88:91], v[18:33]
	v_mfma_f32_32x32x16_bf16 v[18:33], v[34:37], v[92:95], v[18:33]
	s_nop 11
	v_max_f32_e32 v18, 0, v18
	v_max_f32_e32 v19, 0, v19
	v_fma_f32 v18, v143, v18, 0
	v_fmac_f32_e32 v18, v142, v19
	v_max_f32_e32 v19, 0, v20
	v_fmac_f32_e32 v18, v141, v19
	v_max_f32_e32 v19, 0, v21
	v_fmac_f32_e32 v18, v140, v19
	v_max_f32_e32 v19, 0, v22
	v_fmac_f32_e32 v18, v139, v19
	v_max_f32_e32 v19, 0, v23
	v_fmac_f32_e32 v18, v138, v19
	v_max_f32_e32 v19, 0, v24
	v_fmac_f32_e32 v18, v137, v19
	v_max_f32_e32 v19, 0, v25
	v_fmac_f32_e32 v18, v136, v19
	v_max_f32_e32 v19, 0, v26
	v_fmac_f32_e32 v18, v135, v19
	v_max_f32_e32 v19, 0, v27
	v_fmac_f32_e32 v18, v134, v19
	v_max_f32_e32 v19, 0, v28
	v_fmac_f32_e32 v18, v133, v19
	v_max_f32_e32 v19, 0, v29
	v_fmac_f32_e32 v18, v132, v19
	v_max_f32_e32 v19, 0, v30
	v_fmac_f32_e32 v18, v131, v19
	v_max_f32_e32 v19, 0, v31
	v_fmac_f32_e32 v18, v130, v19
	v_max_f32_e32 v19, 0, v32
	v_fmac_f32_e32 v18, v129, v19
	v_max_f32_e32 v19, 0, v33
	v_fmac_f32_e32 v18, v128, v19
	v_ashrrev_i32_e32 v19, 31, v18
	v_bitop3_b32 v18, v19, v18, s8 bitop3:0x36
	v_cndmask_b32_e32 v154, 0, v18, vcc
	s_cmp_lt_u32 s0, 0x140
	s_cbranch_scc1 .Lix_z10
.Lix_b10:
	s_cmp_lt_u32 s0, 0x1a0
	s_cbranch_scc1 .Lix_w10
	s_add_u32 m0, s1, 0x1000
	s_nop 0
	global_load_lds_dwordx4 v112, s[22:23]
	s_add_u32 s22, s22, 0x1e800
	s_addc_u32 s23, s23, 0
	s_add_u32 m0, s1, 0x1400
	s_nop 0
	global_load_lds_dwordx4 v113, s[22:23]
	s_add_u32 s22, s22, 0x1e800
	s_addc_u32 s23, s23, 0
	s_add_u32 m0, s1, 0x1800
	s_nop 0
	global_load_lds_dwordx4 v112, s[22:23]
	s_add_u32 s22, s22, 0x1e800
	s_addc_u32 s23, s23, 0
	s_add_u32 m0, s1, 0x1c00
	s_nop 0
	global_load_lds_dwordx4 v113, s[22:23]
	s_add_u32 s22, s22, 0x1e800
	s_addc_u32 s23, s23, 0
	s_waitcnt vmcnt(8)
	s_branch .Lix_r10

; #define MFMA(a, b, c) __builtin_amdgcn_mfma_f32_32x32x16_bf16((a), (b), (c), 0, 0, 0)
; DI void indexer_phase(const u16* __restrict__ P, unsigned* __restrict__ mask) {
;     ...
;         const u16* kp = P + (brow + 32 * kb + r32) * 7808 + 3584 + 8 * hi;
; #pragma unroll
;         for (int s = 0; s < 4; ++s) { const bf16x8 bk = *(const bf16x8*)(kp + 16 * s); a = MFMA(aq[s], bk, a); }
.Lix_r10:
	s_cmp_lt_u32 s0, 0x160
	s_cbranch_scc1 .Lix_n10
	ds_read_b128 v[80:83], v114 offset:12288
	ds_read_b128 v[84:87], v115 offset:12288
	ds_read_b128 v[88:91], v116 offset:12288
	ds_read_b128 v[92:95], v117 offset:12288
	s_waitcnt lgkmcnt(4)
	s_branch .Lix_m10

; #define MFMA(a, b, c) __builtin_amdgcn_mfma_f32_32x32x16_bf16((a), (b), (c), 0, 0, 0)
; DI unsigned ordkey(float f) { const unsigned b = __float_as_uint(f); return b ^ ((unsigned)((int)b >> 31) | 0x80000000u); }
; DI void indexer_phase(const u16* __restrict__ P, unsigned* __restrict__ mask) {
;     ...
;     for (int kb = 0; kb < 64; ++kb) {
;       unsigned u = 0u;
;       if (kb <= kbmax) {
;         f32x16 a;
; #pragma unroll
;         for (int r = 0; r < 16; ++r) a[r] = 0.f;
;         const u16* kp = P + (brow + 32 * kb + r32) * 7808 + 3584 + 8 * hi;
; #pragma unroll
;         for (int s = 0; s < 4; ++s) { const bf16x8 bk = *(const bf16x8*)(kp + 16 * s); a = MFMA(aq[s], bk, a); }
;         float v = 0.f;
; #pragma unroll
;         for (int i = 0; i < 16; ++i) v = fmaf(wv[i], fmaxf(a[i], 0.f), v);
;         u = (32 * kb + r32 <= tme) ? ordkey(v) : 0u;
;       }
;       sc[kb] = u;
.Lix_m10:
	v_cmp_le_i32_e32 vcc, 0x140, v16
	v_mfma_f32_32x32x16_bf16 v[18:33], v[46:49], v[64:67], 0
	v_mfma_f32_32x32x16_bf16 v[18:33], v[42:45], v[68:71], v[18:33]
	v_mfma_f32_32x32x16_bf16 v[18:33], v[38:41], v[72:75], v[18:33]
	v_mfma_f32_32x32x16_bf16 v[18:33], v[34:37], v[76:79], v[18:33]
	s_nop 11
	v_max_f32_e32 v18, 0, v18
	v_max_f32_e32 v19, 0, v19
	v_fma_f32 v18, v143, v18, 0
	v_fmac_f32_e32 v18, v142, v19
	v_max_f32_e32 v19, 0, v20
	v_fmac_f32_e32 v18, v141, v19
	v_max_f32_e32 v19, 0, v21
	v_fmac_f32_e32 v18, v140, v19
	v_max_f32_e32 v19, 0, v22
	v_fmac_f32_e32 v18, v139, v19
	v_max_f32_e32 v19, 0, v23
	v_fmac_f32_e32 v18, v138, v19
	v_max_f32_e32 v19, 0, v24
	v_fmac_f32_e32 v18, v137, v19
	v_max_f32_e32 v19, 0, v25
	v_fmac_f32_e32 v18, v136, v19
	v_max_f32_e32 v19, 0, v26
	v_fmac_f32_e32 v18, v135, v19
	v_max_f32_e32 v19, 0, v27
	v_fmac_f32_e32 v18, v134, v19
	v_max_f32_e32 v19, 0, v28
	v_fmac_f32_e32 v18, v133, v19
	v_max_f32_e32 v19, 0, v29
	v_fmac_f32_e32 v18, v132, v19
	v_max_f32_e32 v19, 0, v30
	v_fmac_f32_e32 v18, v131, v19
	v_max_f32_e32 v19, 0, v31
	v_fmac_f32_e32 v18, v130, v19
	v_max_f32_e32 v19, 0, v32
	v_fmac_f32_e32 v18, v129, v19
	v_max_f32_e32 v19, 0, v33
	v_fmac_f32_e32 v18, v128, v19
	v_ashrrev_i32_e32 v19, 31, v18
	v_bitop3_b32 v18, v19, v18, s8 bitop3:0x36
	v_cndmask_b32_e32 v153, 0, v18, vcc
	s_cmp_lt_u32 s0, 0x160
	s_cbranch_scc1 .Lix_z11
.Lix_b11:
	s_cmp_lt_u32 s0, 0x1c0
	s_cbranch_scc1 .Lix_w11
	s_add_u32 m0, s1, 0x2000
	s_nop 0
	global_load_lds_dwordx4 v112, s[22:23]
	s_add_u32 s22, s22, 0x1e800
	s_addc_u32 s23, s23, 0
	s_add_u32 m0, s1, 0x2400
	s_nop 0
	global_load_lds_dwordx4 v113, s[22:23]
	s_add_u32 s22, s22, 0x1e800
	s_addc_u32 s23, s23, 0
	s_add_u32 m0, s1, 0x2800
	s_nop 0
	global_load_lds_dwordx4 v112, s[22:23]
	s_add_u32 s22, s22, 0x1e800
	s_addc_u32 s23, s23, 0
	s_add_u32 m0, s1, 0x2c00
	s_nop 0
	global_load_lds_dwordx4 v113, s[22:23]
	s_add_u32 s22, s22, 0x1e800
	s_addc_u32 s23, s23, 0
	s_waitcnt vmcnt(8)
	s_branch .Lix_r11

; #define MFMA(a, b, c) __builtin_amdgcn_mfma_f32_32x32x16_bf16((a), (b), (c), 0, 0, 0)
; DI void indexer_phase(const u16* __restrict__ P, unsigned* __restrict__ mask) {
;     ...
;         const u16* kp = P + (brow + 32 * kb + r32) * 7808 + 3584 + 8 * hi;
; #pragma unroll
;         for (int s = 0; s < 4; ++s) { const bf16x8 bk = *(const bf16x8*)(kp + 16 * s); a = MFMA(aq[s], bk, a); }
.Lix_r11:
	s_cmp_lt_u32 s0, 0x180
	s_cbranch_scc1 .Lix_n11
	ds_read_b128 v[64:67], v114
	ds_read_b128 v[68:71], v115
	ds_read_b128 v[72:75], v116
	ds_read_b128 v[76:79], v117
	s_waitcnt lgkmcnt(4)
	s_branch .Lix_m11

; #define MFMA(a, b, c) __builtin_amdgcn_mfma_f32_32x32x16_bf16((a), (b), (c), 0, 0, 0)
; DI unsigned ordkey(float f) { const unsigned b = __float_as_uint(f); return b ^ ((unsigned)((int)b >> 31) | 0x80000000u); }
; DI void indexer_phase(const u16* __restrict__ P, unsigned* __restrict__ mask) {
;     ...
;     for (int kb = 0; kb < 64; ++kb) {
;       unsigned u = 0u;
;       if (kb <= kbmax) {
;         f32x16 a;
; #pragma unroll
;         for (int r = 0; r < 16; ++r) a[r] = 0.f;
;         const u16* kp = P + (brow + 32 * kb + r32) * 7808 + 3584 + 8 * hi;
; #pragma unroll
;         for (int s = 0; s < 4; ++s) { const bf16x8 bk = *(const bf16x8*)(kp + 16 * s); a = MFMA(aq[s], bk, a); }
;         float v = 0.f;
; #pragma unroll
;         for (int i = 0; i < 16; ++i) v = fmaf(wv[i], fmaxf(a[i], 0.f), v);
;         u = (32 * kb + r32 <= tme) ? ordkey(v) : 0u;
;       }
;       sc[kb] = u;
.Lix_m11:
	v_cmp_le_i32_e32 vcc, 0x160, v16
	v_mfma_f32_32x32x16_bf16 v[18:33], v[46:49], v[80:83], 0
	v_mfma_f32_32x32x16_bf16 v[18:33], v[42:45], v[84:87], v[18:33]
	v_mfma_f32_32x32x16_bf16 v[18:33], v[38:41], v[88:91], v[18:33]
	v_mfma_f32_32x32x16_bf16 v[18:33], v[34:37], v[92:95], v[18:33]
	s_nop 11
	v_max_f32_e32 v18, 0, v18
	v_max_f32_e32 v19, 0, v19
	v_fma_f32 v18, v143, v18, 0
	v_fmac_f32_e32 v18, v142, v19
	v_max_f32_e32 v19, 0, v20
	v_fmac_f32_e32 v18, v141, v19
	v_max_f32_e32 v19, 0, v21
	v_fmac_f32_e32 v18, v140, v19
	v_max_f32_e32 v19, 0, v22
	v_fmac_f32_e32 v18, v139, v19
	v_max_f32_e32 v19, 0, v23
	v_fmac_f32_e32 v18, v138, v19
	v_max_f32_e32 v19, 0, v24
	v_fmac_f32_e32 v18, v137, v19
	v_max_f32_e32 v19, 0, v25
	v_fmac_f32_e32 v18, v136, v19
	v_max_f32_e32 v19, 0, v26
	v_fmac_f32_e32 v18, v135, v19
	v_max_f32_e32 v19, 0, v27
	v_fmac_f32_e32 v18, v134, v19
	v_max_f32_e32 v19, 0, v28
	v_fmac_f32_e32 v18, v133, v19
	v_max_f32_e32 v19, 0, v29
	v_fmac_f32_e32 v18, v132, v19
	v_max_f32_e32 v19, 0, v30
	v_fmac_f32_e32 v18, v131, v19
	v_max_f32_e32 v19, 0, v31
	v_fmac_f32_e32 v18, v130, v19
	v_max_f32_e32 v19, 0, v32
	v_fmac_f32_e32 v18, v129, v19
	v_max_f32_e32 v19, 0, v33
	v_fmac_f32_e32 v18, v128, v19
	v_ashrrev_i32_e32 v19, 31, v18
	v_bitop3_b32 v18, v19, v18, s8 bitop3:0x36
	v_cndmask_b32_e32 v156, 0, v18, vcc
	s_cmp_lt_u32 s0, 0x180
	s_cbranch_scc1 .Lix_z12
.Lix_b12:
	s_cmp_lt_u32 s0, 0x1e0
	s_cbranch_scc1 .Lix_w12
	s_add_u32 m0, s1, 0x3000
	s_nop 0
	global_load_lds_dwordx4 v112, s[22:23]
	s_add_u32 s22, s22, 0x1e800
	s_addc_u32 s23, s23, 0
	s_add_u32 m0, s1, 0x3400
	s_nop 0
	global_load_lds_dwordx4 v113, s[22:23]
	s_add_u32 s22, s22, 0x1e800
	s_addc_u32 s23, s23, 0
	s_add_u32 m0, s1, 0x3800
	s_nop 0
	global_load_lds_dwordx4 v112, s[22:23]
	s_add_u32 s22, s22, 0x1e800
	s_addc_u32 s23, s23, 0
	s_add_u32 m0, s1, 0x3c00
	s_nop 0
	global_load_lds_dwordx4 v113, s[22:23]
	s_add_u32 s22, s22, 0x1e800
	s_addc_u32 s23, s23, 0
	s_waitcnt vmcnt(8)
	s_branch .Lix_r12

; #define MFMA(a, b, c) __builtin_amdgcn_mfma_f32_32x32x16_bf16((a), (b), (c), 0, 0, 0)
; DI void indexer_phase(const u16* __restrict__ P, unsigned* __restrict__ mask) {
;     ...
;         const u16* kp = P + (brow + 32 * kb + r32) * 7808 + 3584 + 8 * hi;
; #pragma unroll
;         for (int s = 0; s < 4; ++s) { const bf16x8 bk = *(const bf16x8*)(kp + 16 * s); a = MFMA(aq[s], bk, a); }
.Lix_r12:
	s_cmp_lt_u32 s0, 0x1a0
	s_cbranch_scc1 .Lix_n12
	ds_read_b128 v[80:83], v114 offset:4096
	ds_read_b128 v[84:87], v115 offset:4096
	ds_read_b128 v[88:91], v116 offset:4096
	ds_read_b128 v[92:95], v117 offset:4096
	s_waitcnt lgkmcnt(4)
	s_branch .Lix_m12

; #define MFMA(a, b, c) __builtin_amdgcn_mfma_f32_32x32x16_bf16((a), (b), (c), 0, 0, 0)
; DI unsigned ordkey(float f) { const unsigned b = __float_as_uint(f); return b ^ ((unsigned)((int)b >> 31) | 0x80000000u); }
; DI void indexer_phase(const u16* __restrict__ P, unsigned* __restrict__ mask) {
;     ...
;     for (int kb = 0; kb < 64; ++kb) {
;       unsigned u = 0u;
;       if (kb <= kbmax) {
;         f32x16 a;
; #pragma unroll
;         for (int r = 0; r < 16; ++r) a[r] = 0.f;
;         const u16* kp = P + (brow + 32 * kb + r32) * 7808 + 3584 + 8 * hi;
; #pragma unroll
;         for (int s = 0; s < 4; ++s) { const bf16x8 bk = *(const bf16x8*)(kp + 16 * s); a = MFMA(aq[s], bk, a); }
;         float v = 0.f;
; #pragma unroll
;         for (int i = 0; i < 16; ++i) v = fmaf(wv[i], fmaxf(a[i], 0.f), v);
;         u = (32 * kb + r32 <= tme) ? ordkey(v) : 0u;
;       }
;       sc[kb] = u;
.Lix_m12:
	v_cmp_le_i32_e32 vcc, 0x180, v16
	v_mfma_f32_32x32x16_bf16 v[18:33], v[46:49], v[64:67], 0
	v_mfma_f32_32x32x16_bf16 v[18:33], v[42:45], v[68:71], v[18:33]
	v_mfma_f32_32x32x16_bf16 v[18:33], v[38:41], v[72:75], v[18:33]
	v_mfma_f32_32x32x16_bf16 v[18:33], v[34:37], v[76:79], v[18:33]
	s_nop 11
	v_max_f32_e32 v18, 0, v18
	v_max_f32_e32 v19, 0, v19
	v_fma_f32 v18, v143, v18, 0
	v_fmac_f32_e32 v18, v142, v19
	v_max_f32_e32 v19, 0, v20
	v_fmac_f32_e32 v18, v141, v19
	v_max_f32_e32 v19, 0, v21
	v_fmac_f32_e32 v18, v140, v19
	v_max_f32_e32 v19, 0, v22
	v_fmac_f32_e32 v18, v139, v19
	v_max_f32_e32 v19, 0, v23
	v_fmac_f32_e32 v18, v138, v19
	v_max_f32_e32 v19, 0, v24
	v_fmac_f32_e32 v18, v137, v19
	v_max_f32_e32 v19, 0, v25
	v_fmac_f32_e32 v18, v136, v19
	v_max_f32_e32 v19, 0, v26
	v_fmac_f32_e32 v18, v135, v19
	v_max_f32_e32 v19, 0, v27
	v_fmac_f32_e32 v18, v134, v19
	v_max_f32_e32 v19, 0, v28
	v_fmac_f32_e32 v18, v133, v19
	v_max_f32_e32 v19, 0, v29
	v_fmac_f32_e32 v18, v132, v19
	v_max_f32_e32 v19, 0, v30
	v_fmac_f32_e32 v18, v131, v19
	v_max_f32_e32 v19, 0, v31
	v_fmac_f32_e32 v18, v130, v19
	v_max_f32_e32 v19, 0, v32
	v_fmac_f32_e32 v18, v129, v19
	v_max_f32_e32 v19, 0, v33
	v_fmac_f32_e32 v18, v128, v19
	v_ashrrev_i32_e32 v19, 31, v18
	v_bitop3_b32 v18, v19, v18, s8 bitop3:0x36
	v_cndmask_b32_e32 v155, 0, v18, vcc
	s_cmp_lt_u32 s0, 0x1a0
	s_cbranch_scc1 .Lix_z13
.Lix_b13:
	s_cmp_lt_u32 s0, 0x200
	s_cbranch_scc1 .Lix_w13
	s_add_u32 m0, s1, 0
	s_nop 0
	global_load_lds_dwordx4 v112, s[22:23]
	s_add_u32 s22, s22, 0x1e800
	s_addc_u32 s23, s23, 0
	s_add_u32 m0, s1, 0x400
	s_nop 0
	global_load_lds_dwordx4 v113, s[22:23]
	s_add_u32 s22, s22, 0x1e800
	s_addc_u32 s23, s23, 0
	s_add_u32 m0, s1, 0x800
	s_nop 0
	global_load_lds_dwordx4 v112, s[22:23]
	s_add_u32 s22, s22, 0x1e800
	s_addc_u32 s23, s23, 0
	s_add_u32 m0, s1, 0xc00
	s_nop 0
	global_load_lds_dwordx4 v113, s[22:23]
	s_add_u32 s22, s22, 0x1e800
	s_addc_u32 s23, s23, 0
	s_waitcnt vmcnt(8)
	s_branch .Lix_r13

; #define MFMA(a, b, c) __builtin_amdgcn_mfma_f32_32x32x16_bf16((a), (b), (c), 0, 0, 0)
; DI void indexer_phase(const u16* __restrict__ P, unsigned* __restrict__ mask) {
;     ...
;         const u16* kp = P + (brow + 32 * kb + r32) * 7808 + 3584 + 8 * hi;
; #pragma unroll
;         for (int s = 0; s < 4; ++s) { const bf16x8 bk = *(const bf16x8*)(kp + 16 * s); a = MFMA(aq[s], bk, a); }
.Lix_r13:
	s_cmp_lt_u32 s0, 0x1c0
	s_cbranch_scc1 .Lix_n13
	ds_read_b128 v[64:67], v114 offset:8192
	ds_read_b128 v[68:71], v115 offset:8192
	ds_read_b128 v[72:75], v116 offset:8192
	ds_read_b128 v[76:79], v117 offset:8192
	s_waitcnt lgkmcnt(4)
	s_branch .Lix_m13

; #define MFMA(a, b, c) __builtin_amdgcn_mfma_f32_32x32x16_bf16((a), (b), (c), 0, 0, 0)
; DI unsigned ordkey(float f) { const unsigned b = __float_as_uint(f); return b ^ ((unsigned)((int)b >> 31) | 0x80000000u); }
; DI void indexer_phase(const u16* __restrict__ P, unsigned* __restrict__ mask) {
;     ...
;     for (int kb = 0; kb < 64; ++kb) {
;       unsigned u = 0u;
;       if (kb <= kbmax) {
;         f32x16 a;
; #pragma unroll
;         for (int r = 0; r < 16; ++r) a[r] = 0.f;
;         const u16* kp = P + (brow + 32 * kb + r32) * 7808 + 3584 + 8 * hi;
; #pragma unroll
;         for (int s = 0; s < 4; ++s) { const bf16x8 bk = *(const bf16x8*)(kp + 16 * s); a = MFMA(aq[s], bk, a); }
;         float v = 0.f;
; #pragma unroll
;         for (int i = 0; i < 16; ++i) v = fmaf(wv[i], fmaxf(a[i], 0.f), v);
;         u = (32 * kb + r32 <= tme) ? ordkey(v) : 0u;
;       }
;       sc[kb] = u;
.Lix_m13:
	v_cmp_le_i32_e32 vcc, 0x1a0, v16
	v_mfma_f32_32x32x16_bf16 v[18:33], v[46:49], v[80:83], 0
	v_mfma_f32_32x32x16_bf16 v[18:33], v[42:45], v[84:87], v[18:33]
	v_mfma_f32_32x32x16_bf16 v[18:33], v[38:41], v[88:91], v[18:33]
	v_mfma_f32_32x32x16_bf16 v[18:33], v[34:37], v[92:95], v[18:33]
	s_nop 11
	v_max_f32_e32 v18, 0, v18
	v_max_f32_e32 v19, 0, v19
	v_fma_f32 v18, v143, v18, 0
	v_fmac_f32_e32 v18, v142, v19
	v_max_f32_e32 v19, 0, v20
	v_fmac_f32_e32 v18, v141, v19
	v_max_f32_e32 v19, 0, v21
	v_fmac_f32_e32 v18, v140, v19
	v_max_f32_e32 v19, 0, v22
	v_fmac_f32_e32 v18, v139, v19
	v_max_f32_e32 v19, 0, v23
	v_fmac_f32_e32 v18, v138, v19
	v_max_f32_e32 v19, 0, v24
	v_fmac_f32_e32 v18, v137, v19
	v_max_f32_e32 v19, 0, v25
	v_fmac_f32_e32 v18, v136, v19
	v_max_f32_e32 v19, 0, v26
	v_fmac_f32_e32 v18, v135, v19
	v_max_f32_e32 v19, 0, v27
	v_fmac_f32_e32 v18, v134, v19
	v_max_f32_e32 v19, 0, v28
	v_fmac_f32_e32 v18, v133, v19
	v_max_f32_e32 v19, 0, v29
	v_fmac_f32_e32 v18, v132, v19
	v_max_f32_e32 v19, 0, v30
	v_fmac_f32_e32 v18, v131, v19
	v_max_f32_e32 v19, 0, v31
	v_fmac_f32_e32 v18, v130, v19
	v_max_f32_e32 v19, 0, v32
	v_fmac_f32_e32 v18, v129, v19
	v_max_f32_e32 v19, 0, v33
	v_fmac_f32_e32 v18, v128, v19
	v_ashrrev_i32_e32 v19, 31, v18
	v_bitop3_b32 v18, v19, v18, s8 bitop3:0x36
	v_cndmask_b32_e32 v158, 0, v18, vcc
	s_cmp_lt_u32 s0, 0x1c0
	s_cbranch_scc1 .Lix_z14
.Lix_b14:
	s_cmp_lt_u32 s0, 0x220
	s_cbranch_scc1 .Lix_w14
	s_add_u32 m0, s1, 0x1000
	s_nop 0
	global_load_lds_dwordx4 v112, s[22:23]
	s_add_u32 s22, s22, 0x1e800
	s_addc_u32 s23, s23, 0
	s_add_u32 m0, s1, 0x1400
	s_nop 0
	global_load_lds_dwordx4 v113, s[22:23]
	s_add_u32 s22, s22, 0x1e800
	s_addc_u32 s23, s23, 0
	s_add_u32 m0, s1, 0x1800
	s_nop 0
	global_load_lds_dwordx4 v112, s[22:23]
	s_add_u32 s22, s22, 0x1e800
	s_addc_u32 s23, s23, 0
	s_add_u32 m0, s1, 0x1c00
	s_nop 0
	global_load_lds_dwordx4 v113, s[22:23]
	s_add_u32 s22, s22, 0x1e800
	s_addc_u32 s23, s23, 0
	s_waitcnt vmcnt(8)
	s_branch .Lix_r14

; #define MFMA(a, b, c) __builtin_amdgcn_mfma_f32_32x32x16_bf16((a), (b), (c), 0, 0, 0)
; DI void indexer_phase(const u16* __restrict__ P, unsigned* __restrict__ mask) {
;     ...
;         const u16* kp = P + (brow + 32 * kb + r32) * 7808 + 3584 + 8 * hi;
; #pragma unroll
;         for (int s = 0; s < 4; ++s) { const bf16x8 bk = *(const bf16x8*)(kp + 16 * s); a = MFMA(aq[s], bk, a); }
.Lix_r14:
	s_cmp_lt_u32 s0, 0x1e0
	s_cbranch_scc1 .Lix_n14
	ds_read_b128 v[80:83], v114 offset:12288
	ds_read_b128 v[84:87], v115 offset:12288
	ds_read_b128 v[88:91], v116 offset:12288
	ds_read_b128 v[92:95], v117 offset:12288
	s_waitcnt lgkmcnt(4)
	s_branch .Lix_m14

; #define MFMA(a, b, c) __builtin_amdgcn_mfma_f32_32x32x16_bf16((a), (b), (c), 0, 0, 0)
; DI unsigned ordkey(float f) { const unsigned b = __float_as_uint(f); return b ^ ((unsigned)((int)b >> 31) | 0x80000000u); }
; DI void indexer_phase(const u16* __restrict__ P, unsigned* __restrict__ mask) {
;     ...
;     for (int kb = 0; kb < 64; ++kb) {
;       unsigned u = 0u;
;       if (kb <= kbmax) {
;         f32x16 a;
; #pragma unroll
;         for (int r = 0; r < 16; ++r) a[r] = 0.f;
;         const u16* kp = P + (brow + 32 * kb + r32) * 7808 + 3584 + 8 * hi;
; #pragma unroll
;         for (int s = 0; s < 4; ++s) { const bf16x8 bk = *(const bf16x8*)(kp + 16 * s); a = MFMA(aq[s], bk, a); }
;         float v = 0.f;
; #pragma unroll
;         for (int i = 0; i < 16; ++i) v = fmaf(wv[i], fmaxf(a[i], 0.f), v);
;         u = (32 * kb + r32 <= tme) ? ordkey(v) : 0u;
;       }
;       sc[kb] = u;
.Lix_m14:
	v_cmp_le_i32_e32 vcc, 0x1c0, v16
	v_mfma_f32_32x32x16_bf16 v[18:33], v[46:49], v[64:67], 0
	v_mfma_f32_32x32x16_bf16 v[18:33], v[42:45], v[68:71], v[18:33]
	v_mfma_f32_32x32x16_bf16 v[18:33], v[38:41], v[72:75], v[18:33]
	v_mfma_f32_32x32x16_bf16 v[18:33], v[34:37], v[76:79], v[18:33]
	s_nop 11
	v_max_f32_e32 v18, 0, v18
	v_max_f32_e32 v19, 0, v19
	v_fma_f32 v18, v143, v18, 0
	v_fmac_f32_e32 v18, v142, v19
	v_max_f32_e32 v19, 0, v20
	v_fmac_f32_e32 v18, v141, v19
	v_max_f32_e32 v19, 0, v21
	v_fmac_f32_e32 v18, v140, v19
	v_max_f32_e32 v19, 0, v22
	v_fmac_f32_e32 v18, v139, v19
	v_max_f32_e32 v19, 0, v23
	v_fmac_f32_e32 v18, v138, v19
	v_max_f32_e32 v19, 0, v24
	v_fmac_f32_e32 v18, v137, v19
	v_max_f32_e32 v19, 0, v25
	v_fmac_f32_e32 v18, v136, v19
	v_max_f32_e32 v19, 0, v26
	v_fmac_f32_e32 v18, v135, v19
	v_max_f32_e32 v19, 0, v27
	v_fmac_f32_e32 v18, v134, v19
	v_max_f32_e32 v19, 0, v28
	v_fmac_f32_e32 v18, v133, v19
	v_max_f32_e32 v19, 0, v29
	v_fmac_f32_e32 v18, v132, v19
	v_max_f32_e32 v19, 0, v30
	v_fmac_f32_e32 v18, v131, v19
	v_max_f32_e32 v19, 0, v31
	v_fmac_f32_e32 v18, v130, v19
	v_max_f32_e32 v19, 0, v32
	v_fmac_f32_e32 v18, v129, v19
	v_max_f32_e32 v19, 0, v33
	v_fmac_f32_e32 v18, v128, v19
	v_ashrrev_i32_e32 v19, 31, v18
	v_bitop3_b32 v18, v19, v18, s8 bitop3:0x36
	v_cndmask_b32_e32 v157, 0, v18, vcc
	s_cmp_lt_u32 s0, 0x1e0
	s_cbranch_scc1 .Lix_z15
.Lix_b15:
	s_cmp_lt_u32 s0, 0x240
	s_cbranch_scc1 .Lix_w15
	s_add_u32 m0, s1, 0x2000
	s_nop 0
	global_load_lds_dwordx4 v112, s[22:23]
	s_add_u32 s22, s22, 0x1e800
	s_addc_u32 s23, s23, 0
	s_add_u32 m0, s1, 0x2400
	s_nop 0
	global_load_lds_dwordx4 v113, s[22:23]
	s_add_u32 s22, s22, 0x1e800
	s_addc_u32 s23, s23, 0
	s_add_u32 m0, s1, 0x2800
	s_nop 0
	global_load_lds_dwordx4 v112, s[22:23]
	s_add_u32 s22, s22, 0x1e800
	s_addc_u32 s23, s23, 0
	s_add_u32 m0, s1, 0x2c00
	s_nop 0
	global_load_lds_dwordx4 v113, s[22:23]
	s_add_u32 s22, s22, 0x1e800
	s_addc_u32 s23, s23, 0
	s_waitcnt vmcnt(8)
	s_branch .Lix_r15

; #define MFMA(a, b, c) __builtin_amdgcn_mfma_f32_32x32x16_bf16((a), (b), (c), 0, 0, 0)
; DI void indexer_phase(const u16* __restrict__ P, unsigned* __restrict__ mask) {
;     ...
;         const u16* kp = P + (brow + 32 * kb + r32) * 7808 + 3584 + 8 * hi;
; #pragma unroll
;         for (int s = 0; s < 4; ++s) { const bf16x8 bk = *(const bf16x8*)(kp + 16 * s); a = MFMA(aq[s], bk, a); }
.Lix_r15:
	s_cmp_lt_u32 s0, 0x200
	s_cbranch_scc1 .Lix_n15
	ds_read_b128 v[64:67], v114
	ds_read_b128 v[68:71], v115
	ds_read_b128 v[72:75], v116
	ds_read_b128 v[76:79], v117
	s_waitcnt lgkmcnt(4)
	s_branch .Lix_m15

; #define MFMA(a, b, c) __builtin_amdgcn_mfma_f32_32x32x16_bf16((a), (b), (c), 0, 0, 0)
; DI unsigned ordkey(float f) { const unsigned b = __float_as_uint(f); return b ^ ((unsigned)((int)b >> 31) | 0x80000000u); }
; DI void indexer_phase(const u16* __restrict__ P, unsigned* __restrict__ mask) {
;     ...
;     for (int kb = 0; kb < 64; ++kb) {
;       unsigned u = 0u;
;       if (kb <= kbmax) {
;         f32x16 a;
; #pragma unroll
;         for (int r = 0; r < 16; ++r) a[r] = 0.f;
;         const u16* kp = P + (brow + 32 * kb + r32) * 7808 + 3584 + 8 * hi;
; #pragma unroll
;         for (int s = 0; s < 4; ++s) { const bf16x8 bk = *(const bf16x8*)(kp + 16 * s); a = MFMA(aq[s], bk, a); }
;         float v = 0.f;
; #pragma unroll
;         for (int i = 0; i < 16; ++i) v = fmaf(wv[i], fmaxf(a[i], 0.f), v);
;         u = (32 * kb + r32 <= tme) ? ordkey(v) : 0u;
;       }
;       sc[kb] = u;
.Lix_m15:
	v_cmp_le_i32_e32 vcc, 0x1e0, v16
	v_mfma_f32_32x32x16_bf16 v[18:33], v[46:49], v[80:83], 0
	v_mfma_f32_32x32x16_bf16 v[18:33], v[42:45], v[84:87], v[18:33]
	v_mfma_f32_32x32x16_bf16 v[18:33], v[38:41], v[88:91], v[18:33]
	v_mfma_f32_32x32x16_bf16 v[18:33], v[34:37], v[92:95], v[18:33]
	s_nop 11
	v_max_f32_e32 v18, 0, v18
	v_max_f32_e32 v19, 0, v19
	v_fma_f32 v18, v143, v18, 0
	v_fmac_f32_e32 v18, v142, v19
	v_max_f32_e32 v19, 0, v20
	v_fmac_f32_e32 v18, v141, v19
	v_max_f32_e32 v19, 0, v21
	v_fmac_f32_e32 v18, v140, v19
	v_max_f32_e32 v19, 0, v22
	v_fmac_f32_e32 v18, v139, v19
	v_max_f32_e32 v19, 0, v23
	v_fmac_f32_e32 v18, v138, v19
	v_max_f32_e32 v19, 0, v24
	v_fmac_f32_e32 v18, v137, v19
	v_max_f32_e32 v19, 0, v25
	v_fmac_f32_e32 v18, v136, v19
	v_max_f32_e32 v19, 0, v26
	v_fmac_f32_e32 v18, v135, v19
	v_max_f32_e32 v19, 0, v27
	v_fmac_f32_e32 v18, v134, v19
	v_max_f32_e32 v19, 0, v28
	v_fmac_f32_e32 v18, v133, v19
	v_max_f32_e32 v19, 0, v29
	v_fmac_f32_e32 v18, v132, v19
	v_max_f32_e32 v19, 0, v30
	v_fmac_f32_e32 v18, v131, v19
	v_max_f32_e32 v19, 0, v31
	v_fmac_f32_e32 v18, v130, v19
	v_max_f32_e32 v19, 0, v32
	v_fmac_f32_e32 v18, v129, v19
	v_max_f32_e32 v19, 0, v33
	v_fmac_f32_e32 v18, v128, v19
	v_ashrrev_i32_e32 v19, 31, v18
	v_bitop3_b32 v18, v19, v18, s8 bitop3:0x36
	v_cndmask_b32_e32 v160, 0, v18, vcc
	s_cmp_lt_u32 s0, 0x200
	s_cbranch_scc1 .Lix_z16
.Lix_b16:
	s_cmp_lt_u32 s0, 0x260
	s_cbranch_scc1 .Lix_w16
	s_add_u32 m0, s1, 0x3000
	s_nop 0
	global_load_lds_dwordx4 v112, s[22:23]
	s_add_u32 s22, s22, 0x1e800
	s_addc_u32 s23, s23, 0
	s_add_u32 m0, s1, 0x3400
	s_nop 0
	global_load_lds_dwordx4 v113, s[22:23]
	s_add_u32 s22, s22, 0x1e800
	s_addc_u32 s23, s23, 0
	s_add_u32 m0, s1, 0x3800
	s_nop 0
	global_load_lds_dwordx4 v112, s[22:23]
	s_add_u32 s22, s22, 0x1e800
	s_addc_u32 s23, s23, 0
	s_add_u32 m0, s1, 0x3c00
	s_nop 0
	global_load_lds_dwordx4 v113, s[22:23]
	s_add_u32 s22, s22, 0x1e800
	s_addc_u32 s23, s23, 0
	s_waitcnt vmcnt(8)
	s_branch .Lix_r16

; #define MFMA(a, b, c) __builtin_amdgcn_mfma_f32_32x32x16_bf16((a), (b), (c), 0, 0, 0)
; DI void indexer_phase(const u16* __restrict__ P, unsigned* __restrict__ mask) {
;     ...
;         const u16* kp = P + (brow + 32 * kb + r32) * 7808 + 3584 + 8 * hi;
; #pragma unroll
;         for (int s = 0; s < 4; ++s) { const bf16x8 bk = *(const bf16x8*)(kp + 16 * s); a = MFMA(aq[s], bk, a); }
.Lix_r16:
	s_cmp_lt_u32 s0, 0x220
	s_cbranch_scc1 .Lix_n16
	ds_read_b128 v[80:83], v114 offset:4096
	ds_read_b128 v[84:87], v115 offset:4096
	ds_read_b128 v[88:91], v116 offset:4096
	ds_read_b128 v[92:95], v117 offset:4096
	s_waitcnt lgkmcnt(4)
	s_branch .Lix_m16

; #define MFMA(a, b, c) __builtin_amdgcn_mfma_f32_32x32x16_bf16((a), (b), (c), 0, 0, 0)
; DI unsigned ordkey(float f) { const unsigned b = __float_as_uint(f); return b ^ ((unsigned)((int)b >> 31) | 0x80000000u); }
; DI void indexer_phase(const u16* __restrict__ P, unsigned* __restrict__ mask) {
;     ...
;     for (int kb = 0; kb < 64; ++kb) {
;       unsigned u = 0u;
;       if (kb <= kbmax) {
;         f32x16 a;
; #pragma unroll
;         for (int r = 0; r < 16; ++r) a[r] = 0.f;
;         const u16* kp = P + (brow + 32 * kb + r32) * 7808 + 3584 + 8 * hi;
; #pragma unroll
;         for (int s = 0; s < 4; ++s) { const bf16x8 bk = *(const bf16x8*)(kp + 16 * s); a = MFMA(aq[s], bk, a); }
;         float v = 0.f;
; #pragma unroll
;         for (int i = 0; i < 16; ++i) v = fmaf(wv[i], fmaxf(a[i], 0.f), v);
;         u = (32 * kb + r32 <= tme) ? ordkey(v) : 0u;
;       }
;       sc[kb] = u;
.Lix_m16:
	v_cmp_le_i32_e32 vcc, 0x200, v16
	v_mfma_f32_32x32x16_bf16 v[18:33], v[46:49], v[64:67], 0
	v_mfma_f32_32x32x16_bf16 v[18:33], v[42:45], v[68:71], v[18:33]
	v_mfma_f32_32x32x16_bf16 v[18:33], v[38:41], v[72:75], v[18:33]
	v_mfma_f32_32x32x16_bf16 v[18:33], v[34:37], v[76:79], v[18:33]
	s_nop 11
	v_max_f32_e32 v18, 0, v18
	v_max_f32_e32 v19, 0, v19
	v_fma_f32 v18, v143, v18, 0
	v_fmac_f32_e32 v18, v142, v19
	v_max_f32_e32 v19, 0, v20
	v_fmac_f32_e32 v18, v141, v19
	v_max_f32_e32 v19, 0, v21
	v_fmac_f32_e32 v18, v140, v19
	v_max_f32_e32 v19, 0, v22
	v_fmac_f32_e32 v18, v139, v19
	v_max_f32_e32 v19, 0, v23
	v_fmac_f32_e32 v18, v138, v19
	v_max_f32_e32 v19, 0, v24
	v_fmac_f32_e32 v18, v137, v19
	v_max_f32_e32 v19, 0, v25
	v_fmac_f32_e32 v18, v136, v19
	v_max_f32_e32 v19, 0, v26
	v_fmac_f32_e32 v18, v135, v19
	v_max_f32_e32 v19, 0, v27
	v_fmac_f32_e32 v18, v134, v19
	v_max_f32_e32 v19, 0, v28
	v_fmac_f32_e32 v18, v133, v19
	v_max_f32_e32 v19, 0, v29
	v_fmac_f32_e32 v18, v132, v19
	v_max_f32_e32 v19, 0, v30
	v_fmac_f32_e32 v18, v131, v19
	v_max_f32_e32 v19, 0, v31
	v_fmac_f32_e32 v18, v130, v19
	v_max_f32_e32 v19, 0, v32
	v_fmac_f32_e32 v18, v129, v19
	v_max_f32_e32 v19, 0, v33
	v_fmac_f32_e32 v18, v128, v19
	v_ashrrev_i32_e32 v19, 31, v18
	v_bitop3_b32 v18, v19, v18, s8 bitop3:0x36
	v_cndmask_b32_e32 v159, 0, v18, vcc
	s_cmp_lt_u32 s0, 0x220
	s_cbranch_scc1 .Lix_z17
.Lix_b17:
	s_cmp_lt_u32 s0, 0x280
	s_cbranch_scc1 .Lix_w17
	s_add_u32 m0, s1, 0
	s_nop 0
	global_load_lds_dwordx4 v112, s[22:23]
	s_add_u32 s22, s22, 0x1e800
	s_addc_u32 s23, s23, 0
	s_add_u32 m0, s1, 0x400
	s_nop 0
	global_load_lds_dwordx4 v113, s[22:23]
	s_add_u32 s22, s22, 0x1e800
	s_addc_u32 s23, s23, 0
	s_add_u32 m0, s1, 0x800
	s_nop 0
	global_load_lds_dwordx4 v112, s[22:23]
	s_add_u32 s22, s22, 0x1e800
	s_addc_u32 s23, s23, 0
	s_add_u32 m0, s1, 0xc00
	s_nop 0
	global_load_lds_dwordx4 v113, s[22:23]
	s_add_u32 s22, s22, 0x1e800
	s_addc_u32 s23, s23, 0
	s_waitcnt vmcnt(8)
	s_branch .Lix_r17

; #define MFMA(a, b, c) __builtin_amdgcn_mfma_f32_32x32x16_bf16((a), (b), (c), 0, 0, 0)
; DI void indexer_phase(const u16* __restrict__ P, unsigned* __restrict__ mask) {
;     ...
;         const u16* kp = P + (brow + 32 * kb + r32) * 7808 + 3584 + 8 * hi;
; #pragma unroll
;         for (int s = 0; s < 4; ++s) { const bf16x8 bk = *(const bf16x8*)(kp + 16 * s); a = MFMA(aq[s], bk, a); }
.Lix_r17:
	s_cmp_lt_u32 s0, 0x240
	s_cbranch_scc1 .Lix_n17
	ds_read_b128 v[64:67], v114 offset:8192
	ds_read_b128 v[68:71], v115 offset:8192
	ds_read_b128 v[72:75], v116 offset:8192
	ds_read_b128 v[76:79], v117 offset:8192
	s_waitcnt lgkmcnt(4)
	s_branch .Lix_m17

; #define MFMA(a, b, c) __builtin_amdgcn_mfma_f32_32x32x16_bf16((a), (b), (c), 0, 0, 0)
; DI unsigned ordkey(float f) { const unsigned b = __float_as_uint(f); return b ^ ((unsigned)((int)b >> 31) | 0x80000000u); }
; DI void indexer_phase(const u16* __restrict__ P, unsigned* __restrict__ mask) {
;     ...
;     for (int kb = 0; kb < 64; ++kb) {
;       unsigned u = 0u;
;       if (kb <= kbmax) {
;         f32x16 a;
; #pragma unroll
;         for (int r = 0; r < 16; ++r) a[r] = 0.f;
;         const u16* kp = P + (brow + 32 * kb + r32) * 7808 + 3584 + 8 * hi;
; #pragma unroll
;         for (int s = 0; s < 4; ++s) { const bf16x8 bk = *(const bf16x8*)(kp + 16 * s); a = MFMA(aq[s], bk, a); }
;         float v = 0.f;
; #pragma unroll
;         for (int i = 0; i < 16; ++i) v = fmaf(wv[i], fmaxf(a[i], 0.f), v);
;         u = (32 * kb + r32 <= tme) ? ordkey(v) : 0u;
;       }
;       sc[kb] = u;
.Lix_m17:
	v_cmp_le_i32_e32 vcc, 0x220, v16
	v_mfma_f32_32x32x16_bf16 v[18:33], v[46:49], v[80:83], 0
	v_mfma_f32_32x32x16_bf16 v[18:33], v[42:45], v[84:87], v[18:33]
	v_mfma_f32_32x32x16_bf16 v[18:33], v[38:41], v[88:91], v[18:33]
	v_mfma_f32_32x32x16_bf16 v[18:33], v[34:37], v[92:95], v[18:33]
	s_nop 11
	v_max_f32_e32 v18, 0, v18
	v_max_f32_e32 v19, 0, v19
	v_fma_f32 v18, v143, v18, 0
	v_fmac_f32_e32 v18, v142, v19
	v_max_f32_e32 v19, 0, v20
	v_fmac_f32_e32 v18, v141, v19
	v_max_f32_e32 v19, 0, v21
	v_fmac_f32_e32 v18, v140, v19
	v_max_f32_e32 v19, 0, v22
	v_fmac_f32_e32 v18, v139, v19
	v_max_f32_e32 v19, 0, v23
	v_fmac_f32_e32 v18, v138, v19
	v_max_f32_e32 v19, 0, v24
	v_fmac_f32_e32 v18, v137, v19
	v_max_f32_e32 v19, 0, v25
	v_fmac_f32_e32 v18, v136, v19
	v_max_f32_e32 v19, 0, v26
	v_fmac_f32_e32 v18, v135, v19
	v_max_f32_e32 v19, 0, v27
	v_fmac_f32_e32 v18, v134, v19
	v_max_f32_e32 v19, 0, v28
	v_fmac_f32_e32 v18, v133, v19
	v_max_f32_e32 v19, 0, v29
	v_fmac_f32_e32 v18, v132, v19
	v_max_f32_e32 v19, 0, v30
	v_fmac_f32_e32 v18, v131, v19
	v_max_f32_e32 v19, 0, v31
	v_fmac_f32_e32 v18, v130, v19
	v_max_f32_e32 v19, 0, v32
	v_fmac_f32_e32 v18, v129, v19
	v_max_f32_e32 v19, 0, v33
	v_fmac_f32_e32 v18, v128, v19
	v_ashrrev_i32_e32 v19, 31, v18
	v_bitop3_b32 v18, v19, v18, s8 bitop3:0x36
	v_cndmask_b32_e32 v162, 0, v18, vcc
	s_cmp_lt_u32 s0, 0x240
	s_cbranch_scc1 .Lix_z18
.Lix_b18:
	s_cmp_lt_u32 s0, 0x2a0
	s_cbranch_scc1 .Lix_w18
	s_add_u32 m0, s1, 0x1000
	s_nop 0
	global_load_lds_dwordx4 v112, s[22:23]
	s_add_u32 s22, s22, 0x1e800
	s_addc_u32 s23, s23, 0
	s_add_u32 m0, s1, 0x1400
	s_nop 0
	global_load_lds_dwordx4 v113, s[22:23]
	s_add_u32 s22, s22, 0x1e800
	s_addc_u32 s23, s23, 0
	s_add_u32 m0, s1, 0x1800
	s_nop 0
	global_load_lds_dwordx4 v112, s[22:23]
	s_add_u32 s22, s22, 0x1e800
	s_addc_u32 s23, s23, 0
	s_add_u32 m0, s1, 0x1c00
	s_nop 0
	global_load_lds_dwordx4 v113, s[22:23]
	s_add_u32 s22, s22, 0x1e800
	s_addc_u32 s23, s23, 0
	s_waitcnt vmcnt(8)
	s_branch .Lix_r18

; #define MFMA(a, b, c) __builtin_amdgcn_mfma_f32_32x32x16_bf16((a), (b), (c), 0, 0, 0)
; DI void indexer_phase(const u16* __restrict__ P, unsigned* __restrict__ mask) {
;     ...
;         const u16* kp = P + (brow + 32 * kb + r32) * 7808 + 3584 + 8 * hi;
; #pragma unroll
;         for (int s = 0; s < 4; ++s) { const bf16x8 bk = *(const bf16x8*)(kp + 16 * s); a = MFMA(aq[s], bk, a); }
.Lix_r18:
	s_cmp_lt_u32 s0, 0x260
	s_cbranch_scc1 .Lix_n18
	ds_read_b128 v[80:83], v114 offset:12288
	ds_read_b128 v[84:87], v115 offset:12288
	ds_read_b128 v[88:91], v116 offset:12288
	ds_read_b128 v[92:95], v117 offset:12288
	s_waitcnt lgkmcnt(4)
	s_branch .Lix_m18

; #define MFMA(a, b, c) __builtin_amdgcn_mfma_f32_32x32x16_bf16((a), (b), (c), 0, 0, 0)
; DI unsigned ordkey(float f) { const unsigned b = __float_as_uint(f); return b ^ ((unsigned)((int)b >> 31) | 0x80000000u); }
; DI void indexer_phase(const u16* __restrict__ P, unsigned* __restrict__ mask) {
;     ...
;     for (int kb = 0; kb < 64; ++kb) {
;       unsigned u = 0u;
;       if (kb <= kbmax) {
;         f32x16 a;
; #pragma unroll
;         for (int r = 0; r < 16; ++r) a[r] = 0.f;
;         const u16* kp = P + (brow + 32 * kb + r32) * 7808 + 3584 + 8 * hi;
; #pragma unroll
;         for (int s = 0; s < 4; ++s) { const bf16x8 bk = *(const bf16x8*)(kp + 16 * s); a = MFMA(aq[s], bk, a); }
;         float v = 0.f;
; #pragma unroll
;         for (int i = 0; i < 16; ++i) v = fmaf(wv[i], fmaxf(a[i], 0.f), v);
;         u = (32 * kb + r32 <= tme) ? ordkey(v) : 0u;
;       }
;       sc[kb] = u;
.Lix_m18:
	v_cmp_le_i32_e32 vcc, 0x240, v16
	v_mfma_f32_32x32x16_bf16 v[18:33], v[46:49], v[64:67], 0
	v_mfma_f32_32x32x16_bf16 v[18:33], v[42:45], v[68:71], v[18:33]
	v_mfma_f32_32x32x16_bf16 v[18:33], v[38:41], v[72:75], v[18:33]
	v_mfma_f32_32x32x16_bf16 v[18:33], v[34:37], v[76:79], v[18:33]
	s_nop 11
	v_max_f32_e32 v18, 0, v18
	v_max_f32_e32 v19, 0, v19
	v_fma_f32 v18, v143, v18, 0
	v_fmac_f32_e32 v18, v142, v19
	v_max_f32_e32 v19, 0, v20
	v_fmac_f32_e32 v18, v141, v19
	v_max_f32_e32 v19, 0, v21
	v_fmac_f32_e32 v18, v140, v19
	v_max_f32_e32 v19, 0, v22
	v_fmac_f32_e32 v18, v139, v19
	v_max_f32_e32 v19, 0, v23
	v_fmac_f32_e32 v18, v138, v19
	v_max_f32_e32 v19, 0, v24
	v_fmac_f32_e32 v18, v137, v19
	v_max_f32_e32 v19, 0, v25
	v_fmac_f32_e32 v18, v136, v19
	v_max_f32_e32 v19, 0, v26
	v_fmac_f32_e32 v18, v135, v19
	v_max_f32_e32 v19, 0, v27
	v_fmac_f32_e32 v18, v134, v19
	v_max_f32_e32 v19, 0, v28
	v_fmac_f32_e32 v18, v133, v19
	v_max_f32_e32 v19, 0, v29
	v_fmac_f32_e32 v18, v132, v19
	v_max_f32_e32 v19, 0, v30
	v_fmac_f32_e32 v18, v131, v19
	v_max_f32_e32 v19, 0, v31
	v_fmac_f32_e32 v18, v130, v19
	v_max_f32_e32 v19, 0, v32
	v_fmac_f32_e32 v18, v129, v19
	v_max_f32_e32 v19, 0, v33
	v_fmac_f32_e32 v18, v128, v19
	v_ashrrev_i32_e32 v19, 31, v18
	v_bitop3_b32 v18, v19, v18, s8 bitop3:0x36
	v_cndmask_b32_e32 v161, 0, v18, vcc
	s_cmp_lt_u32 s0, 0x260
	s_cbranch_scc1 .Lix_z19
.Lix_b19:
	s_cmp_lt_u32 s0, 0x2c0
	s_cbranch_scc1 .Lix_w19
	s_add_u32 m0, s1, 0x2000
	s_nop 0
	global_load_lds_dwordx4 v112, s[22:23]
	s_add_u32 s22, s22, 0x1e800
	s_addc_u32 s23, s23, 0
	s_add_u32 m0, s1, 0x2400
	s_nop 0
	global_load_lds_dwordx4 v113, s[22:23]
	s_add_u32 s22, s22, 0x1e800
	s_addc_u32 s23, s23, 0
	s_add_u32 m0, s1, 0x2800
	s_nop 0
	global_load_lds_dwordx4 v112, s[22:23]
	s_add_u32 s22, s22, 0x1e800
	s_addc_u32 s23, s23, 0
	s_add_u32 m0, s1, 0x2c00
	s_nop 0
	global_load_lds_dwordx4 v113, s[22:23]
	s_add_u32 s22, s22, 0x1e800
	s_addc_u32 s23, s23, 0
	s_waitcnt vmcnt(8)
	s_branch .Lix_r19

; #define MFMA(a, b, c) __builtin_amdgcn_mfma_f32_32x32x16_bf16((a), (b), (c), 0, 0, 0)
; DI void indexer_phase(const u16* __restrict__ P, unsigned* __restrict__ mask) {
;     ...
;         const u16* kp = P + (brow + 32 * kb + r32) * 7808 + 3584 + 8 * hi;
; #pragma unroll
;         for (int s = 0; s < 4; ++s) { const bf16x8 bk = *(const bf16x8*)(kp + 16 * s); a = MFMA(aq[s], bk, a); }
.Lix_r19:
	s_cmp_lt_u32 s0, 0x280
	s_cbranch_scc1 .Lix_n19
	ds_read_b128 v[64:67], v114
	ds_read_b128 v[68:71], v115
	ds_read_b128 v[72:75], v116
	ds_read_b128 v[76:79], v117
	s_waitcnt lgkmcnt(4)
	s_branch .Lix_m19

; #define MFMA(a, b, c) __builtin_amdgcn_mfma_f32_32x32x16_bf16((a), (b), (c), 0, 0, 0)
; DI unsigned ordkey(float f) { const unsigned b = __float_as_uint(f); return b ^ ((unsigned)((int)b >> 31) | 0x80000000u); }
; DI void indexer_phase(const u16* __restrict__ P, unsigned* __restrict__ mask) {
;     ...
;     for (int kb = 0; kb < 64; ++kb) {
;       unsigned u = 0u;
;       if (kb <= kbmax) {
;         f32x16 a;
; #pragma unroll
;         for (int r = 0; r < 16; ++r) a[r] = 0.f;
;         const u16* kp = P + (brow + 32 * kb + r32) * 7808 + 3584 + 8 * hi;
; #pragma unroll
;         for (int s = 0; s < 4; ++s) { const bf16x8 bk = *(const bf16x8*)(kp + 16 * s); a = MFMA(aq[s], bk, a); }
;         float v = 0.f;
; #pragma unroll
;         for (int i = 0; i < 16; ++i) v = fmaf(wv[i], fmaxf(a[i], 0.f), v);
;         u = (32 * kb + r32 <= tme) ? ordkey(v) : 0u;
;       }
;       sc[kb] = u;
.Lix_m19:
	v_cmp_le_i32_e32 vcc, 0x260, v16
	v_mfma_f32_32x32x16_bf16 v[18:33], v[46:49], v[80:83], 0
	v_mfma_f32_32x32x16_bf16 v[18:33], v[42:45], v[84:87], v[18:33]
	v_mfma_f32_32x32x16_bf16 v[18:33], v[38:41], v[88:91], v[18:33]
	v_mfma_f32_32x32x16_bf16 v[18:33], v[34:37], v[92:95], v[18:33]
	s_nop 11
	v_max_f32_e32 v18, 0, v18
	v_max_f32_e32 v19, 0, v19
	v_fma_f32 v18, v143, v18, 0
	v_fmac_f32_e32 v18, v142, v19
	v_max_f32_e32 v19, 0, v20
	v_fmac_f32_e32 v18, v141, v19
	v_max_f32_e32 v19, 0, v21
	v_fmac_f32_e32 v18, v140, v19
	v_max_f32_e32 v19, 0, v22
	v_fmac_f32_e32 v18, v139, v19
	v_max_f32_e32 v19, 0, v23
	v_fmac_f32_e32 v18, v138, v19
	v_max_f32_e32 v19, 0, v24
	v_fmac_f32_e32 v18, v137, v19
	v_max_f32_e32 v19, 0, v25
	v_fmac_f32_e32 v18, v136, v19
	v_max_f32_e32 v19, 0, v26
	v_fmac_f32_e32 v18, v135, v19
	v_max_f32_e32 v19, 0, v27
	v_fmac_f32_e32 v18, v134, v19
	v_max_f32_e32 v19, 0, v28
	v_fmac_f32_e32 v18, v133, v19
	v_max_f32_e32 v19, 0, v29
	v_fmac_f32_e32 v18, v132, v19
	v_max_f32_e32 v19, 0, v30
	v_fmac_f32_e32 v18, v131, v19
	v_max_f32_e32 v19, 0, v31
	v_fmac_f32_e32 v18, v130, v19
	v_max_f32_e32 v19, 0, v32
	v_fmac_f32_e32 v18, v129, v19
	v_max_f32_e32 v19, 0, v33
	v_fmac_f32_e32 v18, v128, v19
	v_ashrrev_i32_e32 v19, 31, v18
	v_bitop3_b32 v18, v19, v18, s8 bitop3:0x36
	v_cndmask_b32_e32 v164, 0, v18, vcc
	s_cmp_lt_u32 s0, 0x280
	s_cbranch_scc1 .Lix_z20
.Lix_b20:
	s_cmp_lt_u32 s0, 0x2e0
	s_cbranch_scc1 .Lix_w20
	s_add_u32 m0, s1, 0x3000
	s_nop 0
	global_load_lds_dwordx4 v112, s[22:23]
	s_add_u32 s22, s22, 0x1e800
	s_addc_u32 s23, s23, 0
	s_add_u32 m0, s1, 0x3400
	s_nop 0
	global_load_lds_dwordx4 v113, s[22:23]
	s_add_u32 s22, s22, 0x1e800
	s_addc_u32 s23, s23, 0
	s_add_u32 m0, s1, 0x3800
	s_nop 0
	global_load_lds_dwordx4 v112, s[22:23]
	s_add_u32 s22, s22, 0x1e800
	s_addc_u32 s23, s23, 0
	s_add_u32 m0, s1, 0x3c00
	s_nop 0
	global_load_lds_dwordx4 v113, s[22:23]
	s_add_u32 s22, s22, 0x1e800
	s_addc_u32 s23, s23, 0
	s_waitcnt vmcnt(8)
	s_branch .Lix_r20

; #define MFMA(a, b, c) __builtin_amdgcn_mfma_f32_32x32x16_bf16((a), (b), (c), 0, 0, 0)
; DI void indexer_phase(const u16* __restrict__ P, unsigned* __restrict__ mask) {
;     ...
;         const u16* kp = P + (brow + 32 * kb + r32) * 7808 + 3584 + 8 * hi;
; #pragma unroll
;         for (int s = 0; s < 4; ++s) { const bf16x8 bk = *(const bf16x8*)(kp + 16 * s); a = MFMA(aq[s], bk, a); }
.Lix_r20:
	s_cmp_lt_u32 s0, 0x2a0
	s_cbranch_scc1 .Lix_n20
	ds_read_b128 v[80:83], v114 offset:4096
	ds_read_b128 v[84:87], v115 offset:4096
	ds_read_b128 v[88:91], v116 offset:4096
	ds_read_b128 v[92:95], v117 offset:4096
	s_waitcnt lgkmcnt(4)
	s_branch .Lix_m20

; #define MFMA(a, b, c) __builtin_amdgcn_mfma_f32_32x32x16_bf16((a), (b), (c), 0, 0, 0)
; DI unsigned ordkey(float f) { const unsigned b = __float_as_uint(f); return b ^ ((unsigned)((int)b >> 31) | 0x80000000u); }
; DI void indexer_phase(const u16* __restrict__ P, unsigned* __restrict__ mask) {
;     ...
;     for (int kb = 0; kb < 64; ++kb) {
;       unsigned u = 0u;
;       if (kb <= kbmax) {
;         f32x16 a;
; #pragma unroll
;         for (int r = 0; r < 16; ++r) a[r] = 0.f;
;         const u16* kp = P + (brow + 32 * kb + r32) * 7808 + 3584 + 8 * hi;
; #pragma unroll
;         for (int s = 0; s < 4; ++s) { const bf16x8 bk = *(const bf16x8*)(kp + 16 * s); a = MFMA(aq[s], bk, a); }
;         float v = 0.f;
; #pragma unroll
;         for (int i = 0; i < 16; ++i) v = fmaf(wv[i], fmaxf(a[i], 0.f), v);
;         u = (32 * kb + r32 <= tme) ? ordkey(v) : 0u;
;       }
;       sc[kb] = u;
.Lix_m20:
	v_cmp_le_i32_e32 vcc, 0x280, v16
	v_mfma_f32_32x32x16_bf16 v[18:33], v[46:49], v[64:67], 0
	v_mfma_f32_32x32x16_bf16 v[18:33], v[42:45], v[68:71], v[18:33]
	v_mfma_f32_32x32x16_bf16 v[18:33], v[38:41], v[72:75], v[18:33]
	v_mfma_f32_32x32x16_bf16 v[18:33], v[34:37], v[76:79], v[18:33]
	s_nop 11
	v_max_f32_e32 v18, 0, v18
	v_max_f32_e32 v19, 0, v19
	v_fma_f32 v18, v143, v18, 0
	v_fmac_f32_e32 v18, v142, v19
	v_max_f32_e32 v19, 0, v20
	v_fmac_f32_e32 v18, v141, v19
	v_max_f32_e32 v19, 0, v21
	v_fmac_f32_e32 v18, v140, v19
	v_max_f32_e32 v19, 0, v22
	v_fmac_f32_e32 v18, v139, v19
	v_max_f32_e32 v19, 0, v23
	v_fmac_f32_e32 v18, v138, v19
	v_max_f32_e32 v19, 0, v24
	v_fmac_f32_e32 v18, v137, v19
	v_max_f32_e32 v19, 0, v25
	v_fmac_f32_e32 v18, v136, v19
	v_max_f32_e32 v19, 0, v26
	v_fmac_f32_e32 v18, v135, v19
	v_max_f32_e32 v19, 0, v27
	v_fmac_f32_e32 v18, v134, v19
	v_max_f32_e32 v19, 0, v28
	v_fmac_f32_e32 v18, v133, v19
	v_max_f32_e32 v19, 0, v29
	v_fmac_f32_e32 v18, v132, v19
	v_max_f32_e32 v19, 0, v30
	v_fmac_f32_e32 v18, v131, v19
	v_max_f32_e32 v19, 0, v31
	v_fmac_f32_e32 v18, v130, v19
	v_max_f32_e32 v19, 0, v32
	v_fmac_f32_e32 v18, v129, v19
	v_max_f32_e32 v19, 0, v33
	v_fmac_f32_e32 v18, v128, v19
	v_ashrrev_i32_e32 v19, 31, v18
	v_bitop3_b32 v18, v19, v18, s8 bitop3:0x36
	v_cndmask_b32_e32 v163, 0, v18, vcc
	s_cmp_lt_u32 s0, 0x2a0
	s_cbranch_scc1 .Lix_z21
.Lix_b21:
	s_cmp_lt_u32 s0, 0x300
	s_cbranch_scc1 .Lix_w21
	s_add_u32 m0, s1, 0
	s_nop 0
	global_load_lds_dwordx4 v112, s[22:23]
	s_add_u32 s22, s22, 0x1e800
	s_addc_u32 s23, s23, 0
	s_add_u32 m0, s1, 0x400
	s_nop 0
	global_load_lds_dwordx4 v113, s[22:23]
	s_add_u32 s22, s22, 0x1e800
	s_addc_u32 s23, s23, 0
	s_add_u32 m0, s1, 0x800
	s_nop 0
	global_load_lds_dwordx4 v112, s[22:23]
	s_add_u32 s22, s22, 0x1e800
	s_addc_u32 s23, s23, 0
	s_add_u32 m0, s1, 0xc00
	s_nop 0
	global_load_lds_dwordx4 v113, s[22:23]
	s_add_u32 s22, s22, 0x1e800
	s_addc_u32 s23, s23, 0
	s_waitcnt vmcnt(8)
	s_branch .Lix_r21

; #define MFMA(a, b, c) __builtin_amdgcn_mfma_f32_32x32x16_bf16((a), (b), (c), 0, 0, 0)
; DI void indexer_phase(const u16* __restrict__ P, unsigned* __restrict__ mask) {
;     ...
;         const u16* kp = P + (brow + 32 * kb + r32) * 7808 + 3584 + 8 * hi;
; #pragma unroll
;         for (int s = 0; s < 4; ++s) { const bf16x8 bk = *(const bf16x8*)(kp + 16 * s); a = MFMA(aq[s], bk, a); }
.Lix_r21:
	s_cmp_lt_u32 s0, 0x2c0
	s_cbranch_scc1 .Lix_n21
	ds_read_b128 v[64:67], v114 offset:8192
	ds_read_b128 v[68:71], v115 offset:8192
	ds_read_b128 v[72:75], v116 offset:8192
	ds_read_b128 v[76:79], v117 offset:8192
	s_waitcnt lgkmcnt(4)
	s_branch .Lix_m21

; #define MFMA(a, b, c) __builtin_amdgcn_mfma_f32_32x32x16_bf16((a), (b), (c), 0, 0, 0)
; DI unsigned ordkey(float f) { const unsigned b = __float_as_uint(f); return b ^ ((unsigned)((int)b >> 31) | 0x80000000u); }
; DI void indexer_phase(const u16* __restrict__ P, unsigned* __restrict__ mask) {
;     ...
;     for (int kb = 0; kb < 64; ++kb) {
;       unsigned u = 0u;
;       if (kb <= kbmax) {
;         f32x16 a;
; #pragma unroll
;         for (int r = 0; r < 16; ++r) a[r] = 0.f;
;         const u16* kp = P + (brow + 32 * kb + r32) * 7808 + 3584 + 8 * hi;
; #pragma unroll
;         for (int s = 0; s < 4; ++s) { const bf16x8 bk = *(const bf16x8*)(kp + 16 * s); a = MFMA(aq[s], bk, a); }
;         float v = 0.f;
; #pragma unroll
;         for (int i = 0; i < 16; ++i) v = fmaf(wv[i], fmaxf(a[i], 0.f), v);
;         u = (32 * kb + r32 <= tme) ? ordkey(v) : 0u;
;       }
;       sc[kb] = u;
.Lix_m21:
	v_cmp_le_i32_e32 vcc, 0x2a0, v16
	v_mfma_f32_32x32x16_bf16 v[18:33], v[46:49], v[80:83], 0
	v_mfma_f32_32x32x16_bf16 v[18:33], v[42:45], v[84:87], v[18:33]
	v_mfma_f32_32x32x16_bf16 v[18:33], v[38:41], v[88:91], v[18:33]
	v_mfma_f32_32x32x16_bf16 v[18:33], v[34:37], v[92:95], v[18:33]
	s_nop 11
	v_max_f32_e32 v18, 0, v18
	v_max_f32_e32 v19, 0, v19
	v_fma_f32 v18, v143, v18, 0
	v_fmac_f32_e32 v18, v142, v19
	v_max_f32_e32 v19, 0, v20
	v_fmac_f32_e32 v18, v141, v19
	v_max_f32_e32 v19, 0, v21
	v_fmac_f32_e32 v18, v140, v19
	v_max_f32_e32 v19, 0, v22
	v_fmac_f32_e32 v18, v139, v19
	v_max_f32_e32 v19, 0, v23
	v_fmac_f32_e32 v18, v138, v19
	v_max_f32_e32 v19, 0, v24
	v_fmac_f32_e32 v18, v137, v19
	v_max_f32_e32 v19, 0, v25
	v_fmac_f32_e32 v18, v136, v19
	v_max_f32_e32 v19, 0, v26
	v_fmac_f32_e32 v18, v135, v19
	v_max_f32_e32 v19, 0, v27
	v_fmac_f32_e32 v18, v134, v19
	v_max_f32_e32 v19, 0, v28
	v_fmac_f32_e32 v18, v133, v19
	v_max_f32_e32 v19, 0, v29
	v_fmac_f32_e32 v18, v132, v19
	v_max_f32_e32 v19, 0, v30
	v_fmac_f32_e32 v18, v131, v19
	v_max_f32_e32 v19, 0, v31
	v_fmac_f32_e32 v18, v130, v19
	v_max_f32_e32 v19, 0, v32
	v_fmac_f32_e32 v18, v129, v19
	v_max_f32_e32 v19, 0, v33
	v_fmac_f32_e32 v18, v128, v19
	v_ashrrev_i32_e32 v19, 31, v18
	v_bitop3_b32 v18, v19, v18, s8 bitop3:0x36
	v_cndmask_b32_e32 v166, 0, v18, vcc
	s_cmp_lt_u32 s0, 0x2c0
	s_cbranch_scc1 .Lix_z22
.Lix_b22:
	s_cmp_lt_u32 s0, 0x320
	s_cbranch_scc1 .Lix_w22
	s_add_u32 m0, s1, 0x1000
	s_nop 0
	global_load_lds_dwordx4 v112, s[22:23]
	s_add_u32 s22, s22, 0x1e800
	s_addc_u32 s23, s23, 0
	s_add_u32 m0, s1, 0x1400
	s_nop 0
	global_load_lds_dwordx4 v113, s[22:23]
	s_add_u32 s22, s22, 0x1e800
	s_addc_u32 s23, s23, 0
	s_add_u32 m0, s1, 0x1800
	s_nop 0
	global_load_lds_dwordx4 v112, s[22:23]
	s_add_u32 s22, s22, 0x1e800
	s_addc_u32 s23, s23, 0
	s_add_u32 m0, s1, 0x1c00
	s_nop 0
	global_load_lds_dwordx4 v113, s[22:23]
	s_add_u32 s22, s22, 0x1e800
	s_addc_u32 s23, s23, 0
	s_waitcnt vmcnt(8)
	s_branch .Lix_r22

; #define MFMA(a, b, c) __builtin_amdgcn_mfma_f32_32x32x16_bf16((a), (b), (c), 0, 0, 0)
; DI void indexer_phase(const u16* __restrict__ P, unsigned* __restrict__ mask) {
;     ...
;         const u16* kp = P + (brow + 32 * kb + r32) * 7808 + 3584 + 8 * hi;
; #pragma unroll
;         for (int s = 0; s < 4; ++s) { const bf16x8 bk = *(const bf16x8*)(kp + 16 * s); a = MFMA(aq[s], bk, a); }
.Lix_r22:
	s_cmp_lt_u32 s0, 0x2e0
	s_cbranch_scc1 .Lix_n22
	ds_read_b128 v[80:83], v114 offset:12288
	ds_read_b128 v[84:87], v115 offset:12288
	ds_read_b128 v[88:91], v116 offset:12288
	ds_read_b128 v[92:95], v117 offset:12288
	s_waitcnt lgkmcnt(4)
	s_branch .Lix_m22

; #define MFMA(a, b, c) __builtin_amdgcn_mfma_f32_32x32x16_bf16((a), (b), (c), 0, 0, 0)
; DI unsigned ordkey(float f) { const unsigned b = __float_as_uint(f); return b ^ ((unsigned)((int)b >> 31) | 0x80000000u); }
; DI void indexer_phase(const u16* __restrict__ P, unsigned* __restrict__ mask) {
;     ...
;     for (int kb = 0; kb < 64; ++kb) {
;       unsigned u = 0u;
;       if (kb <= kbmax) {
;         f32x16 a;
; #pragma unroll
;         for (int r = 0; r < 16; ++r) a[r] = 0.f;
;         const u16* kp = P + (brow + 32 * kb + r32) * 7808 + 3584 + 8 * hi;
; #pragma unroll
;         for (int s = 0; s < 4; ++s) { const bf16x8 bk = *(const bf16x8*)(kp + 16 * s); a = MFMA(aq[s], bk, a); }
;         float v = 0.f;
; #pragma unroll
;         for (int i = 0; i < 16; ++i) v = fmaf(wv[i], fmaxf(a[i], 0.f), v);
;         u = (32 * kb + r32 <= tme) ? ordkey(v) : 0u;
;       }
;       sc[kb] = u;
.Lix_m22:
	v_cmp_le_i32_e32 vcc, 0x2c0, v16
	v_mfma_f32_32x32x16_bf16 v[18:33], v[46:49], v[64:67], 0
	v_mfma_f32_32x32x16_bf16 v[18:33], v[42:45], v[68:71], v[18:33]
	v_mfma_f32_32x32x16_bf16 v[18:33], v[38:41], v[72:75], v[18:33]
	v_mfma_f32_32x32x16_bf16 v[18:33], v[34:37], v[76:79], v[18:33]
	s_nop 11
	v_max_f32_e32 v18, 0, v18
	v_max_f32_e32 v19, 0, v19
	v_fma_f32 v18, v143, v18, 0
	v_fmac_f32_e32 v18, v142, v19
	v_max_f32_e32 v19, 0, v20
	v_fmac_f32_e32 v18, v141, v19
	v_max_f32_e32 v19, 0, v21
	v_fmac_f32_e32 v18, v140, v19
	v_max_f32_e32 v19, 0, v22
	v_fmac_f32_e32 v18, v139, v19
	v_max_f32_e32 v19, 0, v23
	v_fmac_f32_e32 v18, v138, v19
	v_max_f32_e32 v19, 0, v24
	v_fmac_f32_e32 v18, v137, v19
	v_max_f32_e32 v19, 0, v25
	v_fmac_f32_e32 v18, v136, v19
	v_max_f32_e32 v19, 0, v26
	v_fmac_f32_e32 v18, v135, v19
	v_max_f32_e32 v19, 0, v27
	v_fmac_f32_e32 v18, v134, v19
	v_max_f32_e32 v19, 0, v28
	v_fmac_f32_e32 v18, v133, v19
	v_max_f32_e32 v19, 0, v29
	v_fmac_f32_e32 v18, v132, v19
	v_max_f32_e32 v19, 0, v30
	v_fmac_f32_e32 v18, v131, v19
	v_max_f32_e32 v19, 0, v31
	v_fmac_f32_e32 v18, v130, v19
	v_max_f32_e32 v19, 0, v32
	v_fmac_f32_e32 v18, v129, v19
	v_max_f32_e32 v19, 0, v33
	v_fmac_f32_e32 v18, v128, v19
	v_ashrrev_i32_e32 v19, 31, v18
	v_bitop3_b32 v18, v19, v18, s8 bitop3:0x36
	v_cndmask_b32_e32 v165, 0, v18, vcc
	s_cmp_lt_u32 s0, 0x2e0
	s_cbranch_scc1 .Lix_z23
.Lix_b23:
	s_cmp_lt_u32 s0, 0x340
	s_cbranch_scc1 .Lix_w23
	s_add_u32 m0, s1, 0x2000
	s_nop 0
	global_load_lds_dwordx4 v112, s[22:23]
	s_add_u32 s22, s22, 0x1e800
	s_addc_u32 s23, s23, 0
	s_add_u32 m0, s1, 0x2400
	s_nop 0
	global_load_lds_dwordx4 v113, s[22:23]
	s_add_u32 s22, s22, 0x1e800
	s_addc_u32 s23, s23, 0
	s_add_u32 m0, s1, 0x2800
	s_nop 0
	global_load_lds_dwordx4 v112, s[22:23]
	s_add_u32 s22, s22, 0x1e800
	s_addc_u32 s23, s23, 0
	s_add_u32 m0, s1, 0x2c00
	s_nop 0
	global_load_lds_dwordx4 v113, s[22:23]
	s_add_u32 s22, s22, 0x1e800
	s_addc_u32 s23, s23, 0
	s_waitcnt vmcnt(8)
	s_branch .Lix_r23

; #define MFMA(a, b, c) __builtin_amdgcn_mfma_f32_32x32x16_bf16((a), (b), (c), 0, 0, 0)
; DI void indexer_phase(const u16* __restrict__ P, unsigned* __restrict__ mask) {
;     ...
;         const u16* kp = P + (brow + 32 * kb + r32) * 7808 + 3584 + 8 * hi;
; #pragma unroll
;         for (int s = 0; s < 4; ++s) { const bf16x8 bk = *(const bf16x8*)(kp + 16 * s); a = MFMA(aq[s], bk, a); }
.Lix_r23:
	s_cmp_lt_u32 s0, 0x300
	s_cbranch_scc1 .Lix_n23
	ds_read_b128 v[64:67], v114
	ds_read_b128 v[68:71], v115
	ds_read_b128 v[72:75], v116
	ds_read_b128 v[76:79], v117
	s_waitcnt lgkmcnt(4)
	s_branch .Lix_m23

; #define MFMA(a, b, c) __builtin_amdgcn_mfma_f32_32x32x16_bf16((a), (b), (c), 0, 0, 0)
; DI unsigned ordkey(float f) { const unsigned b = __float_as_uint(f); return b ^ ((unsigned)((int)b >> 31) | 0x80000000u); }
; DI void indexer_phase(const u16* __restrict__ P, unsigned* __restrict__ mask) {
;     ...
;     for (int kb = 0; kb < 64; ++kb) {
;       unsigned u = 0u;
;       if (kb <= kbmax) {
;         f32x16 a;
; #pragma unroll
;         for (int r = 0; r < 16; ++r) a[r] = 0.f;
;         const u16* kp = P + (brow + 32 * kb + r32) * 7808 + 3584 + 8 * hi;
; #pragma unroll
;         for (int s = 0; s < 4; ++s) { const bf16x8 bk = *(const bf16x8*)(kp + 16 * s); a = MFMA(aq[s], bk, a); }
;         float v = 0.f;
; #pragma unroll
;         for (int i = 0; i < 16; ++i) v = fmaf(wv[i], fmaxf(a[i], 0.f), v);
;         u = (32 * kb + r32 <= tme) ? ordkey(v) : 0u;
;       }
;       sc[kb] = u;
.Lix_m23:
	v_cmp_le_i32_e32 vcc, 0x2e0, v16
	v_mfma_f32_32x32x16_bf16 v[18:33], v[46:49], v[80:83], 0
	v_mfma_f32_32x32x16_bf16 v[18:33], v[42:45], v[84:87], v[18:33]
	v_mfma_f32_32x32x16_bf16 v[18:33], v[38:41], v[88:91], v[18:33]
	v_mfma_f32_32x32x16_bf16 v[18:33], v[34:37], v[92:95], v[18:33]
	s_nop 11
	v_max_f32_e32 v18, 0, v18
	v_max_f32_e32 v19, 0, v19
	v_fma_f32 v18, v143, v18, 0
	v_fmac_f32_e32 v18, v142, v19
	v_max_f32_e32 v19, 0, v20
	v_fmac_f32_e32 v18, v141, v19
	v_max_f32_e32 v19, 0, v21
	v_fmac_f32_e32 v18, v140, v19
	v_max_f32_e32 v19, 0, v22
	v_fmac_f32_e32 v18, v139, v19
	v_max_f32_e32 v19, 0, v23
	v_fmac_f32_e32 v18, v138, v19
	v_max_f32_e32 v19, 0, v24
	v_fmac_f32_e32 v18, v137, v19
	v_max_f32_e32 v19, 0, v25
	v_fmac_f32_e32 v18, v136, v19
	v_max_f32_e32 v19, 0, v26
	v_fmac_f32_e32 v18, v135, v19
	v_max_f32_e32 v19, 0, v27
	v_fmac_f32_e32 v18, v134, v19
	v_max_f32_e32 v19, 0, v28
	v_fmac_f32_e32 v18, v133, v19
	v_max_f32_e32 v19, 0, v29
	v_fmac_f32_e32 v18, v132, v19
	v_max_f32_e32 v19, 0, v30
	v_fmac_f32_e32 v18, v131, v19
	v_max_f32_e32 v19, 0, v31
	v_fmac_f32_e32 v18, v130, v19
	v_max_f32_e32 v19, 0, v32
	v_fmac_f32_e32 v18, v129, v19
	v_max_f32_e32 v19, 0, v33
	v_fmac_f32_e32 v18, v128, v19
	v_ashrrev_i32_e32 v19, 31, v18
	v_bitop3_b32 v18, v19, v18, s8 bitop3:0x36
	v_cndmask_b32_e32 v168, 0, v18, vcc
	s_cmp_lt_u32 s0, 0x300
	s_cbranch_scc1 .Lix_z24
.Lix_b24:
	s_cmp_lt_u32 s0, 0x360
	s_cbranch_scc1 .Lix_w24
	s_add_u32 m0, s1, 0x3000
	s_nop 0
	global_load_lds_dwordx4 v112, s[22:23]
	s_add_u32 s22, s22, 0x1e800
	s_addc_u32 s23, s23, 0
	s_add_u32 m0, s1, 0x3400
	s_nop 0
	global_load_lds_dwordx4 v113, s[22:23]
	s_add_u32 s22, s22, 0x1e800
	s_addc_u32 s23, s23, 0
	s_add_u32 m0, s1, 0x3800
	s_nop 0
	global_load_lds_dwordx4 v112, s[22:23]
	s_add_u32 s22, s22, 0x1e800
	s_addc_u32 s23, s23, 0
	s_add_u32 m0, s1, 0x3c00
	s_nop 0
	global_load_lds_dwordx4 v113, s[22:23]
	s_add_u32 s22, s22, 0x1e800
	s_addc_u32 s23, s23, 0
	s_waitcnt vmcnt(8)
	s_branch .Lix_r24

; #define MFMA(a, b, c) __builtin_amdgcn_mfma_f32_32x32x16_bf16((a), (b), (c), 0, 0, 0)
; DI void indexer_phase(const u16* __restrict__ P, unsigned* __restrict__ mask) {
;     ...
;         const u16* kp = P + (brow + 32 * kb + r32) * 7808 + 3584 + 8 * hi;
; #pragma unroll
;         for (int s = 0; s < 4; ++s) { const bf16x8 bk = *(const bf16x8*)(kp + 16 * s); a = MFMA(aq[s], bk, a); }
.Lix_r24:
	s_cmp_lt_u32 s0, 0x320
	s_cbranch_scc1 .Lix_n24
	ds_read_b128 v[80:83], v114 offset:4096
	ds_read_b128 v[84:87], v115 offset:4096
	ds_read_b128 v[88:91], v116 offset:4096
	ds_read_b128 v[92:95], v117 offset:4096
	s_waitcnt lgkmcnt(4)
	s_branch .Lix_m24

; #define MFMA(a, b, c) __builtin_amdgcn_mfma_f32_32x32x16_bf16((a), (b), (c), 0, 0, 0)
; DI unsigned ordkey(float f) { const unsigned b = __float_as_uint(f); return b ^ ((unsigned)((int)b >> 31) | 0x80000000u); }
; DI void indexer_phase(const u16* __restrict__ P, unsigned* __restrict__ mask) {
;     ...
;     for (int kb = 0; kb < 64; ++kb) {
;       unsigned u = 0u;
;       if (kb <= kbmax) {
;         f32x16 a;
; #pragma unroll
;         for (int r = 0; r < 16; ++r) a[r] = 0.f;
;         const u16* kp = P + (brow + 32 * kb + r32) * 7808 + 3584 + 8 * hi;
; #pragma unroll
;         for (int s = 0; s < 4; ++s) { const bf16x8 bk = *(const bf16x8*)(kp + 16 * s); a = MFMA(aq[s], bk, a); }
;         float v = 0.f;
; #pragma unroll
;         for (int i = 0; i < 16; ++i) v = fmaf(wv[i], fmaxf(a[i], 0.f), v);
;         u = (32 * kb + r32 <= tme) ? ordkey(v) : 0u;
;       }
;       sc[kb] = u;
.Lix_m24:
	v_cmp_le_i32_e32 vcc, 0x300, v16
	v_mfma_f32_32x32x16_bf16 v[18:33], v[46:49], v[64:67], 0
	v_mfma_f32_32x32x16_bf16 v[18:33], v[42:45], v[68:71], v[18:33]
	v_mfma_f32_32x32x16_bf16 v[18:33], v[38:41], v[72:75], v[18:33]
	v_mfma_f32_32x32x16_bf16 v[18:33], v[34:37], v[76:79], v[18:33]
	s_nop 11
	v_max_f32_e32 v18, 0, v18
	v_max_f32_e32 v19, 0, v19
	v_fma_f32 v18, v143, v18, 0
	v_fmac_f32_e32 v18, v142, v19
	v_max_f32_e32 v19, 0, v20
	v_fmac_f32_e32 v18, v141, v19
	v_max_f32_e32 v19, 0, v21
	v_fmac_f32_e32 v18, v140, v19
	v_max_f32_e32 v19, 0, v22
	v_fmac_f32_e32 v18, v139, v19
	v_max_f32_e32 v19, 0, v23
	v_fmac_f32_e32 v18, v138, v19
	v_max_f32_e32 v19, 0, v24
	v_fmac_f32_e32 v18, v137, v19
	v_max_f32_e32 v19, 0, v25
	v_fmac_f32_e32 v18, v136, v19
	v_max_f32_e32 v19, 0, v26
	v_fmac_f32_e32 v18, v135, v19
	v_max_f32_e32 v19, 0, v27
	v_fmac_f32_e32 v18, v134, v19
	v_max_f32_e32 v19, 0, v28
	v_fmac_f32_e32 v18, v133, v19
	v_max_f32_e32 v19, 0, v29
	v_fmac_f32_e32 v18, v132, v19
	v_max_f32_e32 v19, 0, v30
	v_fmac_f32_e32 v18, v131, v19
	v_max_f32_e32 v19, 0, v31
	v_fmac_f32_e32 v18, v130, v19
	v_max_f32_e32 v19, 0, v32
	v_fmac_f32_e32 v18, v129, v19
	v_max_f32_e32 v19, 0, v33
	v_fmac_f32_e32 v18, v128, v19
	v_ashrrev_i32_e32 v19, 31, v18
	v_bitop3_b32 v18, v19, v18, s8 bitop3:0x36
	v_cndmask_b32_e32 v167, 0, v18, vcc
	s_cmp_lt_u32 s0, 0x320
	s_cbranch_scc1 .Lix_z25
.Lix_b25:
	s_cmp_lt_u32 s0, 0x380
	s_cbranch_scc1 .Lix_w25
	s_add_u32 m0, s1, 0
	s_nop 0
	global_load_lds_dwordx4 v112, s[22:23]
	s_add_u32 s22, s22, 0x1e800
	s_addc_u32 s23, s23, 0
	s_add_u32 m0, s1, 0x400
	s_nop 0
	global_load_lds_dwordx4 v113, s[22:23]
	s_add_u32 s22, s22, 0x1e800
	s_addc_u32 s23, s23, 0
	s_add_u32 m0, s1, 0x800
	s_nop 0
	global_load_lds_dwordx4 v112, s[22:23]
	s_add_u32 s22, s22, 0x1e800
	s_addc_u32 s23, s23, 0
	s_add_u32 m0, s1, 0xc00
	s_nop 0
	global_load_lds_dwordx4 v113, s[22:23]
	s_add_u32 s22, s22, 0x1e800
	s_addc_u32 s23, s23, 0
	s_waitcnt vmcnt(8)
	s_branch .Lix_r25

; #define MFMA(a, b, c) __builtin_amdgcn_mfma_f32_32x32x16_bf16((a), (b), (c), 0, 0, 0)
; DI void indexer_phase(const u16* __restrict__ P, unsigned* __restrict__ mask) {
;     ...
;         const u16* kp = P + (brow + 32 * kb + r32) * 7808 + 3584 + 8 * hi;
; #pragma unroll
;         for (int s = 0; s < 4; ++s) { const bf16x8 bk = *(const bf16x8*)(kp + 16 * s); a = MFMA(aq[s], bk, a); }
.Lix_r25:
	s_cmp_lt_u32 s0, 0x340
	s_cbranch_scc1 .Lix_n25
	ds_read_b128 v[64:67], v114 offset:8192
	ds_read_b128 v[68:71], v115 offset:8192
	ds_read_b128 v[72:75], v116 offset:8192
	ds_read_b128 v[76:79], v117 offset:8192
	s_waitcnt lgkmcnt(4)
	s_branch .Lix_m25

; #define MFMA(a, b, c) __builtin_amdgcn_mfma_f32_32x32x16_bf16((a), (b), (c), 0, 0, 0)
; DI unsigned ordkey(float f) { const unsigned b = __float_as_uint(f); return b ^ ((unsigned)((int)b >> 31) | 0x80000000u); }
; DI void indexer_phase(const u16* __restrict__ P, unsigned* __restrict__ mask) {
;     ...
;     for (int kb = 0; kb < 64; ++kb) {
;       unsigned u = 0u;
;       if (kb <= kbmax) {
;         f32x16 a;
; #pragma unroll
;         for (int r = 0; r < 16; ++r) a[r] = 0.f;
;         const u16* kp = P + (brow + 32 * kb + r32) * 7808 + 3584 + 8 * hi;
; #pragma unroll
;         for (int s = 0; s < 4; ++s) { const bf16x8 bk = *(const bf16x8*)(kp + 16 * s); a = MFMA(aq[s], bk, a); }
;         float v = 0.f;
; #pragma unroll
;         for (int i = 0; i < 16; ++i) v = fmaf(wv[i], fmaxf(a[i], 0.f), v);
;         u = (32 * kb + r32 <= tme) ? ordkey(v) : 0u;
;       }
;       sc[kb] = u;
.Lix_m25:
	v_cmp_le_i32_e32 vcc, 0x320, v16
	v_mfma_f32_32x32x16_bf16 v[18:33], v[46:49], v[80:83], 0
	v_mfma_f32_32x32x16_bf16 v[18:33], v[42:45], v[84:87], v[18:33]
	v_mfma_f32_32x32x16_bf16 v[18:33], v[38:41], v[88:91], v[18:33]
	v_mfma_f32_32x32x16_bf16 v[18:33], v[34:37], v[92:95], v[18:33]
	s_nop 11
	v_max_f32_e32 v18, 0, v18
	v_max_f32_e32 v19, 0, v19
	v_fma_f32 v18, v143, v18, 0
	v_fmac_f32_e32 v18, v142, v19
	v_max_f32_e32 v19, 0, v20
	v_fmac_f32_e32 v18, v141, v19
	v_max_f32_e32 v19, 0, v21
	v_fmac_f32_e32 v18, v140, v19
	v_max_f32_e32 v19, 0, v22
	v_fmac_f32_e32 v18, v139, v19
	v_max_f32_e32 v19, 0, v23
	v_fmac_f32_e32 v18, v138, v19
	v_max_f32_e32 v19, 0, v24
	v_fmac_f32_e32 v18, v137, v19
	v_max_f32_e32 v19, 0, v25
	v_fmac_f32_e32 v18, v136, v19
	v_max_f32_e32 v19, 0, v26
	v_fmac_f32_e32 v18, v135, v19
	v_max_f32_e32 v19, 0, v27
	v_fmac_f32_e32 v18, v134, v19
	v_max_f32_e32 v19, 0, v28
	v_fmac_f32_e32 v18, v133, v19
	v_max_f32_e32 v19, 0, v29
	v_fmac_f32_e32 v18, v132, v19
	v_max_f32_e32 v19, 0, v30
	v_fmac_f32_e32 v18, v131, v19
	v_max_f32_e32 v19, 0, v31
	v_fmac_f32_e32 v18, v130, v19
	v_max_f32_e32 v19, 0, v32
	v_fmac_f32_e32 v18, v129, v19
	v_max_f32_e32 v19, 0, v33
	v_fmac_f32_e32 v18, v128, v19
	v_ashrrev_i32_e32 v19, 31, v18
	v_bitop3_b32 v18, v19, v18, s8 bitop3:0x36
	v_cndmask_b32_e32 v170, 0, v18, vcc
	s_cmp_lt_u32 s0, 0x340
	s_cbranch_scc1 .Lix_z26
.Lix_b26:
	s_cmp_lt_u32 s0, 0x3a0
	s_cbranch_scc1 .Lix_w26
	s_add_u32 m0, s1, 0x1000
	s_nop 0
	global_load_lds_dwordx4 v112, s[22:23]
	s_add_u32 s22, s22, 0x1e800
	s_addc_u32 s23, s23, 0
	s_add_u32 m0, s1, 0x1400
	s_nop 0
	global_load_lds_dwordx4 v113, s[22:23]
	s_add_u32 s22, s22, 0x1e800
	s_addc_u32 s23, s23, 0
	s_add_u32 m0, s1, 0x1800
	s_nop 0
	global_load_lds_dwordx4 v112, s[22:23]
	s_add_u32 s22, s22, 0x1e800
	s_addc_u32 s23, s23, 0
	s_add_u32 m0, s1, 0x1c00
	s_nop 0
	global_load_lds_dwordx4 v113, s[22:23]
	s_add_u32 s22, s22, 0x1e800
	s_addc_u32 s23, s23, 0
	s_waitcnt vmcnt(8)
	s_branch .Lix_r26

; #define MFMA(a, b, c) __builtin_amdgcn_mfma_f32_32x32x16_bf16((a), (b), (c), 0, 0, 0)
; DI void indexer_phase(const u16* __restrict__ P, unsigned* __restrict__ mask) {
;     ...
;         const u16* kp = P + (brow + 32 * kb + r32) * 7808 + 3584 + 8 * hi;
; #pragma unroll
;         for (int s = 0; s < 4; ++s) { const bf16x8 bk = *(const bf16x8*)(kp + 16 * s); a = MFMA(aq[s], bk, a); }
.Lix_r26:
	s_cmp_lt_u32 s0, 0x360
	s_cbranch_scc1 .Lix_n26
	ds_read_b128 v[80:83], v114 offset:12288
	ds_read_b128 v[84:87], v115 offset:12288
	ds_read_b128 v[88:91], v116 offset:12288
	ds_read_b128 v[92:95], v117 offset:12288
	s_waitcnt lgkmcnt(4)
	s_branch .Lix_m26

; #define MFMA(a, b, c) __builtin_amdgcn_mfma_f32_32x32x16_bf16((a), (b), (c), 0, 0, 0)
; DI unsigned ordkey(float f) { const unsigned b = __float_as_uint(f); return b ^ ((unsigned)((int)b >> 31) | 0x80000000u); }
; DI void indexer_phase(const u16* __restrict__ P, unsigned* __restrict__ mask) {
;     ...
;     for (int kb = 0; kb < 64; ++kb) {
;       unsigned u = 0u;
;       if (kb <= kbmax) {
;         f32x16 a;
; #pragma unroll
;         for (int r = 0; r < 16; ++r) a[r] = 0.f;
;         const u16* kp = P + (brow + 32 * kb + r32) * 7808 + 3584 + 8 * hi;
; #pragma unroll
;         for (int s = 0; s < 4; ++s) { const bf16x8 bk = *(const bf16x8*)(kp + 16 * s); a = MFMA(aq[s], bk, a); }
;         float v = 0.f;
; #pragma unroll
;         for (int i = 0; i < 16; ++i) v = fmaf(wv[i], fmaxf(a[i], 0.f), v);
;         u = (32 * kb + r32 <= tme) ? ordkey(v) : 0u;
;       }
;       sc[kb] = u;
.Lix_m26:
	v_cmp_le_i32_e32 vcc, 0x340, v16
	v_mfma_f32_32x32x16_bf16 v[18:33], v[46:49], v[64:67], 0
	v_mfma_f32_32x32x16_bf16 v[18:33], v[42:45], v[68:71], v[18:33]
	v_mfma_f32_32x32x16_bf16 v[18:33], v[38:41], v[72:75], v[18:33]
	v_mfma_f32_32x32x16_bf16 v[18:33], v[34:37], v[76:79], v[18:33]
	s_nop 11
	v_max_f32_e32 v18, 0, v18
	v_max_f32_e32 v19, 0, v19
	v_fma_f32 v18, v143, v18, 0
	v_fmac_f32_e32 v18, v142, v19
	v_max_f32_e32 v19, 0, v20
	v_fmac_f32_e32 v18, v141, v19
	v_max_f32_e32 v19, 0, v21
	v_fmac_f32_e32 v18, v140, v19
	v_max_f32_e32 v19, 0, v22
	v_fmac_f32_e32 v18, v139, v19
	v_max_f32_e32 v19, 0, v23
	v_fmac_f32_e32 v18, v138, v19
	v_max_f32_e32 v19, 0, v24
	v_fmac_f32_e32 v18, v137, v19
	v_max_f32_e32 v19, 0, v25
	v_fmac_f32_e32 v18, v136, v19
	v_max_f32_e32 v19, 0, v26
	v_fmac_f32_e32 v18, v135, v19
	v_max_f32_e32 v19, 0, v27
	v_fmac_f32_e32 v18, v134, v19
	v_max_f32_e32 v19, 0, v28
	v_fmac_f32_e32 v18, v133, v19
	v_max_f32_e32 v19, 0, v29
	v_fmac_f32_e32 v18, v132, v19
	v_max_f32_e32 v19, 0, v30
	v_fmac_f32_e32 v18, v131, v19
	v_max_f32_e32 v19, 0, v31
	v_fmac_f32_e32 v18, v130, v19
	v_max_f32_e32 v19, 0, v32
	v_fmac_f32_e32 v18, v129, v19
	v_max_f32_e32 v19, 0, v33
	v_fmac_f32_e32 v18, v128, v19
	v_ashrrev_i32_e32 v19, 31, v18
	v_bitop3_b32 v18, v19, v18, s8 bitop3:0x36
	v_cndmask_b32_e32 v169, 0, v18, vcc
	s_cmp_lt_u32 s0, 0x360
	s_cbranch_scc1 .Lix_z27
.Lix_b27:
	s_cmp_lt_u32 s0, 0x3c0
	s_cbranch_scc1 .Lix_w27
	s_add_u32 m0, s1, 0x2000
	s_nop 0
	global_load_lds_dwordx4 v112, s[22:23]
	s_add_u32 s22, s22, 0x1e800
	s_addc_u32 s23, s23, 0
	s_add_u32 m0, s1, 0x2400
	s_nop 0
	global_load_lds_dwordx4 v113, s[22:23]
	s_add_u32 s22, s22, 0x1e800
	s_addc_u32 s23, s23, 0
	s_add_u32 m0, s1, 0x2800
	s_nop 0
	global_load_lds_dwordx4 v112, s[22:23]
	s_add_u32 s22, s22, 0x1e800
	s_addc_u32 s23, s23, 0
	s_add_u32 m0, s1, 0x2c00
	s_nop 0
	global_load_lds_dwordx4 v113, s[22:23]
	s_add_u32 s22, s22, 0x1e800
	s_addc_u32 s23, s23, 0
	s_waitcnt vmcnt(8)
	s_branch .Lix_r27

; #define MFMA(a, b, c) __builtin_amdgcn_mfma_f32_32x32x16_bf16((a), (b), (c), 0, 0, 0)
; DI void indexer_phase(const u16* __restrict__ P, unsigned* __restrict__ mask) {
;     ...
;         const u16* kp = P + (brow + 32 * kb + r32) * 7808 + 3584 + 8 * hi;
; #pragma unroll
;         for (int s = 0; s < 4; ++s) { const bf16x8 bk = *(const bf16x8*)(kp + 16 * s); a = MFMA(aq[s], bk, a); }
.Lix_r27:
	s_cmp_lt_u32 s0, 0x380
	s_cbranch_scc1 .Lix_n27
	ds_read_b128 v[64:67], v114
	ds_read_b128 v[68:71], v115
	ds_read_b128 v[72:75], v116
	ds_read_b128 v[76:79], v117
	s_waitcnt lgkmcnt(4)
	s_branch .Lix_m27

; #define MFMA(a, b, c) __builtin_amdgcn_mfma_f32_32x32x16_bf16((a), (b), (c), 0, 0, 0)
; DI unsigned ordkey(float f) { const unsigned b = __float_as_uint(f); return b ^ ((unsigned)((int)b >> 31) | 0x80000000u); }
; DI void indexer_phase(const u16* __restrict__ P, unsigned* __restrict__ mask) {
;     ...
;     for (int kb = 0; kb < 64; ++kb) {
;       unsigned u = 0u;
;       if (kb <= kbmax) {
;         f32x16 a;
; #pragma unroll
;         for (int r = 0; r < 16; ++r) a[r] = 0.f;
;         const u16* kp = P + (brow + 32 * kb + r32) * 7808 + 3584 + 8 * hi;
; #pragma unroll
;         for (int s = 0; s < 4; ++s) { const bf16x8 bk = *(const bf16x8*)(kp + 16 * s); a = MFMA(aq[s], bk, a); }
;         float v = 0.f;
; #pragma unroll
;         for (int i = 0; i < 16; ++i) v = fmaf(wv[i], fmaxf(a[i], 0.f), v);
;         u = (32 * kb + r32 <= tme) ? ordkey(v) : 0u;
;       }
;       sc[kb] = u;
.Lix_m27:
	v_cmp_le_i32_e32 vcc, 0x360, v16
	v_mfma_f32_32x32x16_bf16 v[18:33], v[46:49], v[80:83], 0
	v_mfma_f32_32x32x16_bf16 v[18:33], v[42:45], v[84:87], v[18:33]
	v_mfma_f32_32x32x16_bf16 v[18:33], v[38:41], v[88:91], v[18:33]
	v_mfma_f32_32x32x16_bf16 v[18:33], v[34:37], v[92:95], v[18:33]
	s_nop 11
	v_max_f32_e32 v18, 0, v18
	v_max_f32_e32 v19, 0, v19
	v_fma_f32 v18, v143, v18, 0
	v_fmac_f32_e32 v18, v142, v19
	v_max_f32_e32 v19, 0, v20
	v_fmac_f32_e32 v18, v141, v19
	v_max_f32_e32 v19, 0, v21
	v_fmac_f32_e32 v18, v140, v19
	v_max_f32_e32 v19, 0, v22
	v_fmac_f32_e32 v18, v139, v19
	v_max_f32_e32 v19, 0, v23
	v_fmac_f32_e32 v18, v138, v19
	v_max_f32_e32 v19, 0, v24
	v_fmac_f32_e32 v18, v137, v19
	v_max_f32_e32 v19, 0, v25
	v_fmac_f32_e32 v18, v136, v19
	v_max_f32_e32 v19, 0, v26
	v_fmac_f32_e32 v18, v135, v19
	v_max_f32_e32 v19, 0, v27
	v_fmac_f32_e32 v18, v134, v19
	v_max_f32_e32 v19, 0, v28
	v_fmac_f32_e32 v18, v133, v19
	v_max_f32_e32 v19, 0, v29
	v_fmac_f32_e32 v18, v132, v19
	v_max_f32_e32 v19, 0, v30
	v_fmac_f32_e32 v18, v131, v19
	v_max_f32_e32 v19, 0, v31
	v_fmac_f32_e32 v18, v130, v19
	v_max_f32_e32 v19, 0, v32
	v_fmac_f32_e32 v18, v129, v19
	v_max_f32_e32 v19, 0, v33
	v_fmac_f32_e32 v18, v128, v19
	v_ashrrev_i32_e32 v19, 31, v18
	v_bitop3_b32 v18, v19, v18, s8 bitop3:0x36
	v_cndmask_b32_e32 v172, 0, v18, vcc
	s_cmp_lt_u32 s0, 0x380
	s_cbranch_scc1 .Lix_z28
.Lix_b28:
	s_cmp_lt_u32 s0, 0x3e0
	s_cbranch_scc1 .Lix_w28
	s_add_u32 m0, s1, 0x3000
	s_nop 0
	global_load_lds_dwordx4 v112, s[22:23]
	s_add_u32 s22, s22, 0x1e800
	s_addc_u32 s23, s23, 0
	s_add_u32 m0, s1, 0x3400
	s_nop 0
	global_load_lds_dwordx4 v113, s[22:23]
	s_add_u32 s22, s22, 0x1e800
	s_addc_u32 s23, s23, 0
	s_add_u32 m0, s1, 0x3800
	s_nop 0
	global_load_lds_dwordx4 v112, s[22:23]
	s_add_u32 s22, s22, 0x1e800
	s_addc_u32 s23, s23, 0
	s_add_u32 m0, s1, 0x3c00
	s_nop 0
	global_load_lds_dwordx4 v113, s[22:23]
	s_add_u32 s22, s22, 0x1e800
	s_addc_u32 s23, s23, 0
	s_waitcnt vmcnt(8)
	s_branch .Lix_r28

; #define MFMA(a, b, c) __builtin_amdgcn_mfma_f32_32x32x16_bf16((a), (b), (c), 0, 0, 0)
; DI void indexer_phase(const u16* __restrict__ P, unsigned* __restrict__ mask) {
;     ...
;         const u16* kp = P + (brow + 32 * kb + r32) * 7808 + 3584 + 8 * hi;
; #pragma unroll
;         for (int s = 0; s < 4; ++s) { const bf16x8 bk = *(const bf16x8*)(kp + 16 * s); a = MFMA(aq[s], bk, a); }
.Lix_r28:
	s_cmp_lt_u32 s0, 0x3a0
	s_cbranch_scc1 .Lix_n28
	ds_read_b128 v[80:83], v114 offset:4096
	ds_read_b128 v[84:87], v115 offset:4096
	ds_read_b128 v[88:91], v116 offset:4096
	ds_read_b128 v[92:95], v117 offset:4096
	s_waitcnt lgkmcnt(4)
	s_branch .Lix_m28

; #define MFMA(a, b, c) __builtin_amdgcn_mfma_f32_32x32x16_bf16((a), (b), (c), 0, 0, 0)
; DI unsigned ordkey(float f) { const unsigned b = __float_as_uint(f); return b ^ ((unsigned)((int)b >> 31) | 0x80000000u); }
; DI void indexer_phase(const u16* __restrict__ P, unsigned* __restrict__ mask) {
;     ...
;     for (int kb = 0; kb < 64; ++kb) {
;       unsigned u = 0u;
;       if (kb <= kbmax) {
;         f32x16 a;
; #pragma unroll
;         for (int r = 0; r < 16; ++r) a[r] = 0.f;
;         const u16* kp = P + (brow + 32 * kb + r32) * 7808 + 3584 + 8 * hi;
; #pragma unroll
;         for (int s = 0; s < 4; ++s) { const bf16x8 bk = *(const bf16x8*)(kp + 16 * s); a = MFMA(aq[s], bk, a); }
;         float v = 0.f;
; #pragma unroll
;         for (int i = 0; i < 16; ++i) v = fmaf(wv[i], fmaxf(a[i], 0.f), v);
;         u = (32 * kb + r32 <= tme) ? ordkey(v) : 0u;
;       }
;       sc[kb] = u;
.Lix_m28:
	v_cmp_le_i32_e32 vcc, 0x380, v16
	v_mfma_f32_32x32x16_bf16 v[18:33], v[46:49], v[64:67], 0
	v_mfma_f32_32x32x16_bf16 v[18:33], v[42:45], v[68:71], v[18:33]
	v_mfma_f32_32x32x16_bf16 v[18:33], v[38:41], v[72:75], v[18:33]
	v_mfma_f32_32x32x16_bf16 v[18:33], v[34:37], v[76:79], v[18:33]
	s_nop 11
	v_max_f32_e32 v18, 0, v18
	v_max_f32_e32 v19, 0, v19
	v_fma_f32 v18, v143, v18, 0
	v_fmac_f32_e32 v18, v142, v19
	v_max_f32_e32 v19, 0, v20
	v_fmac_f32_e32 v18, v141, v19
	v_max_f32_e32 v19, 0, v21
	v_fmac_f32_e32 v18, v140, v19
	v_max_f32_e32 v19, 0, v22
	v_fmac_f32_e32 v18, v139, v19
	v_max_f32_e32 v19, 0, v23
	v_fmac_f32_e32 v18, v138, v19
	v_max_f32_e32 v19, 0, v24
	v_fmac_f32_e32 v18, v137, v19
	v_max_f32_e32 v19, 0, v25
	v_fmac_f32_e32 v18, v136, v19
	v_max_f32_e32 v19, 0, v26
	v_fmac_f32_e32 v18, v135, v19
	v_max_f32_e32 v19, 0, v27
	v_fmac_f32_e32 v18, v134, v19
	v_max_f32_e32 v19, 0, v28
	v_fmac_f32_e32 v18, v133, v19
	v_max_f32_e32 v19, 0, v29
	v_fmac_f32_e32 v18, v132, v19
	v_max_f32_e32 v19, 0, v30
	v_fmac_f32_e32 v18, v131, v19
	v_max_f32_e32 v19, 0, v31
	v_fmac_f32_e32 v18, v130, v19
	v_max_f32_e32 v19, 0, v32
	v_fmac_f32_e32 v18, v129, v19
	v_max_f32_e32 v19, 0, v33
	v_fmac_f32_e32 v18, v128, v19
	v_ashrrev_i32_e32 v19, 31, v18
	v_bitop3_b32 v18, v19, v18, s8 bitop3:0x36
	v_cndmask_b32_e32 v171, 0, v18, vcc
	s_cmp_lt_u32 s0, 0x3a0
	s_cbranch_scc1 .Lix_z29
.Lix_b29:
	s_cmp_lt_u32 s0, 0x400
	s_cbranch_scc1 .Lix_w29
	s_add_u32 m0, s1, 0
	s_nop 0
	global_load_lds_dwordx4 v112, s[22:23]
	s_add_u32 s22, s22, 0x1e800
	s_addc_u32 s23, s23, 0
	s_add_u32 m0, s1, 0x400
	s_nop 0
	global_load_lds_dwordx4 v113, s[22:23]
	s_add_u32 s22, s22, 0x1e800
	s_addc_u32 s23, s23, 0
	s_add_u32 m0, s1, 0x800
	s_nop 0
	global_load_lds_dwordx4 v112, s[22:23]
	s_add_u32 s22, s22, 0x1e800
	s_addc_u32 s23, s23, 0
	s_add_u32 m0, s1, 0xc00
	s_nop 0
	global_load_lds_dwordx4 v113, s[22:23]
	s_add_u32 s22, s22, 0x1e800
	s_addc_u32 s23, s23, 0
	s_waitcnt vmcnt(8)
	s_branch .Lix_r29

; #define MFMA(a, b, c) __builtin_amdgcn_mfma_f32_32x32x16_bf16((a), (b), (c), 0, 0, 0)
; DI void indexer_phase(const u16* __restrict__ P, unsigned* __restrict__ mask) {
;     ...
;         const u16* kp = P + (brow + 32 * kb + r32) * 7808 + 3584 + 8 * hi;
; #pragma unroll
;         for (int s = 0; s < 4; ++s) { const bf16x8 bk = *(const bf16x8*)(kp + 16 * s); a = MFMA(aq[s], bk, a); }
.Lix_r29:
	s_cmp_lt_u32 s0, 0x3c0
	s_cbranch_scc1 .Lix_n29
	ds_read_b128 v[64:67], v114 offset:8192
	ds_read_b128 v[68:71], v115 offset:8192
	ds_read_b128 v[72:75], v116 offset:8192
	ds_read_b128 v[76:79], v117 offset:8192
	s_waitcnt lgkmcnt(4)
	s_branch .Lix_m29

; #define MFMA(a, b, c) __builtin_amdgcn_mfma_f32_32x32x16_bf16((a), (b), (c), 0, 0, 0)
; DI unsigned ordkey(float f) { const unsigned b = __float_as_uint(f); return b ^ ((unsigned)((int)b >> 31) | 0x80000000u); }
; DI void indexer_phase(const u16* __restrict__ P, unsigned* __restrict__ mask) {
;     ...
;     for (int kb = 0; kb < 64; ++kb) {
;       unsigned u = 0u;
;       if (kb <= kbmax) {
;         f32x16 a;
; #pragma unroll
;         for (int r = 0; r < 16; ++r) a[r] = 0.f;
;         const u16* kp = P + (brow + 32 * kb + r32) * 7808 + 3584 + 8 * hi;
; #pragma unroll
;         for (int s = 0; s < 4; ++s) { const bf16x8 bk = *(const bf16x8*)(kp + 16 * s); a = MFMA(aq[s], bk, a); }
;         float v = 0.f;
; #pragma unroll
;         for (int i = 0; i < 16; ++i) v = fmaf(wv[i], fmaxf(a[i], 0.f), v);
;         u = (32 * kb + r32 <= tme) ? ordkey(v) : 0u;
;       }
;       sc[kb] = u;
.Lix_m29:
	v_cmp_le_i32_e32 vcc, 0x3a0, v16
	v_mfma_f32_32x32x16_bf16 v[18:33], v[46:49], v[80:83], 0
	v_mfma_f32_32x32x16_bf16 v[18:33], v[42:45], v[84:87], v[18:33]
	v_mfma_f32_32x32x16_bf16 v[18:33], v[38:41], v[88:91], v[18:33]
	v_mfma_f32_32x32x16_bf16 v[18:33], v[34:37], v[92:95], v[18:33]
	s_nop 11
	v_max_f32_e32 v18, 0, v18
	v_max_f32_e32 v19, 0, v19
	v_fma_f32 v18, v143, v18, 0
	v_fmac_f32_e32 v18, v142, v19
	v_max_f32_e32 v19, 0, v20
	v_fmac_f32_e32 v18, v141, v19
	v_max_f32_e32 v19, 0, v21
	v_fmac_f32_e32 v18, v140, v19
	v_max_f32_e32 v19, 0, v22
	v_fmac_f32_e32 v18, v139, v19
	v_max_f32_e32 v19, 0, v23
	v_fmac_f32_e32 v18, v138, v19
	v_max_f32_e32 v19, 0, v24
	v_fmac_f32_e32 v18, v137, v19
	v_max_f32_e32 v19, 0, v25
	v_fmac_f32_e32 v18, v136, v19
	v_max_f32_e32 v19, 0, v26
	v_fmac_f32_e32 v18, v135, v19
	v_max_f32_e32 v19, 0, v27
	v_fmac_f32_e32 v18, v134, v19
	v_max_f32_e32 v19, 0, v28
	v_fmac_f32_e32 v18, v133, v19
	v_max_f32_e32 v19, 0, v29
	v_fmac_f32_e32 v18, v132, v19
	v_max_f32_e32 v19, 0, v30
	v_fmac_f32_e32 v18, v131, v19
	v_max_f32_e32 v19, 0, v31
	v_fmac_f32_e32 v18, v130, v19
	v_max_f32_e32 v19, 0, v32
	v_fmac_f32_e32 v18, v129, v19
	v_max_f32_e32 v19, 0, v33
	v_fmac_f32_e32 v18, v128, v19
	v_ashrrev_i32_e32 v19, 31, v18
	v_bitop3_b32 v18, v19, v18, s8 bitop3:0x36
	v_cndmask_b32_e32 v174, 0, v18, vcc
	s_cmp_lt_u32 s0, 0x3c0
	s_cbranch_scc1 .Lix_z30
.Lix_b30:
	s_cmp_lt_u32 s0, 0x420
	s_cbranch_scc1 .Lix_w30
	s_add_u32 m0, s1, 0x1000
	s_nop 0
	global_load_lds_dwordx4 v112, s[22:23]
	s_add_u32 s22, s22, 0x1e800
	s_addc_u32 s23, s23, 0
	s_add_u32 m0, s1, 0x1400
	s_nop 0
	global_load_lds_dwordx4 v113, s[22:23]
	s_add_u32 s22, s22, 0x1e800
	s_addc_u32 s23, s23, 0
	s_add_u32 m0, s1, 0x1800
	s_nop 0
	global_load_lds_dwordx4 v112, s[22:23]
	s_add_u32 s22, s22, 0x1e800
	s_addc_u32 s23, s23, 0
	s_add_u32 m0, s1, 0x1c00
	s_nop 0
	global_load_lds_dwordx4 v113, s[22:23]
	s_add_u32 s22, s22, 0x1e800
	s_addc_u32 s23, s23, 0
	s_waitcnt vmcnt(8)
	s_branch .Lix_r30

; #define MFMA(a, b, c) __builtin_amdgcn_mfma_f32_32x32x16_bf16((a), (b), (c), 0, 0, 0)
; DI void indexer_phase(const u16* __restrict__ P, unsigned* __restrict__ mask) {
;     ...
;         const u16* kp = P + (brow + 32 * kb + r32) * 7808 + 3584 + 8 * hi;
; #pragma unroll
;         for (int s = 0; s < 4; ++s) { const bf16x8 bk = *(const bf16x8*)(kp + 16 * s); a = MFMA(aq[s], bk, a); }
.Lix_r30:
	s_cmp_lt_u32 s0, 0x3e0
	s_cbranch_scc1 .Lix_n30
	ds_read_b128 v[80:83], v114 offset:12288
	ds_read_b128 v[84:87], v115 offset:12288
	ds_read_b128 v[88:91], v116 offset:12288
	ds_read_b128 v[92:95], v117 offset:12288
	s_waitcnt lgkmcnt(4)
	s_branch .Lix_m30

; #define MFMA(a, b, c) __builtin_amdgcn_mfma_f32_32x32x16_bf16((a), (b), (c), 0, 0, 0)
; DI unsigned ordkey(float f) { const unsigned b = __float_as_uint(f); return b ^ ((unsigned)((int)b >> 31) | 0x80000000u); }
; DI void indexer_phase(const u16* __restrict__ P, unsigned* __restrict__ mask) {
;     ...
;     for (int kb = 0; kb < 64; ++kb) {
;       unsigned u = 0u;
;       if (kb <= kbmax) {
;         f32x16 a;
; #pragma unroll
;         for (int r = 0; r < 16; ++r) a[r] = 0.f;
;         const u16* kp = P + (brow + 32 * kb + r32) * 7808 + 3584 + 8 * hi;
; #pragma unroll
;         for (int s = 0; s < 4; ++s) { const bf16x8 bk = *(const bf16x8*)(kp + 16 * s); a = MFMA(aq[s], bk, a); }
;         float v = 0.f;
; #pragma unroll
;         for (int i = 0; i < 16; ++i) v = fmaf(wv[i], fmaxf(a[i], 0.f), v);
;         u = (32 * kb + r32 <= tme) ? ordkey(v) : 0u;
;       }
;       sc[kb] = u;
.Lix_m30:
	v_cmp_le_i32_e32 vcc, 0x3c0, v16
	v_mfma_f32_32x32x16_bf16 v[18:33], v[46:49], v[64:67], 0
	v_mfma_f32_32x32x16_bf16 v[18:33], v[42:45], v[68:71], v[18:33]
	v_mfma_f32_32x32x16_bf16 v[18:33], v[38:41], v[72:75], v[18:33]
	v_mfma_f32_32x32x16_bf16 v[18:33], v[34:37], v[76:79], v[18:33]
	s_nop 11
	v_max_f32_e32 v18, 0, v18
	v_max_f32_e32 v19, 0, v19
	v_fma_f32 v18, v143, v18, 0
	v_fmac_f32_e32 v18, v142, v19
	v_max_f32_e32 v19, 0, v20
	v_fmac_f32_e32 v18, v141, v19
	v_max_f32_e32 v19, 0, v21
	v_fmac_f32_e32 v18, v140, v19
	v_max_f32_e32 v19, 0, v22
	v_fmac_f32_e32 v18, v139, v19
	v_max_f32_e32 v19, 0, v23
	v_fmac_f32_e32 v18, v138, v19
	v_max_f32_e32 v19, 0, v24
	v_fmac_f32_e32 v18, v137, v19
	v_max_f32_e32 v19, 0, v25
	v_fmac_f32_e32 v18, v136, v19
	v_max_f32_e32 v19, 0, v26
	v_fmac_f32_e32 v18, v135, v19
	v_max_f32_e32 v19, 0, v27
	v_fmac_f32_e32 v18, v134, v19
	v_max_f32_e32 v19, 0, v28
	v_fmac_f32_e32 v18, v133, v19
	v_max_f32_e32 v19, 0, v29
	v_fmac_f32_e32 v18, v132, v19
	v_max_f32_e32 v19, 0, v30
	v_fmac_f32_e32 v18, v131, v19
	v_max_f32_e32 v19, 0, v31
	v_fmac_f32_e32 v18, v130, v19
	v_max_f32_e32 v19, 0, v32
	v_fmac_f32_e32 v18, v129, v19
	v_max_f32_e32 v19, 0, v33
	v_fmac_f32_e32 v18, v128, v19
	v_ashrrev_i32_e32 v19, 31, v18
	v_bitop3_b32 v18, v19, v18, s8 bitop3:0x36
	v_cndmask_b32_e32 v173, 0, v18, vcc
	s_cmp_lt_u32 s0, 0x3e0
	s_cbranch_scc1 .Lix_z31
.Lix_b31:
	s_cmp_lt_u32 s0, 0x440
	s_cbranch_scc1 .Lix_w31
	s_add_u32 m0, s1, 0x2000
	s_nop 0
	global_load_lds_dwordx4 v112, s[22:23]
	s_add_u32 s22, s22, 0x1e800
	s_addc_u32 s23, s23, 0
	s_add_u32 m0, s1, 0x2400
	s_nop 0
	global_load_lds_dwordx4 v113, s[22:23]
	s_add_u32 s22, s22, 0x1e800
	s_addc_u32 s23, s23, 0
	s_add_u32 m0, s1, 0x2800
	s_nop 0
	global_load_lds_dwordx4 v112, s[22:23]
	s_add_u32 s22, s22, 0x1e800
	s_addc_u32 s23, s23, 0
	s_add_u32 m0, s1, 0x2c00
	s_nop 0
	global_load_lds_dwordx4 v113, s[22:23]
	s_add_u32 s22, s22, 0x1e800
	s_addc_u32 s23, s23, 0
	s_waitcnt vmcnt(8)
	s_branch .Lix_r31

; #define MFMA(a, b, c) __builtin_amdgcn_mfma_f32_32x32x16_bf16((a), (b), (c), 0, 0, 0)
; DI void indexer_phase(const u16* __restrict__ P, unsigned* __restrict__ mask) {
;     ...
;         const u16* kp = P + (brow + 32 * kb + r32) * 7808 + 3584 + 8 * hi;
; #pragma unroll
;         for (int s = 0; s < 4; ++s) { const bf16x8 bk = *(const bf16x8*)(kp + 16 * s); a = MFMA(aq[s], bk, a); }
.Lix_r31:
	s_cmp_lt_u32 s0, 0x400
	s_cbranch_scc1 .Lix_n31
	ds_read_b128 v[64:67], v114
	ds_read_b128 v[68:71], v115
	ds_read_b128 v[72:75], v116
	ds_read_b128 v[76:79], v117
	s_waitcnt lgkmcnt(4)
	s_branch .Lix_m31

; #define MFMA(a, b, c) __builtin_amdgcn_mfma_f32_32x32x16_bf16((a), (b), (c), 0, 0, 0)
; DI unsigned ordkey(float f) { const unsigned b = __float_as_uint(f); return b ^ ((unsigned)((int)b >> 31) | 0x80000000u); }
; DI void indexer_phase(const u16* __restrict__ P, unsigned* __restrict__ mask) {
;     ...
;     for (int kb = 0; kb < 64; ++kb) {
;       unsigned u = 0u;
;       if (kb <= kbmax) {
;         f32x16 a;
; #pragma unroll
;         for (int r = 0; r < 16; ++r) a[r] = 0.f;
;         const u16* kp = P + (brow + 32 * kb + r32) * 7808 + 3584 + 8 * hi;
; #pragma unroll
;         for (int s = 0; s < 4; ++s) { const bf16x8 bk = *(const bf16x8*)(kp + 16 * s); a = MFMA(aq[s], bk, a); }
;         float v = 0.f;
; #pragma unroll
;         for (int i = 0; i < 16; ++i) v = fmaf(wv[i], fmaxf(a[i], 0.f), v);
;         u = (32 * kb + r32 <= tme) ? ordkey(v) : 0u;
;       }
;       sc[kb] = u;
.Lix_m31:
	v_cmp_le_i32_e32 vcc, 0x3e0, v16
	v_mfma_f32_32x32x16_bf16 v[18:33], v[46:49], v[80:83], 0
	v_mfma_f32_32x32x16_bf16 v[18:33], v[42:45], v[84:87], v[18:33]
	v_mfma_f32_32x32x16_bf16 v[18:33], v[38:41], v[88:91], v[18:33]
	v_mfma_f32_32x32x16_bf16 v[18:33], v[34:37], v[92:95], v[18:33]
	s_nop 11
	v_max_f32_e32 v18, 0, v18
	v_max_f32_e32 v19, 0, v19
	v_fma_f32 v18, v143, v18, 0
	v_fmac_f32_e32 v18, v142, v19
	v_max_f32_e32 v19, 0, v20
	v_fmac_f32_e32 v18, v141, v19
	v_max_f32_e32 v19, 0, v21
	v_fmac_f32_e32 v18, v140, v19
	v_max_f32_e32 v19, 0, v22
	v_fmac_f32_e32 v18, v139, v19
	v_max_f32_e32 v19, 0, v23
	v_fmac_f32_e32 v18, v138, v19
	v_max_f32_e32 v19, 0, v24
	v_fmac_f32_e32 v18, v137, v19
	v_max_f32_e32 v19, 0, v25
	v_fmac_f32_e32 v18, v136, v19
	v_max_f32_e32 v19, 0, v26
	v_fmac_f32_e32 v18, v135, v19
	v_max_f32_e32 v19, 0, v27
	v_fmac_f32_e32 v18, v134, v19
	v_max_f32_e32 v19, 0, v28
	v_fmac_f32_e32 v18, v133, v19
	v_max_f32_e32 v19, 0, v29
	v_fmac_f32_e32 v18, v132, v19
	v_max_f32_e32 v19, 0, v30
	v_fmac_f32_e32 v18, v131, v19
	v_max_f32_e32 v19, 0, v31
	v_fmac_f32_e32 v18, v130, v19
	v_max_f32_e32 v19, 0, v32
	v_fmac_f32_e32 v18, v129, v19
	v_max_f32_e32 v19, 0, v33
	v_fmac_f32_e32 v18, v128, v19
	v_ashrrev_i32_e32 v19, 31, v18
	v_bitop3_b32 v18, v19, v18, s8 bitop3:0x36
	v_cndmask_b32_e32 v182, 0, v18, vcc
	s_cmp_lt_u32 s0, 0x400
	s_cbranch_scc1 .Lix_z32
.Lix_b32:
	s_cmp_lt_u32 s0, 0x460
	s_cbranch_scc1 .Lix_w32
	s_add_u32 m0, s1, 0x3000
	s_nop 0
	global_load_lds_dwordx4 v112, s[22:23]
	s_add_u32 s22, s22, 0x1e800
	s_addc_u32 s23, s23, 0
	s_add_u32 m0, s1, 0x3400
	s_nop 0
	global_load_lds_dwordx4 v113, s[22:23]
	s_add_u32 s22, s22, 0x1e800
	s_addc_u32 s23, s23, 0
	s_add_u32 m0, s1, 0x3800
	s_nop 0
	global_load_lds_dwordx4 v112, s[22:23]
	s_add_u32 s22, s22, 0x1e800
	s_addc_u32 s23, s23, 0
	s_add_u32 m0, s1, 0x3c00
	s_nop 0
	global_load_lds_dwordx4 v113, s[22:23]
	s_add_u32 s22, s22, 0x1e800
	s_addc_u32 s23, s23, 0
	s_waitcnt vmcnt(8)
	s_branch .Lix_r32

; #define MFMA(a, b, c) __builtin_amdgcn_mfma_f32_32x32x16_bf16((a), (b), (c), 0, 0, 0)
; DI void indexer_phase(const u16* __restrict__ P, unsigned* __restrict__ mask) {
;     ...
;         const u16* kp = P + (brow + 32 * kb + r32) * 7808 + 3584 + 8 * hi;
; #pragma unroll
;         for (int s = 0; s < 4; ++s) { const bf16x8 bk = *(const bf16x8*)(kp + 16 * s); a = MFMA(aq[s], bk, a); }
.Lix_r32:
	s_cmp_lt_u32 s0, 0x420
	s_cbranch_scc1 .Lix_n32
	ds_read_b128 v[80:83], v114 offset:4096
	ds_read_b128 v[84:87], v115 offset:4096
	ds_read_b128 v[88:91], v116 offset:4096
	ds_read_b128 v[92:95], v117 offset:4096
	s_waitcnt lgkmcnt(4)
	s_branch .Lix_m32

; #define MFMA(a, b, c) __builtin_amdgcn_mfma_f32_32x32x16_bf16((a), (b), (c), 0, 0, 0)
; DI unsigned ordkey(float f) { const unsigned b = __float_as_uint(f); return b ^ ((unsigned)((int)b >> 31) | 0x80000000u); }
; DI void indexer_phase(const u16* __restrict__ P, unsigned* __restrict__ mask) {
;     ...
;     for (int kb = 0; kb < 64; ++kb) {
;       unsigned u = 0u;
;       if (kb <= kbmax) {
;         f32x16 a;
; #pragma unroll
;         for (int r = 0; r < 16; ++r) a[r] = 0.f;
;         const u16* kp = P + (brow + 32 * kb + r32) * 7808 + 3584 + 8 * hi;
; #pragma unroll
;         for (int s = 0; s < 4; ++s) { const bf16x8 bk = *(const bf16x8*)(kp + 16 * s); a = MFMA(aq[s], bk, a); }
;         float v = 0.f;
; #pragma unroll
;         for (int i = 0; i < 16; ++i) v = fmaf(wv[i], fmaxf(a[i], 0.f), v);
;         u = (32 * kb + r32 <= tme) ? ordkey(v) : 0u;
;       }
;       sc[kb] = u;
.Lix_m32:
	v_cmp_le_i32_e32 vcc, 0x400, v16
	v_mfma_f32_32x32x16_bf16 v[18:33], v[46:49], v[64:67], 0
	v_mfma_f32_32x32x16_bf16 v[18:33], v[42:45], v[68:71], v[18:33]
	v_mfma_f32_32x32x16_bf16 v[18:33], v[38:41], v[72:75], v[18:33]
	v_mfma_f32_32x32x16_bf16 v[18:33], v[34:37], v[76:79], v[18:33]
	s_nop 11
	v_max_f32_e32 v18, 0, v18
	v_max_f32_e32 v19, 0, v19
	v_fma_f32 v18, v143, v18, 0
	v_fmac_f32_e32 v18, v142, v19
	v_max_f32_e32 v19, 0, v20
	v_fmac_f32_e32 v18, v141, v19
	v_max_f32_e32 v19, 0, v21
	v_fmac_f32_e32 v18, v140, v19
	v_max_f32_e32 v19, 0, v22
	v_fmac_f32_e32 v18, v139, v19
	v_max_f32_e32 v19, 0, v23
	v_fmac_f32_e32 v18, v138, v19
	v_max_f32_e32 v19, 0, v24
	v_fmac_f32_e32 v18, v137, v19
	v_max_f32_e32 v19, 0, v25
	v_fmac_f32_e32 v18, v136, v19
	v_max_f32_e32 v19, 0, v26
	v_fmac_f32_e32 v18, v135, v19
	v_max_f32_e32 v19, 0, v27
	v_fmac_f32_e32 v18, v134, v19
	v_max_f32_e32 v19, 0, v28
	v_fmac_f32_e32 v18, v133, v19
	v_max_f32_e32 v19, 0, v29
	v_fmac_f32_e32 v18, v132, v19
	v_max_f32_e32 v19, 0, v30
	v_fmac_f32_e32 v18, v131, v19
	v_max_f32_e32 v19, 0, v31
	v_fmac_f32_e32 v18, v130, v19
	v_max_f32_e32 v19, 0, v32
	v_fmac_f32_e32 v18, v129, v19
	v_max_f32_e32 v19, 0, v33
	v_fmac_f32_e32 v18, v128, v19
	v_ashrrev_i32_e32 v19, 31, v18
	v_bitop3_b32 v18, v19, v18, s8 bitop3:0x36
	v_cndmask_b32_e32 v175, 0, v18, vcc
	s_cmp_lt_u32 s0, 0x420
	s_cbranch_scc1 .Lix_z33
.Lix_b33:
	s_cmp_lt_u32 s0, 0x480
	s_cbranch_scc1 .Lix_w33
	s_add_u32 m0, s1, 0
	s_nop 0
	global_load_lds_dwordx4 v112, s[22:23]
	s_add_u32 s22, s22, 0x1e800
	s_addc_u32 s23, s23, 0
	s_add_u32 m0, s1, 0x400
	s_nop 0
	global_load_lds_dwordx4 v113, s[22:23]
	s_add_u32 s22, s22, 0x1e800
	s_addc_u32 s23, s23, 0
	s_add_u32 m0, s1, 0x800
	s_nop 0
	global_load_lds_dwordx4 v112, s[22:23]
	s_add_u32 s22, s22, 0x1e800
	s_addc_u32 s23, s23, 0
	s_add_u32 m0, s1, 0xc00
	s_nop 0
	global_load_lds_dwordx4 v113, s[22:23]
	s_add_u32 s22, s22, 0x1e800
	s_addc_u32 s23, s23, 0
	s_waitcnt vmcnt(8)
	s_branch .Lix_r33

; #define MFMA(a, b, c) __builtin_amdgcn_mfma_f32_32x32x16_bf16((a), (b), (c), 0, 0, 0)
; DI void indexer_phase(const u16* __restrict__ P, unsigned* __restrict__ mask) {
;     ...
;         const u16* kp = P + (brow + 32 * kb + r32) * 7808 + 3584 + 8 * hi;
; #pragma unroll
;         for (int s = 0; s < 4; ++s) { const bf16x8 bk = *(const bf16x8*)(kp + 16 * s); a = MFMA(aq[s], bk, a); }
.Lix_r33:
	s_cmp_lt_u32 s0, 0x440
	s_cbranch_scc1 .Lix_n33
	ds_read_b128 v[64:67], v114 offset:8192
	ds_read_b128 v[68:71], v115 offset:8192
	ds_read_b128 v[72:75], v116 offset:8192
	ds_read_b128 v[76:79], v117 offset:8192
	s_waitcnt lgkmcnt(4)
	s_branch .Lix_m33

; #define MFMA(a, b, c) __builtin_amdgcn_mfma_f32_32x32x16_bf16((a), (b), (c), 0, 0, 0)
; DI unsigned ordkey(float f) { const unsigned b = __float_as_uint(f); return b ^ ((unsigned)((int)b >> 31) | 0x80000000u); }
; DI void indexer_phase(const u16* __restrict__ P, unsigned* __restrict__ mask) {
;     ...
;     for (int kb = 0; kb < 64; ++kb) {
;       unsigned u = 0u;
;       if (kb <= kbmax) {
;         f32x16 a;
; #pragma unroll
;         for (int r = 0; r < 16; ++r) a[r] = 0.f;
;         const u16* kp = P + (brow + 32 * kb + r32) * 7808 + 3584 + 8 * hi;
; #pragma unroll
;         for (int s = 0; s < 4; ++s) { const bf16x8 bk = *(const bf16x8*)(kp + 16 * s); a = MFMA(aq[s], bk, a); }
;         float v = 0.f;
; #pragma unroll
;         for (int i = 0; i < 16; ++i) v = fmaf(wv[i], fmaxf(a[i], 0.f), v);
;         u = (32 * kb + r32 <= tme) ? ordkey(v) : 0u;
;       }
;       sc[kb] = u;
.Lix_m33:
	v_cmp_le_i32_e32 vcc, 0x420, v16
	v_mfma_f32_32x32x16_bf16 v[18:33], v[46:49], v[80:83], 0
	v_mfma_f32_32x32x16_bf16 v[18:33], v[42:45], v[84:87], v[18:33]
	v_mfma_f32_32x32x16_bf16 v[18:33], v[38:41], v[88:91], v[18:33]
	v_mfma_f32_32x32x16_bf16 v[18:33], v[34:37], v[92:95], v[18:33]
	s_nop 11
	v_max_f32_e32 v18, 0, v18
	v_max_f32_e32 v19, 0, v19
	v_fma_f32 v18, v143, v18, 0
	v_fmac_f32_e32 v18, v142, v19
	v_max_f32_e32 v19, 0, v20
	v_fmac_f32_e32 v18, v141, v19
	v_max_f32_e32 v19, 0, v21
	v_fmac_f32_e32 v18, v140, v19
	v_max_f32_e32 v19, 0, v22
	v_fmac_f32_e32 v18, v139, v19
	v_max_f32_e32 v19, 0, v23
	v_fmac_f32_e32 v18, v138, v19
	v_max_f32_e32 v19, 0, v24
	v_fmac_f32_e32 v18, v137, v19
	v_max_f32_e32 v19, 0, v25
	v_fmac_f32_e32 v18, v136, v19
	v_max_f32_e32 v19, 0, v26
	v_fmac_f32_e32 v18, v135, v19
	v_max_f32_e32 v19, 0, v27
	v_fmac_f32_e32 v18, v134, v19
	v_max_f32_e32 v19, 0, v28
	v_fmac_f32_e32 v18, v133, v19
	v_max_f32_e32 v19, 0, v29
	v_fmac_f32_e32 v18, v132, v19
	v_max_f32_e32 v19, 0, v30
	v_fmac_f32_e32 v18, v131, v19
	v_max_f32_e32 v19, 0, v31
	v_fmac_f32_e32 v18, v130, v19
	v_max_f32_e32 v19, 0, v32
	v_fmac_f32_e32 v18, v129, v19
	v_max_f32_e32 v19, 0, v33
	v_fmac_f32_e32 v18, v128, v19
	v_ashrrev_i32_e32 v19, 31, v18
	v_bitop3_b32 v18, v19, v18, s8 bitop3:0x36
	v_cndmask_b32_e32 v184, 0, v18, vcc
	s_cmp_lt_u32 s0, 0x440
	s_cbranch_scc1 .Lix_z34
.Lix_b34:
	s_cmp_lt_u32 s0, 0x4a0
	s_cbranch_scc1 .Lix_w34
	s_add_u32 m0, s1, 0x1000
	s_nop 0
	global_load_lds_dwordx4 v112, s[22:23]
	s_add_u32 s22, s22, 0x1e800
	s_addc_u32 s23, s23, 0
	s_add_u32 m0, s1, 0x1400
	s_nop 0
	global_load_lds_dwordx4 v113, s[22:23]
	s_add_u32 s22, s22, 0x1e800
	s_addc_u32 s23, s23, 0
	s_add_u32 m0, s1, 0x1800
	s_nop 0
	global_load_lds_dwordx4 v112, s[22:23]
	s_add_u32 s22, s22, 0x1e800
	s_addc_u32 s23, s23, 0
	s_add_u32 m0, s1, 0x1c00
	s_nop 0
	global_load_lds_dwordx4 v113, s[22:23]
	s_add_u32 s22, s22, 0x1e800
	s_addc_u32 s23, s23, 0
	s_waitcnt vmcnt(8)
	s_branch .Lix_r34

; #define MFMA(a, b, c) __builtin_amdgcn_mfma_f32_32x32x16_bf16((a), (b), (c), 0, 0, 0)
; DI void indexer_phase(const u16* __restrict__ P, unsigned* __restrict__ mask) {
;     ...
;         const u16* kp = P + (brow + 32 * kb + r32) * 7808 + 3584 + 8 * hi;
; #pragma unroll
;         for (int s = 0; s < 4; ++s) { const bf16x8 bk = *(const bf16x8*)(kp + 16 * s); a = MFMA(aq[s], bk, a); }
.Lix_r34:
	s_cmp_lt_u32 s0, 0x460
	s_cbranch_scc1 .Lix_n34
	ds_read_b128 v[80:83], v114 offset:12288
	ds_read_b128 v[84:87], v115 offset:12288
	ds_read_b128 v[88:91], v116 offset:12288
	ds_read_b128 v[92:95], v117 offset:12288
	s_waitcnt lgkmcnt(4)
	s_branch .Lix_m34

; #define MFMA(a, b, c) __builtin_amdgcn_mfma_f32_32x32x16_bf16((a), (b), (c), 0, 0, 0)
; DI unsigned ordkey(float f) { const unsigned b = __float_as_uint(f); return b ^ ((unsigned)((int)b >> 31) | 0x80000000u); }
; DI void indexer_phase(const u16* __restrict__ P, unsigned* __restrict__ mask) {
;     ...
;     for (int kb = 0; kb < 64; ++kb) {
;       unsigned u = 0u;
;       if (kb <= kbmax) {
;         f32x16 a;
; #pragma unroll
;         for (int r = 0; r < 16; ++r) a[r] = 0.f;
;         const u16* kp = P + (brow + 32 * kb + r32) * 7808 + 3584 + 8 * hi;
; #pragma unroll
;         for (int s = 0; s < 4; ++s) { const bf16x8 bk = *(const bf16x8*)(kp + 16 * s); a = MFMA(aq[s], bk, a); }
;         float v = 0.f;
; #pragma unroll
;         for (int i = 0; i < 16; ++i) v = fmaf(wv[i], fmaxf(a[i], 0.f), v);
;         u = (32 * kb + r32 <= tme) ? ordkey(v) : 0u;
;       }
;       sc[kb] = u;
.Lix_m34:
	v_cmp_le_i32_e32 vcc, 0x440, v16
	v_mfma_f32_32x32x16_bf16 v[18:33], v[46:49], v[64:67], 0
	v_mfma_f32_32x32x16_bf16 v[18:33], v[42:45], v[68:71], v[18:33]
	v_mfma_f32_32x32x16_bf16 v[18:33], v[38:41], v[72:75], v[18:33]
	v_mfma_f32_32x32x16_bf16 v[18:33], v[34:37], v[76:79], v[18:33]
	s_nop 11
	v_max_f32_e32 v18, 0, v18
	v_max_f32_e32 v19, 0, v19
	v_fma_f32 v18, v143, v18, 0
	v_fmac_f32_e32 v18, v142, v19
	v_max_f32_e32 v19, 0, v20
	v_fmac_f32_e32 v18, v141, v19
	v_max_f32_e32 v19, 0, v21
	v_fmac_f32_e32 v18, v140, v19
	v_max_f32_e32 v19, 0, v22
	v_fmac_f32_e32 v18, v139, v19
	v_max_f32_e32 v19, 0, v23
	v_fmac_f32_e32 v18, v138, v19
	v_max_f32_e32 v19, 0, v24
	v_fmac_f32_e32 v18, v137, v19
	v_max_f32_e32 v19, 0, v25
	v_fmac_f32_e32 v18, v136, v19
	v_max_f32_e32 v19, 0, v26
	v_fmac_f32_e32 v18, v135, v19
	v_max_f32_e32 v19, 0, v27
	v_fmac_f32_e32 v18, v134, v19
	v_max_f32_e32 v19, 0, v28
	v_fmac_f32_e32 v18, v133, v19
	v_max_f32_e32 v19, 0, v29
	v_fmac_f32_e32 v18, v132, v19
	v_max_f32_e32 v19, 0, v30
	v_fmac_f32_e32 v18, v131, v19
	v_max_f32_e32 v19, 0, v31
	v_fmac_f32_e32 v18, v130, v19
	v_max_f32_e32 v19, 0, v32
	v_fmac_f32_e32 v18, v129, v19
	v_max_f32_e32 v19, 0, v33
	v_fmac_f32_e32 v18, v128, v19
	v_ashrrev_i32_e32 v19, 31, v18
	v_bitop3_b32 v18, v19, v18, s8 bitop3:0x36
	v_cndmask_b32_e32 v183, 0, v18, vcc
	s_cmp_lt_u32 s0, 0x460
	s_cbranch_scc1 .Lix_z35
.Lix_b35:
	s_cmp_lt_u32 s0, 0x4c0
	s_cbranch_scc1 .Lix_w35
	s_add_u32 m0, s1, 0x2000
	s_nop 0
	global_load_lds_dwordx4 v112, s[22:23]
	s_add_u32 s22, s22, 0x1e800
	s_addc_u32 s23, s23, 0
	s_add_u32 m0, s1, 0x2400
	s_nop 0
	global_load_lds_dwordx4 v113, s[22:23]
	s_add_u32 s22, s22, 0x1e800
	s_addc_u32 s23, s23, 0
	s_add_u32 m0, s1, 0x2800
	s_nop 0
	global_load_lds_dwordx4 v112, s[22:23]
	s_add_u32 s22, s22, 0x1e800
	s_addc_u32 s23, s23, 0
	s_add_u32 m0, s1, 0x2c00
	s_nop 0
	global_load_lds_dwordx4 v113, s[22:23]
	s_add_u32 s22, s22, 0x1e800
	s_addc_u32 s23, s23, 0
	s_waitcnt vmcnt(8)
	s_branch .Lix_r35

; #define MFMA(a, b, c) __builtin_amdgcn_mfma_f32_32x32x16_bf16((a), (b), (c), 0, 0, 0)
; DI void indexer_phase(const u16* __restrict__ P, unsigned* __restrict__ mask) {
;     ...
;         const u16* kp = P + (brow + 32 * kb + r32) * 7808 + 3584 + 8 * hi;
; #pragma unroll
;         for (int s = 0; s < 4; ++s) { const bf16x8 bk = *(const bf16x8*)(kp + 16 * s); a = MFMA(aq[s], bk, a); }
.Lix_r35:
	s_cmp_lt_u32 s0, 0x480
	s_cbranch_scc1 .Lix_n35
	ds_read_b128 v[64:67], v114
	ds_read_b128 v[68:71], v115
	ds_read_b128 v[72:75], v116
	ds_read_b128 v[76:79], v117
	s_waitcnt lgkmcnt(4)
	s_branch .Lix_m35

; #define MFMA(a, b, c) __builtin_amdgcn_mfma_f32_32x32x16_bf16((a), (b), (c), 0, 0, 0)
; DI unsigned ordkey(float f) { const unsigned b = __float_as_uint(f); return b ^ ((unsigned)((int)b >> 31) | 0x80000000u); }
; DI void indexer_phase(const u16* __restrict__ P, unsigned* __restrict__ mask) {
;     ...
;     for (int kb = 0; kb < 64; ++kb) {
;       unsigned u = 0u;
;       if (kb <= kbmax) {
;         f32x16 a;
; #pragma unroll
;         for (int r = 0; r < 16; ++r) a[r] = 0.f;
;         const u16* kp = P + (brow + 32 * kb + r32) * 7808 + 3584 + 8 * hi;
; #pragma unroll
;         for (int s = 0; s < 4; ++s) { const bf16x8 bk = *(const bf16x8*)(kp + 16 * s); a = MFMA(aq[s], bk, a); }
;         float v = 0.f;
; #pragma unroll
;         for (int i = 0; i < 16; ++i) v = fmaf(wv[i], fmaxf(a[i], 0.f), v);
;         u = (32 * kb + r32 <= tme) ? ordkey(v) : 0u;
;       }
;       sc[kb] = u;
.Lix_m35:
	v_cmp_le_i32_e32 vcc, 0x460, v16
	v_mfma_f32_32x32x16_bf16 v[18:33], v[46:49], v[80:83], 0
	v_mfma_f32_32x32x16_bf16 v[18:33], v[42:45], v[84:87], v[18:33]
	v_mfma_f32_32x32x16_bf16 v[18:33], v[38:41], v[88:91], v[18:33]
	v_mfma_f32_32x32x16_bf16 v[18:33], v[34:37], v[92:95], v[18:33]
	s_nop 11
	v_max_f32_e32 v18, 0, v18
	v_max_f32_e32 v19, 0, v19
	v_fma_f32 v18, v143, v18, 0
	v_fmac_f32_e32 v18, v142, v19
	v_max_f32_e32 v19, 0, v20
	v_fmac_f32_e32 v18, v141, v19
	v_max_f32_e32 v19, 0, v21
	v_fmac_f32_e32 v18, v140, v19
	v_max_f32_e32 v19, 0, v22
	v_fmac_f32_e32 v18, v139, v19
	v_max_f32_e32 v19, 0, v23
	v_fmac_f32_e32 v18, v138, v19
	v_max_f32_e32 v19, 0, v24
	v_fmac_f32_e32 v18, v137, v19
	v_max_f32_e32 v19, 0, v25
	v_fmac_f32_e32 v18, v136, v19
	v_max_f32_e32 v19, 0, v26
	v_fmac_f32_e32 v18, v135, v19
	v_max_f32_e32 v19, 0, v27
	v_fmac_f32_e32 v18, v134, v19
	v_max_f32_e32 v19, 0, v28
	v_fmac_f32_e32 v18, v133, v19
	v_max_f32_e32 v19, 0, v29
	v_fmac_f32_e32 v18, v132, v19
	v_max_f32_e32 v19, 0, v30
	v_fmac_f32_e32 v18, v131, v19
	v_max_f32_e32 v19, 0, v31
	v_fmac_f32_e32 v18, v130, v19
	v_max_f32_e32 v19, 0, v32
	v_fmac_f32_e32 v18, v129, v19
	v_max_f32_e32 v19, 0, v33
	v_fmac_f32_e32 v18, v128, v19
	v_ashrrev_i32_e32 v19, 31, v18
	v_bitop3_b32 v18, v19, v18, s8 bitop3:0x36
	v_cndmask_b32_e32 v186, 0, v18, vcc
	s_cmp_lt_u32 s0, 0x480
	s_cbranch_scc1 .Lix_z36
.Lix_b36:
	s_cmp_lt_u32 s0, 0x4e0
	s_cbranch_scc1 .Lix_w36
	s_add_u32 m0, s1, 0x3000
	s_nop 0
	global_load_lds_dwordx4 v112, s[22:23]
	s_add_u32 s22, s22, 0x1e800
	s_addc_u32 s23, s23, 0
	s_add_u32 m0, s1, 0x3400
	s_nop 0
	global_load_lds_dwordx4 v113, s[22:23]
	s_add_u32 s22, s22, 0x1e800
	s_addc_u32 s23, s23, 0
	s_add_u32 m0, s1, 0x3800
	s_nop 0
	global_load_lds_dwordx4 v112, s[22:23]
	s_add_u32 s22, s22, 0x1e800
	s_addc_u32 s23, s23, 0
	s_add_u32 m0, s1, 0x3c00
	s_nop 0
	global_load_lds_dwordx4 v113, s[22:23]
	s_add_u32 s22, s22, 0x1e800
	s_addc_u32 s23, s23, 0
	s_waitcnt vmcnt(8)
	s_branch .Lix_r36

; #define MFMA(a, b, c) __builtin_amdgcn_mfma_f32_32x32x16_bf16((a), (b), (c), 0, 0, 0)
; DI void indexer_phase(const u16* __restrict__ P, unsigned* __restrict__ mask) {
;     ...
;         const u16* kp = P + (brow + 32 * kb + r32) * 7808 + 3584 + 8 * hi;
; #pragma unroll
;         for (int s = 0; s < 4; ++s) { const bf16x8 bk = *(const bf16x8*)(kp + 16 * s); a = MFMA(aq[s], bk, a); }
.Lix_r36:
	s_cmp_lt_u32 s0, 0x4a0
	s_cbranch_scc1 .Lix_n36
	ds_read_b128 v[80:83], v114 offset:4096
	ds_read_b128 v[84:87], v115 offset:4096
	ds_read_b128 v[88:91], v116 offset:4096
	ds_read_b128 v[92:95], v117 offset:4096
	s_waitcnt lgkmcnt(4)
	s_branch .Lix_m36

; #define MFMA(a, b, c) __builtin_amdgcn_mfma_f32_32x32x16_bf16((a), (b), (c), 0, 0, 0)
; DI unsigned ordkey(float f) { const unsigned b = __float_as_uint(f); return b ^ ((unsigned)((int)b >> 31) | 0x80000000u); }
; DI void indexer_phase(const u16* __restrict__ P, unsigned* __restrict__ mask) {
;     ...
;     for (int kb = 0; kb < 64; ++kb) {
;       unsigned u = 0u;
;       if (kb <= kbmax) {
;         f32x16 a;
; #pragma unroll
;         for (int r = 0; r < 16; ++r) a[r] = 0.f;
;         const u16* kp = P + (brow + 32 * kb + r32) * 7808 + 3584 + 8 * hi;
; #pragma unroll
;         for (int s = 0; s < 4; ++s) { const bf16x8 bk = *(const bf16x8*)(kp + 16 * s); a = MFMA(aq[s], bk, a); }
;         float v = 0.f;
; #pragma unroll
;         for (int i = 0; i < 16; ++i) v = fmaf(wv[i], fmaxf(a[i], 0.f), v);
;         u = (32 * kb + r32 <= tme) ? ordkey(v) : 0u;
;       }
;       sc[kb] = u;
.Lix_m36:
	v_cmp_le_i32_e32 vcc, 0x480, v16
	v_mfma_f32_32x32x16_bf16 v[18:33], v[46:49], v[64:67], 0
	v_mfma_f32_32x32x16_bf16 v[18:33], v[42:45], v[68:71], v[18:33]
	v_mfma_f32_32x32x16_bf16 v[18:33], v[38:41], v[72:75], v[18:33]
	v_mfma_f32_32x32x16_bf16 v[18:33], v[34:37], v[76:79], v[18:33]
	s_nop 11
	v_max_f32_e32 v18, 0, v18
	v_max_f32_e32 v19, 0, v19
	v_fma_f32 v18, v143, v18, 0
	v_fmac_f32_e32 v18, v142, v19
	v_max_f32_e32 v19, 0, v20
	v_fmac_f32_e32 v18, v141, v19
	v_max_f32_e32 v19, 0, v21
	v_fmac_f32_e32 v18, v140, v19
	v_max_f32_e32 v19, 0, v22
	v_fmac_f32_e32 v18, v139, v19
	v_max_f32_e32 v19, 0, v23
	v_fmac_f32_e32 v18, v138, v19
	v_max_f32_e32 v19, 0, v24
	v_fmac_f32_e32 v18, v137, v19
	v_max_f32_e32 v19, 0, v25
	v_fmac_f32_e32 v18, v136, v19
	v_max_f32_e32 v19, 0, v26
	v_fmac_f32_e32 v18, v135, v19
	v_max_f32_e32 v19, 0, v27
	v_fmac_f32_e32 v18, v134, v19
	v_max_f32_e32 v19, 0, v28
	v_fmac_f32_e32 v18, v133, v19
	v_max_f32_e32 v19, 0, v29
	v_fmac_f32_e32 v18, v132, v19
	v_max_f32_e32 v19, 0, v30
	v_fmac_f32_e32 v18, v131, v19
	v_max_f32_e32 v19, 0, v31
	v_fmac_f32_e32 v18, v130, v19
	v_max_f32_e32 v19, 0, v32
	v_fmac_f32_e32 v18, v129, v19
	v_max_f32_e32 v19, 0, v33
	v_fmac_f32_e32 v18, v128, v19
	v_ashrrev_i32_e32 v19, 31, v18
	v_bitop3_b32 v18, v19, v18, s8 bitop3:0x36
	v_cndmask_b32_e32 v185, 0, v18, vcc
	s_cmp_lt_u32 s0, 0x4a0
	s_cbranch_scc1 .Lix_z37
.Lix_b37:
	s_cmp_lt_u32 s0, 0x500
	s_cbranch_scc1 .Lix_w37
	s_add_u32 m0, s1, 0
	s_nop 0
	global_load_lds_dwordx4 v112, s[22:23]
	s_add_u32 s22, s22, 0x1e800
	s_addc_u32 s23, s23, 0
	s_add_u32 m0, s1, 0x400
	s_nop 0
	global_load_lds_dwordx4 v113, s[22:23]
	s_add_u32 s22, s22, 0x1e800
	s_addc_u32 s23, s23, 0
	s_add_u32 m0, s1, 0x800
	s_nop 0
	global_load_lds_dwordx4 v112, s[22:23]
	s_add_u32 s22, s22, 0x1e800
	s_addc_u32 s23, s23, 0
	s_add_u32 m0, s1, 0xc00
	s_nop 0
	global_load_lds_dwordx4 v113, s[22:23]
	s_add_u32 s22, s22, 0x1e800
	s_addc_u32 s23, s23, 0
	s_waitcnt vmcnt(8)
	s_branch .Lix_r37

; #define MFMA(a, b, c) __builtin_amdgcn_mfma_f32_32x32x16_bf16((a), (b), (c), 0, 0, 0)
; DI void indexer_phase(const u16* __restrict__ P, unsigned* __restrict__ mask) {
;     ...
;         const u16* kp = P + (brow + 32 * kb + r32) * 7808 + 3584 + 8 * hi;
; #pragma unroll
;         for (int s = 0; s < 4; ++s) { const bf16x8 bk = *(const bf16x8*)(kp + 16 * s); a = MFMA(aq[s], bk, a); }
.Lix_r37:
	s_cmp_lt_u32 s0, 0x4c0
	s_cbranch_scc1 .Lix_n37
	ds_read_b128 v[64:67], v114 offset:8192
	ds_read_b128 v[68:71], v115 offset:8192
	ds_read_b128 v[72:75], v116 offset:8192
	ds_read_b128 v[76:79], v117 offset:8192
	s_waitcnt lgkmcnt(4)
	s_branch .Lix_m37

; #define MFMA(a, b, c) __builtin_amdgcn_mfma_f32_32x32x16_bf16((a), (b), (c), 0, 0, 0)
; DI unsigned ordkey(float f) { const unsigned b = __float_as_uint(f); return b ^ ((unsigned)((int)b >> 31) | 0x80000000u); }
; DI void indexer_phase(const u16* __restrict__ P, unsigned* __restrict__ mask) {
;     ...
;     for (int kb = 0; kb < 64; ++kb) {
;       unsigned u = 0u;
;       if (kb <= kbmax) {
;         f32x16 a;
; #pragma unroll
;         for (int r = 0; r < 16; ++r) a[r] = 0.f;
;         const u16* kp = P + (brow + 32 * kb + r32) * 7808 + 3584 + 8 * hi;
; #pragma unroll
;         for (int s = 0; s < 4; ++s) { const bf16x8 bk = *(const bf16x8*)(kp + 16 * s); a = MFMA(aq[s], bk, a); }
;         float v = 0.f;
; #pragma unroll
;         for (int i = 0; i < 16; ++i) v = fmaf(wv[i], fmaxf(a[i], 0.f), v);
;         u = (32 * kb + r32 <= tme) ? ordkey(v) : 0u;
;       }
;       sc[kb] = u;
.Lix_m37:
	v_cmp_le_i32_e32 vcc, 0x4a0, v16
	v_mfma_f32_32x32x16_bf16 v[18:33], v[46:49], v[80:83], 0
	v_mfma_f32_32x32x16_bf16 v[18:33], v[42:45], v[84:87], v[18:33]
	v_mfma_f32_32x32x16_bf16 v[18:33], v[38:41], v[88:91], v[18:33]
	v_mfma_f32_32x32x16_bf16 v[18:33], v[34:37], v[92:95], v[18:33]
	s_nop 11
	v_max_f32_e32 v18, 0, v18
	v_max_f32_e32 v19, 0, v19
	v_fma_f32 v18, v143, v18, 0
	v_fmac_f32_e32 v18, v142, v19
	v_max_f32_e32 v19, 0, v20
	v_fmac_f32_e32 v18, v141, v19
	v_max_f32_e32 v19, 0, v21
	v_fmac_f32_e32 v18, v140, v19
	v_max_f32_e32 v19, 0, v22
	v_fmac_f32_e32 v18, v139, v19
	v_max_f32_e32 v19, 0, v23
	v_fmac_f32_e32 v18, v138, v19
	v_max_f32_e32 v19, 0, v24
	v_fmac_f32_e32 v18, v137, v19
	v_max_f32_e32 v19, 0, v25
	v_fmac_f32_e32 v18, v136, v19
	v_max_f32_e32 v19, 0, v26
	v_fmac_f32_e32 v18, v135, v19
	v_max_f32_e32 v19, 0, v27
	v_fmac_f32_e32 v18, v134, v19
	v_max_f32_e32 v19, 0, v28
	v_fmac_f32_e32 v18, v133, v19
	v_max_f32_e32 v19, 0, v29
	v_fmac_f32_e32 v18, v132, v19
	v_max_f32_e32 v19, 0, v30
	v_fmac_f32_e32 v18, v131, v19
	v_max_f32_e32 v19, 0, v31
	v_fmac_f32_e32 v18, v130, v19
	v_max_f32_e32 v19, 0, v32
	v_fmac_f32_e32 v18, v129, v19
	v_max_f32_e32 v19, 0, v33
	v_fmac_f32_e32 v18, v128, v19
	v_ashrrev_i32_e32 v19, 31, v18
	v_bitop3_b32 v18, v19, v18, s8 bitop3:0x36
	v_cndmask_b32_e32 v188, 0, v18, vcc
	s_cmp_lt_u32 s0, 0x4c0
	s_cbranch_scc1 .Lix_z38
.Lix_b38:
	s_cmp_lt_u32 s0, 0x520
	s_cbranch_scc1 .Lix_w38
	s_add_u32 m0, s1, 0x1000
	s_nop 0
	global_load_lds_dwordx4 v112, s[22:23]
	s_add_u32 s22, s22, 0x1e800
	s_addc_u32 s23, s23, 0
	s_add_u32 m0, s1, 0x1400
	s_nop 0
	global_load_lds_dwordx4 v113, s[22:23]
	s_add_u32 s22, s22, 0x1e800
	s_addc_u32 s23, s23, 0
	s_add_u32 m0, s1, 0x1800
	s_nop 0
	global_load_lds_dwordx4 v112, s[22:23]
	s_add_u32 s22, s22, 0x1e800
	s_addc_u32 s23, s23, 0
	s_add_u32 m0, s1, 0x1c00
	s_nop 0
	global_load_lds_dwordx4 v113, s[22:23]
	s_add_u32 s22, s22, 0x1e800
	s_addc_u32 s23, s23, 0
	s_waitcnt vmcnt(8)
	s_branch .Lix_r38

; #define MFMA(a, b, c) __builtin_amdgcn_mfma_f32_32x32x16_bf16((a), (b), (c), 0, 0, 0)
; DI void indexer_phase(const u16* __restrict__ P, unsigned* __restrict__ mask) {
;     ...
;         const u16* kp = P + (brow + 32 * kb + r32) * 7808 + 3584 + 8 * hi;
; #pragma unroll
;         for (int s = 0; s < 4; ++s) { const bf16x8 bk = *(const bf16x8*)(kp + 16 * s); a = MFMA(aq[s], bk, a); }
.Lix_r38:
	s_cmp_lt_u32 s0, 0x4e0
	s_cbranch_scc1 .Lix_n38
	ds_read_b128 v[80:83], v114 offset:12288
	ds_read_b128 v[84:87], v115 offset:12288
	ds_read_b128 v[88:91], v116 offset:12288
	ds_read_b128 v[92:95], v117 offset:12288
	s_waitcnt lgkmcnt(4)
	s_branch .Lix_m38

; #define MFMA(a, b, c) __builtin_amdgcn_mfma_f32_32x32x16_bf16((a), (b), (c), 0, 0, 0)
; DI unsigned ordkey(float f) { const unsigned b = __float_as_uint(f); return b ^ ((unsigned)((int)b >> 31) | 0x80000000u); }
; DI void indexer_phase(const u16* __restrict__ P, unsigned* __restrict__ mask) {
;     ...
;     for (int kb = 0; kb < 64; ++kb) {
;       unsigned u = 0u;
;       if (kb <= kbmax) {
;         f32x16 a;
; #pragma unroll
;         for (int r = 0; r < 16; ++r) a[r] = 0.f;
;         const u16* kp = P + (brow + 32 * kb + r32) * 7808 + 3584 + 8 * hi;
; #pragma unroll
;         for (int s = 0; s < 4; ++s) { const bf16x8 bk = *(const bf16x8*)(kp + 16 * s); a = MFMA(aq[s], bk, a); }
;         float v = 0.f;
; #pragma unroll
;         for (int i = 0; i < 16; ++i) v = fmaf(wv[i], fmaxf(a[i], 0.f), v);
;         u = (32 * kb + r32 <= tme) ? ordkey(v) : 0u;
;       }
;       sc[kb] = u;
.Lix_m38:
	v_cmp_le_i32_e32 vcc, 0x4c0, v16
	v_mfma_f32_32x32x16_bf16 v[18:33], v[46:49], v[64:67], 0
	v_mfma_f32_32x32x16_bf16 v[18:33], v[42:45], v[68:71], v[18:33]
	v_mfma_f32_32x32x16_bf16 v[18:33], v[38:41], v[72:75], v[18:33]
	v_mfma_f32_32x32x16_bf16 v[18:33], v[34:37], v[76:79], v[18:33]
	s_nop 11
	v_max_f32_e32 v18, 0, v18
	v_max_f32_e32 v19, 0, v19
	v_fma_f32 v18, v143, v18, 0
	v_fmac_f32_e32 v18, v142, v19
	v_max_f32_e32 v19, 0, v20
	v_fmac_f32_e32 v18, v141, v19
	v_max_f32_e32 v19, 0, v21
	v_fmac_f32_e32 v18, v140, v19
	v_max_f32_e32 v19, 0, v22
	v_fmac_f32_e32 v18, v139, v19
	v_max_f32_e32 v19, 0, v23
	v_fmac_f32_e32 v18, v138, v19
	v_max_f32_e32 v19, 0, v24
	v_fmac_f32_e32 v18, v137, v19
	v_max_f32_e32 v19, 0, v25
	v_fmac_f32_e32 v18, v136, v19
	v_max_f32_e32 v19, 0, v26
	v_fmac_f32_e32 v18, v135, v19
	v_max_f32_e32 v19, 0, v27
	v_fmac_f32_e32 v18, v134, v19
	v_max_f32_e32 v19, 0, v28
	v_fmac_f32_e32 v18, v133, v19
	v_max_f32_e32 v19, 0, v29
	v_fmac_f32_e32 v18, v132, v19
	v_max_f32_e32 v19, 0, v30
	v_fmac_f32_e32 v18, v131, v19
	v_max_f32_e32 v19, 0, v31
	v_fmac_f32_e32 v18, v130, v19
	v_max_f32_e32 v19, 0, v32
	v_fmac_f32_e32 v18, v129, v19
	v_max_f32_e32 v19, 0, v33
	v_fmac_f32_e32 v18, v128, v19
	v_ashrrev_i32_e32 v19, 31, v18
	v_bitop3_b32 v18, v19, v18, s8 bitop3:0x36
	v_cndmask_b32_e32 v187, 0, v18, vcc
	s_cmp_lt_u32 s0, 0x4e0
	s_cbranch_scc1 .Lix_z39
.Lix_b39:
	s_cmp_lt_u32 s0, 0x540
	s_cbranch_scc1 .Lix_w39
	s_add_u32 m0, s1, 0x2000
	s_nop 0
	global_load_lds_dwordx4 v112, s[22:23]
	s_add_u32 s22, s22, 0x1e800
	s_addc_u32 s23, s23, 0
	s_add_u32 m0, s1, 0x2400
	s_nop 0
	global_load_lds_dwordx4 v113, s[22:23]
	s_add_u32 s22, s22, 0x1e800
	s_addc_u32 s23, s23, 0
	s_add_u32 m0, s1, 0x2800
	s_nop 0
	global_load_lds_dwordx4 v112, s[22:23]
	s_add_u32 s22, s22, 0x1e800
	s_addc_u32 s23, s23, 0
	s_add_u32 m0, s1, 0x2c00
	s_nop 0
	global_load_lds_dwordx4 v113, s[22:23]
	s_add_u32 s22, s22, 0x1e800
	s_addc_u32 s23, s23, 0
	s_waitcnt vmcnt(8)
	s_branch .Lix_r39

; #define MFMA(a, b, c) __builtin_amdgcn_mfma_f32_32x32x16_bf16((a), (b), (c), 0, 0, 0)
; DI void indexer_phase(const u16* __restrict__ P, unsigned* __restrict__ mask) {
;     ...
;         const u16* kp = P + (brow + 32 * kb + r32) * 7808 + 3584 + 8 * hi;
; #pragma unroll
;         for (int s = 0; s < 4; ++s) { const bf16x8 bk = *(const bf16x8*)(kp + 16 * s); a = MFMA(aq[s], bk, a); }
.Lix_r39:
	s_cmp_lt_u32 s0, 0x500
	s_cbranch_scc1 .Lix_n39
	ds_read_b128 v[64:67], v114
	ds_read_b128 v[68:71], v115
	ds_read_b128 v[72:75], v116
	ds_read_b128 v[76:79], v117
	s_waitcnt lgkmcnt(4)
	s_branch .Lix_m39

; #define MFMA(a, b, c) __builtin_amdgcn_mfma_f32_32x32x16_bf16((a), (b), (c), 0, 0, 0)
; DI unsigned ordkey(float f) { const unsigned b = __float_as_uint(f); return b ^ ((unsigned)((int)b >> 31) | 0x80000000u); }
; DI void indexer_phase(const u16* __restrict__ P, unsigned* __restrict__ mask) {
;     ...
;     for (int kb = 0; kb < 64; ++kb) {
;       unsigned u = 0u;
;       if (kb <= kbmax) {
;         f32x16 a;
; #pragma unroll
;         for (int r = 0; r < 16; ++r) a[r] = 0.f;
;         const u16* kp = P + (brow + 32 * kb + r32) * 7808 + 3584 + 8 * hi;
; #pragma unroll
;         for (int s = 0; s < 4; ++s) { const bf16x8 bk = *(const bf16x8*)(kp + 16 * s); a = MFMA(aq[s], bk, a); }
;         float v = 0.f;
; #pragma unroll
;         for (int i = 0; i < 16; ++i) v = fmaf(wv[i], fmaxf(a[i], 0.f), v);
;         u = (32 * kb + r32 <= tme) ? ordkey(v) : 0u;
;       }
;       sc[kb] = u;
.Lix_m39:
	v_cmp_le_i32_e32 vcc, 0x4e0, v16
	v_mfma_f32_32x32x16_bf16 v[18:33], v[46:49], v[80:83], 0
	v_mfma_f32_32x32x16_bf16 v[18:33], v[42:45], v[84:87], v[18:33]
	v_mfma_f32_32x32x16_bf16 v[18:33], v[38:41], v[88:91], v[18:33]
	v_mfma_f32_32x32x16_bf16 v[18:33], v[34:37], v[92:95], v[18:33]
	s_nop 11
	v_max_f32_e32 v18, 0, v18
	v_max_f32_e32 v19, 0, v19
	v_fma_f32 v18, v143, v18, 0
	v_fmac_f32_e32 v18, v142, v19
	v_max_f32_e32 v19, 0, v20
	v_fmac_f32_e32 v18, v141, v19
	v_max_f32_e32 v19, 0, v21
	v_fmac_f32_e32 v18, v140, v19
	v_max_f32_e32 v19, 0, v22
	v_fmac_f32_e32 v18, v139, v19
	v_max_f32_e32 v19, 0, v23
	v_fmac_f32_e32 v18, v138, v19
	v_max_f32_e32 v19, 0, v24
	v_fmac_f32_e32 v18, v137, v19
	v_max_f32_e32 v19, 0, v25
	v_fmac_f32_e32 v18, v136, v19
	v_max_f32_e32 v19, 0, v26
	v_fmac_f32_e32 v18, v135, v19
	v_max_f32_e32 v19, 0, v27
	v_fmac_f32_e32 v18, v134, v19
	v_max_f32_e32 v19, 0, v28
	v_fmac_f32_e32 v18, v133, v19
	v_max_f32_e32 v19, 0, v29
	v_fmac_f32_e32 v18, v132, v19
	v_max_f32_e32 v19, 0, v30
	v_fmac_f32_e32 v18, v131, v19
	v_max_f32_e32 v19, 0, v31
	v_fmac_f32_e32 v18, v130, v19
	v_max_f32_e32 v19, 0, v32
	v_fmac_f32_e32 v18, v129, v19
	v_max_f32_e32 v19, 0, v33
	v_fmac_f32_e32 v18, v128, v19
	v_ashrrev_i32_e32 v19, 31, v18
	v_bitop3_b32 v18, v19, v18, s8 bitop3:0x36
	v_cndmask_b32_e32 v190, 0, v18, vcc
	s_cmp_lt_u32 s0, 0x500
	s_cbranch_scc1 .Lix_z40
.Lix_b40:
	s_cmp_lt_u32 s0, 0x560
	s_cbranch_scc1 .Lix_w40
	s_add_u32 m0, s1, 0x3000
	s_nop 0
	global_load_lds_dwordx4 v112, s[22:23]
	s_add_u32 s22, s22, 0x1e800
	s_addc_u32 s23, s23, 0
	s_add_u32 m0, s1, 0x3400
	s_nop 0
	global_load_lds_dwordx4 v113, s[22:23]
	s_add_u32 s22, s22, 0x1e800
	s_addc_u32 s23, s23, 0
	s_add_u32 m0, s1, 0x3800
	s_nop 0
	global_load_lds_dwordx4 v112, s[22:23]
	s_add_u32 s22, s22, 0x1e800
	s_addc_u32 s23, s23, 0
	s_add_u32 m0, s1, 0x3c00
	s_nop 0
	global_load_lds_dwordx4 v113, s[22:23]
	s_add_u32 s22, s22, 0x1e800
	s_addc_u32 s23, s23, 0
	s_waitcnt vmcnt(8)
	s_branch .Lix_r40

; #define MFMA(a, b, c) __builtin_amdgcn_mfma_f32_32x32x16_bf16((a), (b), (c), 0, 0, 0)
; DI void indexer_phase(const u16* __restrict__ P, unsigned* __restrict__ mask) {
;     ...
;         const u16* kp = P + (brow + 32 * kb + r32) * 7808 + 3584 + 8 * hi;
; #pragma unroll
;         for (int s = 0; s < 4; ++s) { const bf16x8 bk = *(const bf16x8*)(kp + 16 * s); a = MFMA(aq[s], bk, a); }
.Lix_r40:
	s_cmp_lt_u32 s0, 0x520
	s_cbranch_scc1 .Lix_n40
	ds_read_b128 v[80:83], v114 offset:4096
	ds_read_b128 v[84:87], v115 offset:4096
	ds_read_b128 v[88:91], v116 offset:4096
	ds_read_b128 v[92:95], v117 offset:4096
	s_waitcnt lgkmcnt(4)
	s_branch .Lix_m40

; #define MFMA(a, b, c) __builtin_amdgcn_mfma_f32_32x32x16_bf16((a), (b), (c), 0, 0, 0)
; DI unsigned ordkey(float f) { const unsigned b = __float_as_uint(f); return b ^ ((unsigned)((int)b >> 31) | 0x80000000u); }
; DI void indexer_phase(const u16* __restrict__ P, unsigned* __restrict__ mask) {
;     ...
;     for (int kb = 0; kb < 64; ++kb) {
;       unsigned u = 0u;
;       if (kb <= kbmax) {
;         f32x16 a;
; #pragma unroll
;         for (int r = 0; r < 16; ++r) a[r] = 0.f;
;         const u16* kp = P + (brow + 32 * kb + r32) * 7808 + 3584 + 8 * hi;
; #pragma unroll
;         for (int s = 0; s < 4; ++s) { const bf16x8 bk = *(const bf16x8*)(kp + 16 * s); a = MFMA(aq[s], bk, a); }
;         float v = 0.f;
; #pragma unroll
;         for (int i = 0; i < 16; ++i) v = fmaf(wv[i], fmaxf(a[i], 0.f), v);
;         u = (32 * kb + r32 <= tme) ? ordkey(v) : 0u;
;       }
;       sc[kb] = u;
.Lix_m40:
	v_cmp_le_i32_e32 vcc, 0x500, v16
	v_mfma_f32_32x32x16_bf16 v[18:33], v[46:49], v[64:67], 0
	v_mfma_f32_32x32x16_bf16 v[18:33], v[42:45], v[68:71], v[18:33]
	v_mfma_f32_32x32x16_bf16 v[18:33], v[38:41], v[72:75], v[18:33]
	v_mfma_f32_32x32x16_bf16 v[18:33], v[34:37], v[76:79], v[18:33]
	s_nop 11
	v_max_f32_e32 v18, 0, v18
	v_max_f32_e32 v19, 0, v19
	v_fma_f32 v18, v143, v18, 0
	v_fmac_f32_e32 v18, v142, v19
	v_max_f32_e32 v19, 0, v20
	v_fmac_f32_e32 v18, v141, v19
	v_max_f32_e32 v19, 0, v21
	v_fmac_f32_e32 v18, v140, v19
	v_max_f32_e32 v19, 0, v22
	v_fmac_f32_e32 v18, v139, v19
	v_max_f32_e32 v19, 0, v23
	v_fmac_f32_e32 v18, v138, v19
	v_max_f32_e32 v19, 0, v24
	v_fmac_f32_e32 v18, v137, v19
	v_max_f32_e32 v19, 0, v25
	v_fmac_f32_e32 v18, v136, v19
	v_max_f32_e32 v19, 0, v26
	v_fmac_f32_e32 v18, v135, v19
	v_max_f32_e32 v19, 0, v27
	v_fmac_f32_e32 v18, v134, v19
	v_max_f32_e32 v19, 0, v28
	v_fmac_f32_e32 v18, v133, v19
	v_max_f32_e32 v19, 0, v29
	v_fmac_f32_e32 v18, v132, v19
	v_max_f32_e32 v19, 0, v30
	v_fmac_f32_e32 v18, v131, v19
	v_max_f32_e32 v19, 0, v31
	v_fmac_f32_e32 v18, v130, v19
	v_max_f32_e32 v19, 0, v32
	v_fmac_f32_e32 v18, v129, v19
	v_max_f32_e32 v19, 0, v33
	v_fmac_f32_e32 v18, v128, v19
	v_ashrrev_i32_e32 v19, 31, v18
	v_bitop3_b32 v18, v19, v18, s8 bitop3:0x36
	v_cndmask_b32_e32 v189, 0, v18, vcc
	s_cmp_lt_u32 s0, 0x520
	s_cbranch_scc1 .Lix_z41
.Lix_b41:
	s_cmp_lt_u32 s0, 0x580
	s_cbranch_scc1 .Lix_w41
	s_add_u32 m0, s1, 0
	s_nop 0
	global_load_lds_dwordx4 v112, s[22:23]
	s_add_u32 s22, s22, 0x1e800
	s_addc_u32 s23, s23, 0
	s_add_u32 m0, s1, 0x400
	s_nop 0
	global_load_lds_dwordx4 v113, s[22:23]
	s_add_u32 s22, s22, 0x1e800
	s_addc_u32 s23, s23, 0
	s_add_u32 m0, s1, 0x800
	s_nop 0
	global_load_lds_dwordx4 v112, s[22:23]
	s_add_u32 s22, s22, 0x1e800
	s_addc_u32 s23, s23, 0
	s_add_u32 m0, s1, 0xc00
	s_nop 0
	global_load_lds_dwordx4 v113, s[22:23]
	s_add_u32 s22, s22, 0x1e800
	s_addc_u32 s23, s23, 0
	s_waitcnt vmcnt(8)
	s_branch .Lix_r41

; #define MFMA(a, b, c) __builtin_amdgcn_mfma_f32_32x32x16_bf16((a), (b), (c), 0, 0, 0)
; DI void indexer_phase(const u16* __restrict__ P, unsigned* __restrict__ mask) {
;     ...
;         const u16* kp = P + (brow + 32 * kb + r32) * 7808 + 3584 + 8 * hi;
; #pragma unroll
;         for (int s = 0; s < 4; ++s) { const bf16x8 bk = *(const bf16x8*)(kp + 16 * s); a = MFMA(aq[s], bk, a); }
.Lix_r41:
	s_cmp_lt_u32 s0, 0x540
	s_cbranch_scc1 .Lix_n41
	ds_read_b128 v[64:67], v114 offset:8192
	ds_read_b128 v[68:71], v115 offset:8192
	ds_read_b128 v[72:75], v116 offset:8192
	ds_read_b128 v[76:79], v117 offset:8192
	s_waitcnt lgkmcnt(4)
	s_branch .Lix_m41

; #define MFMA(a, b, c) __builtin_amdgcn_mfma_f32_32x32x16_bf16((a), (b), (c), 0, 0, 0)
; DI unsigned ordkey(float f) { const unsigned b = __float_as_uint(f); return b ^ ((unsigned)((int)b >> 31) | 0x80000000u); }
; DI void indexer_phase(const u16* __restrict__ P, unsigned* __restrict__ mask) {
;     ...
;     for (int kb = 0; kb < 64; ++kb) {
;       unsigned u = 0u;
;       if (kb <= kbmax) {
;         f32x16 a;
; #pragma unroll
;         for (int r = 0; r < 16; ++r) a[r] = 0.f;
;         const u16* kp = P + (brow + 32 * kb + r32) * 7808 + 3584 + 8 * hi;
; #pragma unroll
;         for (int s = 0; s < 4; ++s) { const bf16x8 bk = *(const bf16x8*)(kp + 16 * s); a = MFMA(aq[s], bk, a); }
;         float v = 0.f;
; #pragma unroll
;         for (int i = 0; i < 16; ++i) v = fmaf(wv[i], fmaxf(a[i], 0.f), v);
;         u = (32 * kb + r32 <= tme) ? ordkey(v) : 0u;
;       }
;       sc[kb] = u;
.Lix_m41:
	v_cmp_le_i32_e32 vcc, 0x520, v16
	v_mfma_f32_32x32x16_bf16 v[18:33], v[46:49], v[80:83], 0
	v_mfma_f32_32x32x16_bf16 v[18:33], v[42:45], v[84:87], v[18:33]
	v_mfma_f32_32x32x16_bf16 v[18:33], v[38:41], v[88:91], v[18:33]
	v_mfma_f32_32x32x16_bf16 v[18:33], v[34:37], v[92:95], v[18:33]
	s_nop 11
	v_max_f32_e32 v18, 0, v18
	v_max_f32_e32 v19, 0, v19
	v_fma_f32 v18, v143, v18, 0
	v_fmac_f32_e32 v18, v142, v19
	v_max_f32_e32 v19, 0, v20
	v_fmac_f32_e32 v18, v141, v19
	v_max_f32_e32 v19, 0, v21
	v_fmac_f32_e32 v18, v140, v19
	v_max_f32_e32 v19, 0, v22
	v_fmac_f32_e32 v18, v139, v19
	v_max_f32_e32 v19, 0, v23
	v_fmac_f32_e32 v18, v138, v19
	v_max_f32_e32 v19, 0, v24
	v_fmac_f32_e32 v18, v137, v19
	v_max_f32_e32 v19, 0, v25
	v_fmac_f32_e32 v18, v136, v19
	v_max_f32_e32 v19, 0, v26
	v_fmac_f32_e32 v18, v135, v19
	v_max_f32_e32 v19, 0, v27
	v_fmac_f32_e32 v18, v134, v19
	v_max_f32_e32 v19, 0, v28
	v_fmac_f32_e32 v18, v133, v19
	v_max_f32_e32 v19, 0, v29
	v_fmac_f32_e32 v18, v132, v19
	v_max_f32_e32 v19, 0, v30
	v_fmac_f32_e32 v18, v131, v19
	v_max_f32_e32 v19, 0, v31
	v_fmac_f32_e32 v18, v130, v19
	v_max_f32_e32 v19, 0, v32
	v_fmac_f32_e32 v18, v129, v19
	v_max_f32_e32 v19, 0, v33
	v_fmac_f32_e32 v18, v128, v19
	v_ashrrev_i32_e32 v19, 31, v18
	v_bitop3_b32 v18, v19, v18, s8 bitop3:0x36
	v_cndmask_b32_e32 v192, 0, v18, vcc
	s_cmp_lt_u32 s0, 0x540
	s_cbranch_scc1 .Lix_z42
.Lix_b42:
	s_cmp_lt_u32 s0, 0x5a0
	s_cbranch_scc1 .Lix_w42
	s_add_u32 m0, s1, 0x1000
	s_nop 0
	global_load_lds_dwordx4 v112, s[22:23]
	s_add_u32 s22, s22, 0x1e800
	s_addc_u32 s23, s23, 0
	s_add_u32 m0, s1, 0x1400
	s_nop 0
	global_load_lds_dwordx4 v113, s[22:23]
	s_add_u32 s22, s22, 0x1e800
	s_addc_u32 s23, s23, 0
	s_add_u32 m0, s1, 0x1800
	s_nop 0
	global_load_lds_dwordx4 v112, s[22:23]
	s_add_u32 s22, s22, 0x1e800
	s_addc_u32 s23, s23, 0
	s_add_u32 m0, s1, 0x1c00
	s_nop 0
	global_load_lds_dwordx4 v113, s[22:23]
	s_add_u32 s22, s22, 0x1e800
	s_addc_u32 s23, s23, 0
	s_waitcnt vmcnt(8)
	s_branch .Lix_r42

; #define MFMA(a, b, c) __builtin_amdgcn_mfma_f32_32x32x16_bf16((a), (b), (c), 0, 0, 0)
; DI void indexer_phase(const u16* __restrict__ P, unsigned* __restrict__ mask) {
;     ...
;         const u16* kp = P + (brow + 32 * kb + r32) * 7808 + 3584 + 8 * hi;
; #pragma unroll
;         for (int s = 0; s < 4; ++s) { const bf16x8 bk = *(const bf16x8*)(kp + 16 * s); a = MFMA(aq[s], bk, a); }
.Lix_r42:
	s_cmp_lt_u32 s0, 0x560
	s_cbranch_scc1 .Lix_n42
	ds_read_b128 v[80:83], v114 offset:12288
	ds_read_b128 v[84:87], v115 offset:12288
	ds_read_b128 v[88:91], v116 offset:12288
	ds_read_b128 v[92:95], v117 offset:12288
	s_waitcnt lgkmcnt(4)
	s_branch .Lix_m42

; #define MFMA(a, b, c) __builtin_amdgcn_mfma_f32_32x32x16_bf16((a), (b), (c), 0, 0, 0)
; DI unsigned ordkey(float f) { const unsigned b = __float_as_uint(f); return b ^ ((unsigned)((int)b >> 31) | 0x80000000u); }
; DI void indexer_phase(const u16* __restrict__ P, unsigned* __restrict__ mask) {
;     ...
;     for (int kb = 0; kb < 64; ++kb) {
;       unsigned u = 0u;
;       if (kb <= kbmax) {
;         f32x16 a;
; #pragma unroll
;         for (int r = 0; r < 16; ++r) a[r] = 0.f;
;         const u16* kp = P + (brow + 32 * kb + r32) * 7808 + 3584 + 8 * hi;
; #pragma unroll
;         for (int s = 0; s < 4; ++s) { const bf16x8 bk = *(const bf16x8*)(kp + 16 * s); a = MFMA(aq[s], bk, a); }
;         float v = 0.f;
; #pragma unroll
;         for (int i = 0; i < 16; ++i) v = fmaf(wv[i], fmaxf(a[i], 0.f), v);
;         u = (32 * kb + r32 <= tme) ? ordkey(v) : 0u;
;       }
;       sc[kb] = u;
.Lix_m42:
	v_cmp_le_i32_e32 vcc, 0x540, v16
	v_mfma_f32_32x32x16_bf16 v[18:33], v[46:49], v[64:67], 0
	v_mfma_f32_32x32x16_bf16 v[18:33], v[42:45], v[68:71], v[18:33]
	v_mfma_f32_32x32x16_bf16 v[18:33], v[38:41], v[72:75], v[18:33]
	v_mfma_f32_32x32x16_bf16 v[18:33], v[34:37], v[76:79], v[18:33]
	s_nop 11
	v_max_f32_e32 v18, 0, v18
	v_max_f32_e32 v19, 0, v19
	v_fma_f32 v18, v143, v18, 0
	v_fmac_f32_e32 v18, v142, v19
	v_max_f32_e32 v19, 0, v20
	v_fmac_f32_e32 v18, v141, v19
	v_max_f32_e32 v19, 0, v21
	v_fmac_f32_e32 v18, v140, v19
	v_max_f32_e32 v19, 0, v22
	v_fmac_f32_e32 v18, v139, v19
	v_max_f32_e32 v19, 0, v23
	v_fmac_f32_e32 v18, v138, v19
	v_max_f32_e32 v19, 0, v24
	v_fmac_f32_e32 v18, v137, v19
	v_max_f32_e32 v19, 0, v25
	v_fmac_f32_e32 v18, v136, v19
	v_max_f32_e32 v19, 0, v26
	v_fmac_f32_e32 v18, v135, v19
	v_max_f32_e32 v19, 0, v27
	v_fmac_f32_e32 v18, v134, v19
	v_max_f32_e32 v19, 0, v28
	v_fmac_f32_e32 v18, v133, v19
	v_max_f32_e32 v19, 0, v29
	v_fmac_f32_e32 v18, v132, v19
	v_max_f32_e32 v19, 0, v30
	v_fmac_f32_e32 v18, v131, v19
	v_max_f32_e32 v19, 0, v31
	v_fmac_f32_e32 v18, v130, v19
	v_max_f32_e32 v19, 0, v32
	v_fmac_f32_e32 v18, v129, v19
	v_max_f32_e32 v19, 0, v33
	v_fmac_f32_e32 v18, v128, v19
	v_ashrrev_i32_e32 v19, 31, v18
	v_bitop3_b32 v18, v19, v18, s8 bitop3:0x36
	v_cndmask_b32_e32 v191, 0, v18, vcc
	s_cmp_lt_u32 s0, 0x560
	s_cbranch_scc1 .Lix_z43
.Lix_b43:
	s_cmp_lt_u32 s0, 0x5c0
	s_cbranch_scc1 .Lix_w43
	s_add_u32 m0, s1, 0x2000
	s_nop 0
	global_load_lds_dwordx4 v112, s[22:23]
	s_add_u32 s22, s22, 0x1e800
	s_addc_u32 s23, s23, 0
	s_add_u32 m0, s1, 0x2400
	s_nop 0
	global_load_lds_dwordx4 v113, s[22:23]
	s_add_u32 s22, s22, 0x1e800
	s_addc_u32 s23, s23, 0
	s_add_u32 m0, s1, 0x2800
	s_nop 0
	global_load_lds_dwordx4 v112, s[22:23]
	s_add_u32 s22, s22, 0x1e800
	s_addc_u32 s23, s23, 0
	s_add_u32 m0, s1, 0x2c00
	s_nop 0
	global_load_lds_dwordx4 v113, s[22:23]
	s_add_u32 s22, s22, 0x1e800
	s_addc_u32 s23, s23, 0
	s_waitcnt vmcnt(8)
	s_branch .Lix_r43

; #define MFMA(a, b, c) __builtin_amdgcn_mfma_f32_32x32x16_bf16((a), (b), (c), 0, 0, 0)
; DI void indexer_phase(const u16* __restrict__ P, unsigned* __restrict__ mask) {
;     ...
;         const u16* kp = P + (brow + 32 * kb + r32) * 7808 + 3584 + 8 * hi;
; #pragma unroll
;         for (int s = 0; s < 4; ++s) { const bf16x8 bk = *(const bf16x8*)(kp + 16 * s); a = MFMA(aq[s], bk, a); }
.Lix_r43:
	s_cmp_lt_u32 s0, 0x580
	s_cbranch_scc1 .Lix_n43
	ds_read_b128 v[64:67], v114
	ds_read_b128 v[68:71], v115
	ds_read_b128 v[72:75], v116
	ds_read_b128 v[76:79], v117
	s_waitcnt lgkmcnt(4)
	s_branch .Lix_m43

; #define MFMA(a, b, c) __builtin_amdgcn_mfma_f32_32x32x16_bf16((a), (b), (c), 0, 0, 0)
; DI unsigned ordkey(float f) { const unsigned b = __float_as_uint(f); return b ^ ((unsigned)((int)b >> 31) | 0x80000000u); }
; DI void indexer_phase(const u16* __restrict__ P, unsigned* __restrict__ mask) {
;     ...
;     for (int kb = 0; kb < 64; ++kb) {
;       unsigned u = 0u;
;       if (kb <= kbmax) {
;         f32x16 a;
; #pragma unroll
;         for (int r = 0; r < 16; ++r) a[r] = 0.f;
;         const u16* kp = P + (brow + 32 * kb + r32) * 7808 + 3584 + 8 * hi;
; #pragma unroll
;         for (int s = 0; s < 4; ++s) { const bf16x8 bk = *(const bf16x8*)(kp + 16 * s); a = MFMA(aq[s], bk, a); }
;         float v = 0.f;
; #pragma unroll
;         for (int i = 0; i < 16; ++i) v = fmaf(wv[i], fmaxf(a[i], 0.f), v);
;         u = (32 * kb + r32 <= tme) ? ordkey(v) : 0u;
;       }
;       sc[kb] = u;
.Lix_m43:
	v_cmp_le_i32_e32 vcc, 0x560, v16
	v_mfma_f32_32x32x16_bf16 v[18:33], v[46:49], v[80:83], 0
	v_mfma_f32_32x32x16_bf16 v[18:33], v[42:45], v[84:87], v[18:33]
	v_mfma_f32_32x32x16_bf16 v[18:33], v[38:41], v[88:91], v[18:33]
	v_mfma_f32_32x32x16_bf16 v[18:33], v[34:37], v[92:95], v[18:33]
	s_nop 11
	v_max_f32_e32 v18, 0, v18
	v_max_f32_e32 v19, 0, v19
	v_fma_f32 v18, v143, v18, 0
	v_fmac_f32_e32 v18, v142, v19
	v_max_f32_e32 v19, 0, v20
	v_fmac_f32_e32 v18, v141, v19
	v_max_f32_e32 v19, 0, v21
	v_fmac_f32_e32 v18, v140, v19
	v_max_f32_e32 v19, 0, v22
	v_fmac_f32_e32 v18, v139, v19
	v_max_f32_e32 v19, 0, v23
	v_fmac_f32_e32 v18, v138, v19
	v_max_f32_e32 v19, 0, v24
	v_fmac_f32_e32 v18, v137, v19
	v_max_f32_e32 v19, 0, v25
	v_fmac_f32_e32 v18, v136, v19
	v_max_f32_e32 v19, 0, v26
	v_fmac_f32_e32 v18, v135, v19
	v_max_f32_e32 v19, 0, v27
	v_fmac_f32_e32 v18, v134, v19
	v_max_f32_e32 v19, 0, v28
	v_fmac_f32_e32 v18, v133, v19
	v_max_f32_e32 v19, 0, v29
	v_fmac_f32_e32 v18, v132, v19
	v_max_f32_e32 v19, 0, v30
	v_fmac_f32_e32 v18, v131, v19
	v_max_f32_e32 v19, 0, v31
	v_fmac_f32_e32 v18, v130, v19
	v_max_f32_e32 v19, 0, v32
	v_fmac_f32_e32 v18, v129, v19
	v_max_f32_e32 v19, 0, v33
	v_fmac_f32_e32 v18, v128, v19
	v_ashrrev_i32_e32 v19, 31, v18
	v_bitop3_b32 v18, v19, v18, s8 bitop3:0x36
	v_cndmask_b32_e32 v194, 0, v18, vcc
	s_cmp_lt_u32 s0, 0x580
	s_cbranch_scc1 .Lix_z44
.Lix_b44:
	s_cmp_lt_u32 s0, 0x5e0
	s_cbranch_scc1 .Lix_w44
	s_add_u32 m0, s1, 0x3000
	s_nop 0
	global_load_lds_dwordx4 v112, s[22:23]
	s_add_u32 s22, s22, 0x1e800
	s_addc_u32 s23, s23, 0
	s_add_u32 m0, s1, 0x3400
	s_nop 0
	global_load_lds_dwordx4 v113, s[22:23]
	s_add_u32 s22, s22, 0x1e800
	s_addc_u32 s23, s23, 0
	s_add_u32 m0, s1, 0x3800
	s_nop 0
	global_load_lds_dwordx4 v112, s[22:23]
	s_add_u32 s22, s22, 0x1e800
	s_addc_u32 s23, s23, 0
	s_add_u32 m0, s1, 0x3c00
	s_nop 0
	global_load_lds_dwordx4 v113, s[22:23]
	s_add_u32 s22, s22, 0x1e800
	s_addc_u32 s23, s23, 0
	s_waitcnt vmcnt(8)
	s_branch .Lix_r44

; #define MFMA(a, b, c) __builtin_amdgcn_mfma_f32_32x32x16_bf16((a), (b), (c), 0, 0, 0)
; DI void indexer_phase(const u16* __restrict__ P, unsigned* __restrict__ mask) {
;     ...
;         const u16* kp = P + (brow + 32 * kb + r32) * 7808 + 3584 + 8 * hi;
; #pragma unroll
;         for (int s = 0; s < 4; ++s) { const bf16x8 bk = *(const bf16x8*)(kp + 16 * s); a = MFMA(aq[s], bk, a); }
.Lix_r44:
	s_cmp_lt_u32 s0, 0x5a0
	s_cbranch_scc1 .Lix_n44
	ds_read_b128 v[80:83], v114 offset:4096
	ds_read_b128 v[84:87], v115 offset:4096
	ds_read_b128 v[88:91], v116 offset:4096
	ds_read_b128 v[92:95], v117 offset:4096
	s_waitcnt lgkmcnt(4)
	s_branch .Lix_m44

; #define MFMA(a, b, c) __builtin_amdgcn_mfma_f32_32x32x16_bf16((a), (b), (c), 0, 0, 0)
; DI unsigned ordkey(float f) { const unsigned b = __float_as_uint(f); return b ^ ((unsigned)((int)b >> 31) | 0x80000000u); }
; DI void indexer_phase(const u16* __restrict__ P, unsigned* __restrict__ mask) {
;     ...
;     for (int kb = 0; kb < 64; ++kb) {
;       unsigned u = 0u;
;       if (kb <= kbmax) {
;         f32x16 a;
; #pragma unroll
;         for (int r = 0; r < 16; ++r) a[r] = 0.f;
;         const u16* kp = P + (brow + 32 * kb + r32) * 7808 + 3584 + 8 * hi;
; #pragma unroll
;         for (int s = 0; s < 4; ++s) { const bf16x8 bk = *(const bf16x8*)(kp + 16 * s); a = MFMA(aq[s], bk, a); }
;         float v = 0.f;
; #pragma unroll
;         for (int i = 0; i < 16; ++i) v = fmaf(wv[i], fmaxf(a[i], 0.f), v);
;         u = (32 * kb + r32 <= tme) ? ordkey(v) : 0u;
;       }
;       sc[kb] = u;
.Lix_m44:
	v_cmp_le_i32_e32 vcc, 0x580, v16
	v_mfma_f32_32x32x16_bf16 v[18:33], v[46:49], v[64:67], 0
	v_mfma_f32_32x32x16_bf16 v[18:33], v[42:45], v[68:71], v[18:33]
	v_mfma_f32_32x32x16_bf16 v[18:33], v[38:41], v[72:75], v[18:33]
	v_mfma_f32_32x32x16_bf16 v[18:33], v[34:37], v[76:79], v[18:33]
	s_nop 11
	v_max_f32_e32 v18, 0, v18
	v_max_f32_e32 v19, 0, v19
	v_fma_f32 v18, v143, v18, 0
	v_fmac_f32_e32 v18, v142, v19
	v_max_f32_e32 v19, 0, v20
	v_fmac_f32_e32 v18, v141, v19
	v_max_f32_e32 v19, 0, v21
	v_fmac_f32_e32 v18, v140, v19
	v_max_f32_e32 v19, 0, v22
	v_fmac_f32_e32 v18, v139, v19
	v_max_f32_e32 v19, 0, v23
	v_fmac_f32_e32 v18, v138, v19
	v_max_f32_e32 v19, 0, v24
	v_fmac_f32_e32 v18, v137, v19
	v_max_f32_e32 v19, 0, v25
	v_fmac_f32_e32 v18, v136, v19
	v_max_f32_e32 v19, 0, v26
	v_fmac_f32_e32 v18, v135, v19
	v_max_f32_e32 v19, 0, v27
	v_fmac_f32_e32 v18, v134, v19
	v_max_f32_e32 v19, 0, v28
	v_fmac_f32_e32 v18, v133, v19
	v_max_f32_e32 v19, 0, v29
	v_fmac_f32_e32 v18, v132, v19
	v_max_f32_e32 v19, 0, v30
	v_fmac_f32_e32 v18, v131, v19
	v_max_f32_e32 v19, 0, v31
	v_fmac_f32_e32 v18, v130, v19
	v_max_f32_e32 v19, 0, v32
	v_fmac_f32_e32 v18, v129, v19
	v_max_f32_e32 v19, 0, v33
	v_fmac_f32_e32 v18, v128, v19
	v_ashrrev_i32_e32 v19, 31, v18
	v_bitop3_b32 v18, v19, v18, s8 bitop3:0x36
	v_cndmask_b32_e32 v193, 0, v18, vcc
	s_cmp_lt_u32 s0, 0x5a0
	s_cbranch_scc1 .Lix_z45
.Lix_b45:
	s_cmp_lt_u32 s0, 0x600
	s_cbranch_scc1 .Lix_w45
	s_add_u32 m0, s1, 0
	s_nop 0
	global_load_lds_dwordx4 v112, s[22:23]
	s_add_u32 s22, s22, 0x1e800
	s_addc_u32 s23, s23, 0
	s_add_u32 m0, s1, 0x400
	s_nop 0
	global_load_lds_dwordx4 v113, s[22:23]
	s_add_u32 s22, s22, 0x1e800
	s_addc_u32 s23, s23, 0
	s_add_u32 m0, s1, 0x800
	s_nop 0
	global_load_lds_dwordx4 v112, s[22:23]
	s_add_u32 s22, s22, 0x1e800
	s_addc_u32 s23, s23, 0
	s_add_u32 m0, s1, 0xc00
	s_nop 0
	global_load_lds_dwordx4 v113, s[22:23]
	s_add_u32 s22, s22, 0x1e800
	s_addc_u32 s23, s23, 0
	s_waitcnt vmcnt(8)
	s_branch .Lix_r45

; #define MFMA(a, b, c) __builtin_amdgcn_mfma_f32_32x32x16_bf16((a), (b), (c), 0, 0, 0)
; DI void indexer_phase(const u16* __restrict__ P, unsigned* __restrict__ mask) {
;     ...
;         const u16* kp = P + (brow + 32 * kb + r32) * 7808 + 3584 + 8 * hi;
; #pragma unroll
;         for (int s = 0; s < 4; ++s) { const bf16x8 bk = *(const bf16x8*)(kp + 16 * s); a = MFMA(aq[s], bk, a); }
.Lix_r45:
	s_cmp_lt_u32 s0, 0x5c0
	s_cbranch_scc1 .Lix_n45
	ds_read_b128 v[64:67], v114 offset:8192
	ds_read_b128 v[68:71], v115 offset:8192
	ds_read_b128 v[72:75], v116 offset:8192
	ds_read_b128 v[76:79], v117 offset:8192
	s_waitcnt lgkmcnt(4)
	s_branch .Lix_m45

; #define MFMA(a, b, c) __builtin_amdgcn_mfma_f32_32x32x16_bf16((a), (b), (c), 0, 0, 0)
; DI unsigned ordkey(float f) { const unsigned b = __float_as_uint(f); return b ^ ((unsigned)((int)b >> 31) | 0x80000000u); }
; DI void indexer_phase(const u16* __restrict__ P, unsigned* __restrict__ mask) {
;     ...
;     for (int kb = 0; kb < 64; ++kb) {
;       unsigned u = 0u;
;       if (kb <= kbmax) {
;         f32x16 a;
; #pragma unroll
;         for (int r = 0; r < 16; ++r) a[r] = 0.f;
;         const u16* kp = P + (brow + 32 * kb + r32) * 7808 + 3584 + 8 * hi;
; #pragma unroll
;         for (int s = 0; s < 4; ++s) { const bf16x8 bk = *(const bf16x8*)(kp + 16 * s); a = MFMA(aq[s], bk, a); }
;         float v = 0.f;
; #pragma unroll
;         for (int i = 0; i < 16; ++i) v = fmaf(wv[i], fmaxf(a[i], 0.f), v);
;         u = (32 * kb + r32 <= tme) ? ordkey(v) : 0u;
;       }
;       sc[kb] = u;
.Lix_m45:
	v_cmp_le_i32_e32 vcc, 0x5a0, v16
	v_mfma_f32_32x32x16_bf16 v[18:33], v[46:49], v[80:83], 0
	v_mfma_f32_32x32x16_bf16 v[18:33], v[42:45], v[84:87], v[18:33]
	v_mfma_f32_32x32x16_bf16 v[18:33], v[38:41], v[88:91], v[18:33]
	v_mfma_f32_32x32x16_bf16 v[18:33], v[34:37], v[92:95], v[18:33]
	s_nop 11
	v_max_f32_e32 v18, 0, v18
	v_max_f32_e32 v19, 0, v19
	v_fma_f32 v18, v143, v18, 0
	v_fmac_f32_e32 v18, v142, v19
	v_max_f32_e32 v19, 0, v20
	v_fmac_f32_e32 v18, v141, v19
	v_max_f32_e32 v19, 0, v21
	v_fmac_f32_e32 v18, v140, v19
	v_max_f32_e32 v19, 0, v22
	v_fmac_f32_e32 v18, v139, v19
	v_max_f32_e32 v19, 0, v23
	v_fmac_f32_e32 v18, v138, v19
	v_max_f32_e32 v19, 0, v24
	v_fmac_f32_e32 v18, v137, v19
	v_max_f32_e32 v19, 0, v25
	v_fmac_f32_e32 v18, v136, v19
	v_max_f32_e32 v19, 0, v26
	v_fmac_f32_e32 v18, v135, v19
	v_max_f32_e32 v19, 0, v27
	v_fmac_f32_e32 v18, v134, v19
	v_max_f32_e32 v19, 0, v28
	v_fmac_f32_e32 v18, v133, v19
	v_max_f32_e32 v19, 0, v29
	v_fmac_f32_e32 v18, v132, v19
	v_max_f32_e32 v19, 0, v30
	v_fmac_f32_e32 v18, v131, v19
	v_max_f32_e32 v19, 0, v31
	v_fmac_f32_e32 v18, v130, v19
	v_max_f32_e32 v19, 0, v32
	v_fmac_f32_e32 v18, v129, v19
	v_max_f32_e32 v19, 0, v33
	v_fmac_f32_e32 v18, v128, v19
	v_ashrrev_i32_e32 v19, 31, v18
	v_bitop3_b32 v18, v19, v18, s8 bitop3:0x36
	v_cndmask_b32_e32 v196, 0, v18, vcc
	s_cmp_lt_u32 s0, 0x5c0
	s_cbranch_scc1 .Lix_z46
.Lix_b46:
	s_cmp_lt_u32 s0, 0x620
	s_cbranch_scc1 .Lix_w46
	s_add_u32 m0, s1, 0x1000
	s_nop 0
	global_load_lds_dwordx4 v112, s[22:23]
	s_add_u32 s22, s22, 0x1e800
	s_addc_u32 s23, s23, 0
	s_add_u32 m0, s1, 0x1400
	s_nop 0
	global_load_lds_dwordx4 v113, s[22:23]
	s_add_u32 s22, s22, 0x1e800
	s_addc_u32 s23, s23, 0
	s_add_u32 m0, s1, 0x1800
	s_nop 0
	global_load_lds_dwordx4 v112, s[22:23]
	s_add_u32 s22, s22, 0x1e800
	s_addc_u32 s23, s23, 0
	s_add_u32 m0, s1, 0x1c00
	s_nop 0
	global_load_lds_dwordx4 v113, s[22:23]
	s_add_u32 s22, s22, 0x1e800
	s_addc_u32 s23, s23, 0
	s_waitcnt vmcnt(8)
	s_branch .Lix_r46

; #define MFMA(a, b, c) __builtin_amdgcn_mfma_f32_32x32x16_bf16((a), (b), (c), 0, 0, 0)
; DI void indexer_phase(const u16* __restrict__ P, unsigned* __restrict__ mask) {
;     ...
;         const u16* kp = P + (brow + 32 * kb + r32) * 7808 + 3584 + 8 * hi;
; #pragma unroll
;         for (int s = 0; s < 4; ++s) { const bf16x8 bk = *(const bf16x8*)(kp + 16 * s); a = MFMA(aq[s], bk, a); }
.Lix_r46:
	s_cmp_lt_u32 s0, 0x5e0
	s_cbranch_scc1 .Lix_n46
	ds_read_b128 v[80:83], v114 offset:12288
	ds_read_b128 v[84:87], v115 offset:12288
	ds_read_b128 v[88:91], v116 offset:12288
	ds_read_b128 v[92:95], v117 offset:12288
	s_waitcnt lgkmcnt(4)
	s_branch .Lix_m46

; #define MFMA(a, b, c) __builtin_amdgcn_mfma_f32_32x32x16_bf16((a), (b), (c), 0, 0, 0)
; DI unsigned ordkey(float f) { const unsigned b = __float_as_uint(f); return b ^ ((unsigned)((int)b >> 31) | 0x80000000u); }
; DI void indexer_phase(const u16* __restrict__ P, unsigned* __restrict__ mask) {
;     ...
;     for (int kb = 0; kb < 64; ++kb) {
;       unsigned u = 0u;
;       if (kb <= kbmax) {
;         f32x16 a;
; #pragma unroll
;         for (int r = 0; r < 16; ++r) a[r] = 0.f;
;         const u16* kp = P + (brow + 32 * kb + r32) * 7808 + 3584 + 8 * hi;
; #pragma unroll
;         for (int s = 0; s < 4; ++s) { const bf16x8 bk = *(const bf16x8*)(kp + 16 * s); a = MFMA(aq[s], bk, a); }
;         float v = 0.f;
; #pragma unroll
;         for (int i = 0; i < 16; ++i) v = fmaf(wv[i], fmaxf(a[i], 0.f), v);
;         u = (32 * kb + r32 <= tme) ? ordkey(v) : 0u;
;       }
;       sc[kb] = u;
.Lix_m46:
	v_cmp_le_i32_e32 vcc, 0x5c0, v16
	v_mfma_f32_32x32x16_bf16 v[18:33], v[46:49], v[64:67], 0
	v_mfma_f32_32x32x16_bf16 v[18:33], v[42:45], v[68:71], v[18:33]
	v_mfma_f32_32x32x16_bf16 v[18:33], v[38:41], v[72:75], v[18:33]
	v_mfma_f32_32x32x16_bf16 v[18:33], v[34:37], v[76:79], v[18:33]
	s_nop 11
	v_max_f32_e32 v18, 0, v18
	v_max_f32_e32 v19, 0, v19
	v_fma_f32 v18, v143, v18, 0
	v_fmac_f32_e32 v18, v142, v19
	v_max_f32_e32 v19, 0, v20
	v_fmac_f32_e32 v18, v141, v19
	v_max_f32_e32 v19, 0, v21
	v_fmac_f32_e32 v18, v140, v19
	v_max_f32_e32 v19, 0, v22
	v_fmac_f32_e32 v18, v139, v19
	v_max_f32_e32 v19, 0, v23
	v_fmac_f32_e32 v18, v138, v19
	v_max_f32_e32 v19, 0, v24
	v_fmac_f32_e32 v18, v137, v19
	v_max_f32_e32 v19, 0, v25
	v_fmac_f32_e32 v18, v136, v19
	v_max_f32_e32 v19, 0, v26
	v_fmac_f32_e32 v18, v135, v19
	v_max_f32_e32 v19, 0, v27
	v_fmac_f32_e32 v18, v134, v19
	v_max_f32_e32 v19, 0, v28
	v_fmac_f32_e32 v18, v133, v19
	v_max_f32_e32 v19, 0, v29
	v_fmac_f32_e32 v18, v132, v19
	v_max_f32_e32 v19, 0, v30
	v_fmac_f32_e32 v18, v131, v19
	v_max_f32_e32 v19, 0, v31
	v_fmac_f32_e32 v18, v130, v19
	v_max_f32_e32 v19, 0, v32
	v_fmac_f32_e32 v18, v129, v19
	v_max_f32_e32 v19, 0, v33
	v_fmac_f32_e32 v18, v128, v19
	v_ashrrev_i32_e32 v19, 31, v18
	v_bitop3_b32 v18, v19, v18, s8 bitop3:0x36
	v_cndmask_b32_e32 v195, 0, v18, vcc
	s_cmp_lt_u32 s0, 0x5e0
	s_cbranch_scc1 .Lix_z47
.Lix_b47:
	s_cmp_lt_u32 s0, 0x640
	s_cbranch_scc1 .Lix_w47
	s_add_u32 m0, s1, 0x2000
	s_nop 0
	global_load_lds_dwordx4 v112, s[22:23]
	s_add_u32 s22, s22, 0x1e800
	s_addc_u32 s23, s23, 0
	s_add_u32 m0, s1, 0x2400
	s_nop 0
	global_load_lds_dwordx4 v113, s[22:23]
	s_add_u32 s22, s22, 0x1e800
	s_addc_u32 s23, s23, 0
	s_add_u32 m0, s1, 0x2800
	s_nop 0
	global_load_lds_dwordx4 v112, s[22:23]
	s_add_u32 s22, s22, 0x1e800
	s_addc_u32 s23, s23, 0
	s_add_u32 m0, s1, 0x2c00
	s_nop 0
	global_load_lds_dwordx4 v113, s[22:23]
	s_add_u32 s22, s22, 0x1e800
	s_addc_u32 s23, s23, 0
	s_waitcnt vmcnt(8)
	s_branch .Lix_r47

; #define MFMA(a, b, c) __builtin_amdgcn_mfma_f32_32x32x16_bf16((a), (b), (c), 0, 0, 0)
; DI void indexer_phase(const u16* __restrict__ P, unsigned* __restrict__ mask) {
;     ...
;         const u16* kp = P + (brow + 32 * kb + r32) * 7808 + 3584 + 8 * hi;
; #pragma unroll
;         for (int s = 0; s < 4; ++s) { const bf16x8 bk = *(const bf16x8*)(kp + 16 * s); a = MFMA(aq[s], bk, a); }
.Lix_r47:
	s_cmp_lt_u32 s0, 0x600
	s_cbranch_scc1 .Lix_n47
	ds_read_b128 v[64:67], v114
	ds_read_b128 v[68:71], v115
	ds_read_b128 v[72:75], v116
	ds_read_b128 v[76:79], v117
	s_waitcnt lgkmcnt(4)
	s_branch .Lix_m47

; #define MFMA(a, b, c) __builtin_amdgcn_mfma_f32_32x32x16_bf16((a), (b), (c), 0, 0, 0)
; DI unsigned ordkey(float f) { const unsigned b = __float_as_uint(f); return b ^ ((unsigned)((int)b >> 31) | 0x80000000u); }
; DI void indexer_phase(const u16* __restrict__ P, unsigned* __restrict__ mask) {
;     ...
;     for (int kb = 0; kb < 64; ++kb) {
;       unsigned u = 0u;
;       if (kb <= kbmax) {
;         f32x16 a;
; #pragma unroll
;         for (int r = 0; r < 16; ++r) a[r] = 0.f;
;         const u16* kp = P + (brow + 32 * kb + r32) * 7808 + 3584 + 8 * hi;
; #pragma unroll
;         for (int s = 0; s < 4; ++s) { const bf16x8 bk = *(const bf16x8*)(kp + 16 * s); a = MFMA(aq[s], bk, a); }
;         float v = 0.f;
; #pragma unroll
;         for (int i = 0; i < 16; ++i) v = fmaf(wv[i], fmaxf(a[i], 0.f), v);
;         u = (32 * kb + r32 <= tme) ? ordkey(v) : 0u;
;       }
;       sc[kb] = u;
.Lix_m47:
	v_cmp_le_i32_e32 vcc, 0x5e0, v16
	v_mfma_f32_32x32x16_bf16 v[18:33], v[46:49], v[80:83], 0
	v_mfma_f32_32x32x16_bf16 v[18:33], v[42:45], v[84:87], v[18:33]
	v_mfma_f32_32x32x16_bf16 v[18:33], v[38:41], v[88:91], v[18:33]
	v_mfma_f32_32x32x16_bf16 v[18:33], v[34:37], v[92:95], v[18:33]
	s_nop 11
	v_max_f32_e32 v18, 0, v18
	v_max_f32_e32 v19, 0, v19
	v_fma_f32 v18, v143, v18, 0
	v_fmac_f32_e32 v18, v142, v19
	v_max_f32_e32 v19, 0, v20
	v_fmac_f32_e32 v18, v141, v19
	v_max_f32_e32 v19, 0, v21
	v_fmac_f32_e32 v18, v140, v19
	v_max_f32_e32 v19, 0, v22
	v_fmac_f32_e32 v18, v139, v19
	v_max_f32_e32 v19, 0, v23
	v_fmac_f32_e32 v18, v138, v19
	v_max_f32_e32 v19, 0, v24
	v_fmac_f32_e32 v18, v137, v19
	v_max_f32_e32 v19, 0, v25
	v_fmac_f32_e32 v18, v136, v19
	v_max_f32_e32 v19, 0, v26
	v_fmac_f32_e32 v18, v135, v19
	v_max_f32_e32 v19, 0, v27
	v_fmac_f32_e32 v18, v134, v19
	v_max_f32_e32 v19, 0, v28
	v_fmac_f32_e32 v18, v133, v19
	v_max_f32_e32 v19, 0, v29
	v_fmac_f32_e32 v18, v132, v19
	v_max_f32_e32 v19, 0, v30
	v_fmac_f32_e32 v18, v131, v19
	v_max_f32_e32 v19, 0, v31
	v_fmac_f32_e32 v18, v130, v19
	v_max_f32_e32 v19, 0, v32
	v_fmac_f32_e32 v18, v129, v19
	v_max_f32_e32 v19, 0, v33
	v_fmac_f32_e32 v18, v128, v19
	v_ashrrev_i32_e32 v19, 31, v18
	v_bitop3_b32 v18, v19, v18, s8 bitop3:0x36
	v_cndmask_b32_e32 v198, 0, v18, vcc
	s_cmp_lt_u32 s0, 0x600
	s_cbranch_scc1 .Lix_z48
.Lix_b48:
	s_cmp_lt_u32 s0, 0x660
	s_cbranch_scc1 .Lix_w48
	s_add_u32 m0, s1, 0x3000
	s_nop 0
	global_load_lds_dwordx4 v112, s[22:23]
	s_add_u32 s22, s22, 0x1e800
	s_addc_u32 s23, s23, 0
	s_add_u32 m0, s1, 0x3400
	s_nop 0
	global_load_lds_dwordx4 v113, s[22:23]
	s_add_u32 s22, s22, 0x1e800
	s_addc_u32 s23, s23, 0
	s_add_u32 m0, s1, 0x3800
	s_nop 0
	global_load_lds_dwordx4 v112, s[22:23]
	s_add_u32 s22, s22, 0x1e800
	s_addc_u32 s23, s23, 0
	s_add_u32 m0, s1, 0x3c00
	s_nop 0
	global_load_lds_dwordx4 v113, s[22:23]
	s_add_u32 s22, s22, 0x1e800
	s_addc_u32 s23, s23, 0
	s_waitcnt vmcnt(8)
	s_branch .Lix_r48

; #define MFMA(a, b, c) __builtin_amdgcn_mfma_f32_32x32x16_bf16((a), (b), (c), 0, 0, 0)
; DI void indexer_phase(const u16* __restrict__ P, unsigned* __restrict__ mask) {
;     ...
;         const u16* kp = P + (brow + 32 * kb + r32) * 7808 + 3584 + 8 * hi;
; #pragma unroll
;         for (int s = 0; s < 4; ++s) { const bf16x8 bk = *(const bf16x8*)(kp + 16 * s); a = MFMA(aq[s], bk, a); }
.Lix_r48:
	s_cmp_lt_u32 s0, 0x620
	s_cbranch_scc1 .Lix_n48
	ds_read_b128 v[80:83], v114 offset:4096
	ds_read_b128 v[84:87], v115 offset:4096
	ds_read_b128 v[88:91], v116 offset:4096
	ds_read_b128 v[92:95], v117 offset:4096
	s_waitcnt lgkmcnt(4)
	s_branch .Lix_m48

; #define MFMA(a, b, c) __builtin_amdgcn_mfma_f32_32x32x16_bf16((a), (b), (c), 0, 0, 0)
; DI unsigned ordkey(float f) { const unsigned b = __float_as_uint(f); return b ^ ((unsigned)((int)b >> 31) | 0x80000000u); }
; DI void indexer_phase(const u16* __restrict__ P, unsigned* __restrict__ mask) {
;     ...
;     for (int kb = 0; kb < 64; ++kb) {
;       unsigned u = 0u;
;       if (kb <= kbmax) {
;         f32x16 a;
; #pragma unroll
;         for (int r = 0; r < 16; ++r) a[r] = 0.f;
;         const u16* kp = P + (brow + 32 * kb + r32) * 7808 + 3584 + 8 * hi;
; #pragma unroll
;         for (int s = 0; s < 4; ++s) { const bf16x8 bk = *(const bf16x8*)(kp + 16 * s); a = MFMA(aq[s], bk, a); }
;         float v = 0.f;
; #pragma unroll
;         for (int i = 0; i < 16; ++i) v = fmaf(wv[i], fmaxf(a[i], 0.f), v);
;         u = (32 * kb + r32 <= tme) ? ordkey(v) : 0u;
;       }
;       sc[kb] = u;
.Lix_m48:
	v_cmp_le_i32_e32 vcc, 0x600, v16
	v_mfma_f32_32x32x16_bf16 v[18:33], v[46:49], v[64:67], 0
	v_mfma_f32_32x32x16_bf16 v[18:33], v[42:45], v[68:71], v[18:33]
	v_mfma_f32_32x32x16_bf16 v[18:33], v[38:41], v[72:75], v[18:33]
	v_mfma_f32_32x32x16_bf16 v[18:33], v[34:37], v[76:79], v[18:33]
	s_nop 11
	v_max_f32_e32 v18, 0, v18
	v_max_f32_e32 v19, 0, v19
	v_fma_f32 v18, v143, v18, 0
	v_fmac_f32_e32 v18, v142, v19
	v_max_f32_e32 v19, 0, v20
	v_fmac_f32_e32 v18, v141, v19
	v_max_f32_e32 v19, 0, v21
	v_fmac_f32_e32 v18, v140, v19
	v_max_f32_e32 v19, 0, v22
	v_fmac_f32_e32 v18, v139, v19
	v_max_f32_e32 v19, 0, v23
	v_fmac_f32_e32 v18, v138, v19
	v_max_f32_e32 v19, 0, v24
	v_fmac_f32_e32 v18, v137, v19
	v_max_f32_e32 v19, 0, v25
	v_fmac_f32_e32 v18, v136, v19
	v_max_f32_e32 v19, 0, v26
	v_fmac_f32_e32 v18, v135, v19
	v_max_f32_e32 v19, 0, v27
	v_fmac_f32_e32 v18, v134, v19
	v_max_f32_e32 v19, 0, v28
	v_fmac_f32_e32 v18, v133, v19
	v_max_f32_e32 v19, 0, v29
	v_fmac_f32_e32 v18, v132, v19
	v_max_f32_e32 v19, 0, v30
	v_fmac_f32_e32 v18, v131, v19
	v_max_f32_e32 v19, 0, v31
	v_fmac_f32_e32 v18, v130, v19
	v_max_f32_e32 v19, 0, v32
	v_fmac_f32_e32 v18, v129, v19
	v_max_f32_e32 v19, 0, v33
	v_fmac_f32_e32 v18, v128, v19
	v_ashrrev_i32_e32 v19, 31, v18
	v_bitop3_b32 v18, v19, v18, s8 bitop3:0x36
	v_cndmask_b32_e32 v197, 0, v18, vcc
	s_cmp_lt_u32 s0, 0x620
	s_cbranch_scc1 .Lix_z49
.Lix_b49:
	s_cmp_lt_u32 s0, 0x680
	s_cbranch_scc1 .Lix_w49
	s_add_u32 m0, s1, 0
	s_nop 0
	global_load_lds_dwordx4 v112, s[22:23]
	s_add_u32 s22, s22, 0x1e800
	s_addc_u32 s23, s23, 0
	s_add_u32 m0, s1, 0x400
	s_nop 0
	global_load_lds_dwordx4 v113, s[22:23]
	s_add_u32 s22, s22, 0x1e800
	s_addc_u32 s23, s23, 0
	s_add_u32 m0, s1, 0x800
	s_nop 0
	global_load_lds_dwordx4 v112, s[22:23]
	s_add_u32 s22, s22, 0x1e800
	s_addc_u32 s23, s23, 0
	s_add_u32 m0, s1, 0xc00
	s_nop 0
	global_load_lds_dwordx4 v113, s[22:23]
	s_add_u32 s22, s22, 0x1e800
	s_addc_u32 s23, s23, 0
	s_waitcnt vmcnt(8)
	s_branch .Lix_r49

; #define MFMA(a, b, c) __builtin_amdgcn_mfma_f32_32x32x16_bf16((a), (b), (c), 0, 0, 0)
; DI void indexer_phase(const u16* __restrict__ P, unsigned* __restrict__ mask) {
;     ...
;         const u16* kp = P + (brow + 32 * kb + r32) * 7808 + 3584 + 8 * hi;
; #pragma unroll
;         for (int s = 0; s < 4; ++s) { const bf16x8 bk = *(const bf16x8*)(kp + 16 * s); a = MFMA(aq[s], bk, a); }
.Lix_r49:
	s_cmp_lt_u32 s0, 0x640
	s_cbranch_scc1 .Lix_n49
	ds_read_b128 v[64:67], v114 offset:8192
	ds_read_b128 v[68:71], v115 offset:8192
	ds_read_b128 v[72:75], v116 offset:8192
	ds_read_b128 v[76:79], v117 offset:8192
	s_waitcnt lgkmcnt(4)
	s_branch .Lix_m49

; #define MFMA(a, b, c) __builtin_amdgcn_mfma_f32_32x32x16_bf16((a), (b), (c), 0, 0, 0)
; DI unsigned ordkey(float f) { const unsigned b = __float_as_uint(f); return b ^ ((unsigned)((int)b >> 31) | 0x80000000u); }
; DI void indexer_phase(const u16* __restrict__ P, unsigned* __restrict__ mask) {
;     ...
;     for (int kb = 0; kb < 64; ++kb) {
;       unsigned u = 0u;
;       if (kb <= kbmax) {
;         f32x16 a;
; #pragma unroll
;         for (int r = 0; r < 16; ++r) a[r] = 0.f;
;         const u16* kp = P + (brow + 32 * kb + r32) * 7808 + 3584 + 8 * hi;
; #pragma unroll
;         for (int s = 0; s < 4; ++s) { const bf16x8 bk = *(const bf16x8*)(kp + 16 * s); a = MFMA(aq[s], bk, a); }
;         float v = 0.f;
; #pragma unroll
;         for (int i = 0; i < 16; ++i) v = fmaf(wv[i], fmaxf(a[i], 0.f), v);
;         u = (32 * kb + r32 <= tme) ? ordkey(v) : 0u;
;       }
;       sc[kb] = u;
.Lix_m49:
	v_cmp_le_i32_e32 vcc, 0x620, v16
	v_mfma_f32_32x32x16_bf16 v[18:33], v[46:49], v[80:83], 0
	v_mfma_f32_32x32x16_bf16 v[18:33], v[42:45], v[84:87], v[18:33]
	v_mfma_f32_32x32x16_bf16 v[18:33], v[38:41], v[88:91], v[18:33]
	v_mfma_f32_32x32x16_bf16 v[18:33], v[34:37], v[92:95], v[18:33]
	s_nop 11
	v_max_f32_e32 v18, 0, v18
	v_max_f32_e32 v19, 0, v19
	v_fma_f32 v18, v143, v18, 0
	v_fmac_f32_e32 v18, v142, v19
	v_max_f32_e32 v19, 0, v20
	v_fmac_f32_e32 v18, v141, v19
	v_max_f32_e32 v19, 0, v21
	v_fmac_f32_e32 v18, v140, v19
	v_max_f32_e32 v19, 0, v22
	v_fmac_f32_e32 v18, v139, v19
	v_max_f32_e32 v19, 0, v23
	v_fmac_f32_e32 v18, v138, v19
	v_max_f32_e32 v19, 0, v24
	v_fmac_f32_e32 v18, v137, v19
	v_max_f32_e32 v19, 0, v25
	v_fmac_f32_e32 v18, v136, v19
	v_max_f32_e32 v19, 0, v26
	v_fmac_f32_e32 v18, v135, v19
	v_max_f32_e32 v19, 0, v27
	v_fmac_f32_e32 v18, v134, v19
	v_max_f32_e32 v19, 0, v28
	v_fmac_f32_e32 v18, v133, v19
	v_max_f32_e32 v19, 0, v29
	v_fmac_f32_e32 v18, v132, v19
	v_max_f32_e32 v19, 0, v30
	v_fmac_f32_e32 v18, v131, v19
	v_max_f32_e32 v19, 0, v31
	v_fmac_f32_e32 v18, v130, v19
	v_max_f32_e32 v19, 0, v32
	v_fmac_f32_e32 v18, v129, v19
	v_max_f32_e32 v19, 0, v33
	v_fmac_f32_e32 v18, v128, v19
	v_ashrrev_i32_e32 v19, 31, v18
	v_bitop3_b32 v18, v19, v18, s8 bitop3:0x36
	v_cndmask_b32_e32 v200, 0, v18, vcc
	s_cmp_lt_u32 s0, 0x640
	s_cbranch_scc1 .Lix_z50
.Lix_b50:
	s_cmp_lt_u32 s0, 0x6a0
	s_cbranch_scc1 .Lix_w50
	s_add_u32 m0, s1, 0x1000
	s_nop 0
	global_load_lds_dwordx4 v112, s[22:23]
	s_add_u32 s22, s22, 0x1e800
	s_addc_u32 s23, s23, 0
	s_add_u32 m0, s1, 0x1400
	s_nop 0
	global_load_lds_dwordx4 v113, s[22:23]
	s_add_u32 s22, s22, 0x1e800
	s_addc_u32 s23, s23, 0
	s_add_u32 m0, s1, 0x1800
	s_nop 0
	global_load_lds_dwordx4 v112, s[22:23]
	s_add_u32 s22, s22, 0x1e800
	s_addc_u32 s23, s23, 0
	s_add_u32 m0, s1, 0x1c00
	s_nop 0
	global_load_lds_dwordx4 v113, s[22:23]
	s_add_u32 s22, s22, 0x1e800
	s_addc_u32 s23, s23, 0
	s_waitcnt vmcnt(8)
	s_branch .Lix_r50

; #define MFMA(a, b, c) __builtin_amdgcn_mfma_f32_32x32x16_bf16((a), (b), (c), 0, 0, 0)
; DI void indexer_phase(const u16* __restrict__ P, unsigned* __restrict__ mask) {
;     ...
;         const u16* kp = P + (brow + 32 * kb + r32) * 7808 + 3584 + 8 * hi;
; #pragma unroll
;         for (int s = 0; s < 4; ++s) { const bf16x8 bk = *(const bf16x8*)(kp + 16 * s); a = MFMA(aq[s], bk, a); }
.Lix_r50:
	s_cmp_lt_u32 s0, 0x660
	s_cbranch_scc1 .Lix_n50
	ds_read_b128 v[80:83], v114 offset:12288
	ds_read_b128 v[84:87], v115 offset:12288
	ds_read_b128 v[88:91], v116 offset:12288
	ds_read_b128 v[92:95], v117 offset:12288
	s_waitcnt lgkmcnt(4)
	s_branch .Lix_m50

; #define MFMA(a, b, c) __builtin_amdgcn_mfma_f32_32x32x16_bf16((a), (b), (c), 0, 0, 0)
; DI unsigned ordkey(float f) { const unsigned b = __float_as_uint(f); return b ^ ((unsigned)((int)b >> 31) | 0x80000000u); }
; DI void indexer_phase(const u16* __restrict__ P, unsigned* __restrict__ mask) {
;     ...
;     for (int kb = 0; kb < 64; ++kb) {
;       unsigned u = 0u;
;       if (kb <= kbmax) {
;         f32x16 a;
; #pragma unroll
;         for (int r = 0; r < 16; ++r) a[r] = 0.f;
;         const u16* kp = P + (brow + 32 * kb + r32) * 7808 + 3584 + 8 * hi;
; #pragma unroll
;         for (int s = 0; s < 4; ++s) { const bf16x8 bk = *(const bf16x8*)(kp + 16 * s); a = MFMA(aq[s], bk, a); }
;         float v = 0.f;
; #pragma unroll
;         for (int i = 0; i < 16; ++i) v = fmaf(wv[i], fmaxf(a[i], 0.f), v);
;         u = (32 * kb + r32 <= tme) ? ordkey(v) : 0u;
;       }
;       sc[kb] = u;
.Lix_m50:
	v_cmp_le_i32_e32 vcc, 0x640, v16
	v_mfma_f32_32x32x16_bf16 v[18:33], v[46:49], v[64:67], 0
	v_mfma_f32_32x32x16_bf16 v[18:33], v[42:45], v[68:71], v[18:33]
	v_mfma_f32_32x32x16_bf16 v[18:33], v[38:41], v[72:75], v[18:33]
	v_mfma_f32_32x32x16_bf16 v[18:33], v[34:37], v[76:79], v[18:33]
	s_nop 11
	v_max_f32_e32 v18, 0, v18
	v_max_f32_e32 v19, 0, v19
	v_fma_f32 v18, v143, v18, 0
	v_fmac_f32_e32 v18, v142, v19
	v_max_f32_e32 v19, 0, v20
	v_fmac_f32_e32 v18, v141, v19
	v_max_f32_e32 v19, 0, v21
	v_fmac_f32_e32 v18, v140, v19
	v_max_f32_e32 v19, 0, v22
	v_fmac_f32_e32 v18, v139, v19
	v_max_f32_e32 v19, 0, v23
	v_fmac_f32_e32 v18, v138, v19
	v_max_f32_e32 v19, 0, v24
	v_fmac_f32_e32 v18, v137, v19
	v_max_f32_e32 v19, 0, v25
	v_fmac_f32_e32 v18, v136, v19
	v_max_f32_e32 v19, 0, v26
	v_fmac_f32_e32 v18, v135, v19
	v_max_f32_e32 v19, 0, v27
	v_fmac_f32_e32 v18, v134, v19
	v_max_f32_e32 v19, 0, v28
	v_fmac_f32_e32 v18, v133, v19
	v_max_f32_e32 v19, 0, v29
	v_fmac_f32_e32 v18, v132, v19
	v_max_f32_e32 v19, 0, v30
	v_fmac_f32_e32 v18, v131, v19
	v_max_f32_e32 v19, 0, v31
	v_fmac_f32_e32 v18, v130, v19
	v_max_f32_e32 v19, 0, v32
	v_fmac_f32_e32 v18, v129, v19
	v_max_f32_e32 v19, 0, v33
	v_fmac_f32_e32 v18, v128, v19
	v_ashrrev_i32_e32 v19, 31, v18
	v_bitop3_b32 v18, v19, v18, s8 bitop3:0x36
	v_cndmask_b32_e32 v199, 0, v18, vcc
	s_cmp_lt_u32 s0, 0x660
	s_cbranch_scc1 .Lix_z51
.Lix_b51:
	s_cmp_lt_u32 s0, 0x6c0
	s_cbranch_scc1 .Lix_w51
	s_add_u32 m0, s1, 0x2000
	s_nop 0
	global_load_lds_dwordx4 v112, s[22:23]
	s_add_u32 s22, s22, 0x1e800
	s_addc_u32 s23, s23, 0
	s_add_u32 m0, s1, 0x2400
	s_nop 0
	global_load_lds_dwordx4 v113, s[22:23]
	s_add_u32 s22, s22, 0x1e800
	s_addc_u32 s23, s23, 0
	s_add_u32 m0, s1, 0x2800
	s_nop 0
	global_load_lds_dwordx4 v112, s[22:23]
	s_add_u32 s22, s22, 0x1e800
	s_addc_u32 s23, s23, 0
	s_add_u32 m0, s1, 0x2c00
	s_nop 0
	global_load_lds_dwordx4 v113, s[22:23]
	s_add_u32 s22, s22, 0x1e800
	s_addc_u32 s23, s23, 0
	s_waitcnt vmcnt(8)
	s_branch .Lix_r51

; #define MFMA(a, b, c) __builtin_amdgcn_mfma_f32_32x32x16_bf16((a), (b), (c), 0, 0, 0)
; DI void indexer_phase(const u16* __restrict__ P, unsigned* __restrict__ mask) {
;     ...
;         const u16* kp = P + (brow + 32 * kb + r32) * 7808 + 3584 + 8 * hi;
; #pragma unroll
;         for (int s = 0; s < 4; ++s) { const bf16x8 bk = *(const bf16x8*)(kp + 16 * s); a = MFMA(aq[s], bk, a); }
.Lix_r51:
	s_cmp_lt_u32 s0, 0x680
	s_cbranch_scc1 .Lix_n51
	ds_read_b128 v[64:67], v114
	ds_read_b128 v[68:71], v115
	ds_read_b128 v[72:75], v116
	ds_read_b128 v[76:79], v117
	s_waitcnt lgkmcnt(4)
	s_branch .Lix_m51

; #define MFMA(a, b, c) __builtin_amdgcn_mfma_f32_32x32x16_bf16((a), (b), (c), 0, 0, 0)
; DI unsigned ordkey(float f) { const unsigned b = __float_as_uint(f); return b ^ ((unsigned)((int)b >> 31) | 0x80000000u); }
; DI void indexer_phase(const u16* __restrict__ P, unsigned* __restrict__ mask) {
;     ...
;     for (int kb = 0; kb < 64; ++kb) {
;       unsigned u = 0u;
;       if (kb <= kbmax) {
;         f32x16 a;
; #pragma unroll
;         for (int r = 0; r < 16; ++r) a[r] = 0.f;
;         const u16* kp = P + (brow + 32 * kb + r32) * 7808 + 3584 + 8 * hi;
; #pragma unroll
;         for (int s = 0; s < 4; ++s) { const bf16x8 bk = *(const bf16x8*)(kp + 16 * s); a = MFMA(aq[s], bk, a); }
;         float v = 0.f;
; #pragma unroll
;         for (int i = 0; i < 16; ++i) v = fmaf(wv[i], fmaxf(a[i], 0.f), v);
;         u = (32 * kb + r32 <= tme) ? ordkey(v) : 0u;
;       }
;       sc[kb] = u;
.Lix_m51:
	v_cmp_le_i32_e32 vcc, 0x660, v16
	v_mfma_f32_32x32x16_bf16 v[18:33], v[46:49], v[80:83], 0
	v_mfma_f32_32x32x16_bf16 v[18:33], v[42:45], v[84:87], v[18:33]
	v_mfma_f32_32x32x16_bf16 v[18:33], v[38:41], v[88:91], v[18:33]
	v_mfma_f32_32x32x16_bf16 v[18:33], v[34:37], v[92:95], v[18:33]
	s_nop 11
	v_max_f32_e32 v18, 0, v18
	v_max_f32_e32 v19, 0, v19
	v_fma_f32 v18, v143, v18, 0
	v_fmac_f32_e32 v18, v142, v19
	v_max_f32_e32 v19, 0, v20
	v_fmac_f32_e32 v18, v141, v19
	v_max_f32_e32 v19, 0, v21
	v_fmac_f32_e32 v18, v140, v19
	v_max_f32_e32 v19, 0, v22
	v_fmac_f32_e32 v18, v139, v19
	v_max_f32_e32 v19, 0, v23
	v_fmac_f32_e32 v18, v138, v19
	v_max_f32_e32 v19, 0, v24
	v_fmac_f32_e32 v18, v137, v19
	v_max_f32_e32 v19, 0, v25
	v_fmac_f32_e32 v18, v136, v19
	v_max_f32_e32 v19, 0, v26
	v_fmac_f32_e32 v18, v135, v19
	v_max_f32_e32 v19, 0, v27
	v_fmac_f32_e32 v18, v134, v19
	v_max_f32_e32 v19, 0, v28
	v_fmac_f32_e32 v18, v133, v19
	v_max_f32_e32 v19, 0, v29
	v_fmac_f32_e32 v18, v132, v19
	v_max_f32_e32 v19, 0, v30
	v_fmac_f32_e32 v18, v131, v19
	v_max_f32_e32 v19, 0, v31
	v_fmac_f32_e32 v18, v130, v19
	v_max_f32_e32 v19, 0, v32
	v_fmac_f32_e32 v18, v129, v19
	v_max_f32_e32 v19, 0, v33
	v_fmac_f32_e32 v18, v128, v19
	v_ashrrev_i32_e32 v19, 31, v18
	v_bitop3_b32 v18, v19, v18, s8 bitop3:0x36
	v_cndmask_b32_e32 v202, 0, v18, vcc
	s_cmp_lt_u32 s0, 0x680
	s_cbranch_scc1 .Lix_z52
.Lix_b52:
	s_cmp_lt_u32 s0, 0x6e0
	s_cbranch_scc1 .Lix_w52
	s_add_u32 m0, s1, 0x3000
	s_nop 0
	global_load_lds_dwordx4 v112, s[22:23]
	s_add_u32 s22, s22, 0x1e800
	s_addc_u32 s23, s23, 0
	s_add_u32 m0, s1, 0x3400
	s_nop 0
	global_load_lds_dwordx4 v113, s[22:23]
	s_add_u32 s22, s22, 0x1e800
	s_addc_u32 s23, s23, 0
	s_add_u32 m0, s1, 0x3800
	s_nop 0
	global_load_lds_dwordx4 v112, s[22:23]
	s_add_u32 s22, s22, 0x1e800
	s_addc_u32 s23, s23, 0
	s_add_u32 m0, s1, 0x3c00
	s_nop 0
	global_load_lds_dwordx4 v113, s[22:23]
	s_add_u32 s22, s22, 0x1e800
	s_addc_u32 s23, s23, 0
	s_waitcnt vmcnt(8)
	s_branch .Lix_r52

; #define MFMA(a, b, c) __builtin_amdgcn_mfma_f32_32x32x16_bf16((a), (b), (c), 0, 0, 0)
; DI void indexer_phase(const u16* __restrict__ P, unsigned* __restrict__ mask) {
;     ...
;         const u16* kp = P + (brow + 32 * kb + r32) * 7808 + 3584 + 8 * hi;
; #pragma unroll
;         for (int s = 0; s < 4; ++s) { const bf16x8 bk = *(const bf16x8*)(kp + 16 * s); a = MFMA(aq[s], bk, a); }
.Lix_r52:
	s_cmp_lt_u32 s0, 0x6a0
	s_cbranch_scc1 .Lix_n52
	ds_read_b128 v[80:83], v114 offset:4096
	ds_read_b128 v[84:87], v115 offset:4096
	ds_read_b128 v[88:91], v116 offset:4096
	ds_read_b128 v[92:95], v117 offset:4096
	s_waitcnt lgkmcnt(4)
	s_branch .Lix_m52

; #define MFMA(a, b, c) __builtin_amdgcn_mfma_f32_32x32x16_bf16((a), (b), (c), 0, 0, 0)
; DI unsigned ordkey(float f) { const unsigned b = __float_as_uint(f); return b ^ ((unsigned)((int)b >> 31) | 0x80000000u); }
; DI void indexer_phase(const u16* __restrict__ P, unsigned* __restrict__ mask) {
;     ...
;     for (int kb = 0; kb < 64; ++kb) {
;       unsigned u = 0u;
;       if (kb <= kbmax) {
;         f32x16 a;
; #pragma unroll
;         for (int r = 0; r < 16; ++r) a[r] = 0.f;
;         const u16* kp = P + (brow + 32 * kb + r32) * 7808 + 3584 + 8 * hi;
; #pragma unroll
;         for (int s = 0; s < 4; ++s) { const bf16x8 bk = *(const bf16x8*)(kp + 16 * s); a = MFMA(aq[s], bk, a); }
;         float v = 0.f;
; #pragma unroll
;         for (int i = 0; i < 16; ++i) v = fmaf(wv[i], fmaxf(a[i], 0.f), v);
;         u = (32 * kb + r32 <= tme) ? ordkey(v) : 0u;
;       }
;       sc[kb] = u;
.Lix_m52:
	v_cmp_le_i32_e32 vcc, 0x680, v16
	v_mfma_f32_32x32x16_bf16 v[18:33], v[46:49], v[64:67], 0
	v_mfma_f32_32x32x16_bf16 v[18:33], v[42:45], v[68:71], v[18:33]
	v_mfma_f32_32x32x16_bf16 v[18:33], v[38:41], v[72:75], v[18:33]
	v_mfma_f32_32x32x16_bf16 v[18:33], v[34:37], v[76:79], v[18:33]
	s_nop 11
	v_max_f32_e32 v18, 0, v18
	v_max_f32_e32 v19, 0, v19
	v_fma_f32 v18, v143, v18, 0
	v_fmac_f32_e32 v18, v142, v19
	v_max_f32_e32 v19, 0, v20
	v_fmac_f32_e32 v18, v141, v19
	v_max_f32_e32 v19, 0, v21
	v_fmac_f32_e32 v18, v140, v19
	v_max_f32_e32 v19, 0, v22
	v_fmac_f32_e32 v18, v139, v19
	v_max_f32_e32 v19, 0, v23
	v_fmac_f32_e32 v18, v138, v19
	v_max_f32_e32 v19, 0, v24
	v_fmac_f32_e32 v18, v137, v19
	v_max_f32_e32 v19, 0, v25
	v_fmac_f32_e32 v18, v136, v19
	v_max_f32_e32 v19, 0, v26
	v_fmac_f32_e32 v18, v135, v19
	v_max_f32_e32 v19, 0, v27
	v_fmac_f32_e32 v18, v134, v19
	v_max_f32_e32 v19, 0, v28
	v_fmac_f32_e32 v18, v133, v19
	v_max_f32_e32 v19, 0, v29
	v_fmac_f32_e32 v18, v132, v19
	v_max_f32_e32 v19, 0, v30
	v_fmac_f32_e32 v18, v131, v19
	v_max_f32_e32 v19, 0, v31
	v_fmac_f32_e32 v18, v130, v19
	v_max_f32_e32 v19, 0, v32
	v_fmac_f32_e32 v18, v129, v19
	v_max_f32_e32 v19, 0, v33
	v_fmac_f32_e32 v18, v128, v19
	v_ashrrev_i32_e32 v19, 31, v18
	v_bitop3_b32 v18, v19, v18, s8 bitop3:0x36
	v_cndmask_b32_e32 v201, 0, v18, vcc
	s_cmp_lt_u32 s0, 0x6a0
	s_cbranch_scc1 .Lix_z53
.Lix_b53:
	s_cmp_lt_u32 s0, 0x700
	s_cbranch_scc1 .Lix_w53
	s_add_u32 m0, s1, 0
	s_nop 0
	global_load_lds_dwordx4 v112, s[22:23]
	s_add_u32 s22, s22, 0x1e800
	s_addc_u32 s23, s23, 0
	s_add_u32 m0, s1, 0x400
	s_nop 0
	global_load_lds_dwordx4 v113, s[22:23]
	s_add_u32 s22, s22, 0x1e800
	s_addc_u32 s23, s23, 0
	s_add_u32 m0, s1, 0x800
	s_nop 0
	global_load_lds_dwordx4 v112, s[22:23]
	s_add_u32 s22, s22, 0x1e800
	s_addc_u32 s23, s23, 0
	s_add_u32 m0, s1, 0xc00
	s_nop 0
	global_load_lds_dwordx4 v113, s[22:23]
	s_add_u32 s22, s22, 0x1e800
	s_addc_u32 s23, s23, 0
	s_waitcnt vmcnt(8)
	s_branch .Lix_r53

; #define MFMA(a, b, c) __builtin_amdgcn_mfma_f32_32x32x16_bf16((a), (b), (c), 0, 0, 0)
; DI void indexer_phase(const u16* __restrict__ P, unsigned* __restrict__ mask) {
;     ...
;         const u16* kp = P + (brow + 32 * kb + r32) * 7808 + 3584 + 8 * hi;
; #pragma unroll
;         for (int s = 0; s < 4; ++s) { const bf16x8 bk = *(const bf16x8*)(kp + 16 * s); a = MFMA(aq[s], bk, a); }
.Lix_r53:
	s_cmp_lt_u32 s0, 0x6c0
	s_cbranch_scc1 .Lix_n53
	ds_read_b128 v[64:67], v114 offset:8192
	ds_read_b128 v[68:71], v115 offset:8192
	ds_read_b128 v[72:75], v116 offset:8192
	ds_read_b128 v[76:79], v117 offset:8192
	s_waitcnt lgkmcnt(4)
	s_branch .Lix_m53

; #define MFMA(a, b, c) __builtin_amdgcn_mfma_f32_32x32x16_bf16((a), (b), (c), 0, 0, 0)
; DI unsigned ordkey(float f) { const unsigned b = __float_as_uint(f); return b ^ ((unsigned)((int)b >> 31) | 0x80000000u); }
; DI void indexer_phase(const u16* __restrict__ P, unsigned* __restrict__ mask) {
;     ...
;     for (int kb = 0; kb < 64; ++kb) {
;       unsigned u = 0u;
;       if (kb <= kbmax) {
;         f32x16 a;
; #pragma unroll
;         for (int r = 0; r < 16; ++r) a[r] = 0.f;
;         const u16* kp = P + (brow + 32 * kb + r32) * 7808 + 3584 + 8 * hi;
; #pragma unroll
;         for (int s = 0; s < 4; ++s) { const bf16x8 bk = *(const bf16x8*)(kp + 16 * s); a = MFMA(aq[s], bk, a); }
;         float v = 0.f;
; #pragma unroll
;         for (int i = 0; i < 16; ++i) v = fmaf(wv[i], fmaxf(a[i], 0.f), v);
;         u = (32 * kb + r32 <= tme) ? ordkey(v) : 0u;
;       }
;       sc[kb] = u;
.Lix_m53:
	v_cmp_le_i32_e32 vcc, 0x6a0, v16
	v_mfma_f32_32x32x16_bf16 v[18:33], v[46:49], v[80:83], 0
	v_mfma_f32_32x32x16_bf16 v[18:33], v[42:45], v[84:87], v[18:33]
	v_mfma_f32_32x32x16_bf16 v[18:33], v[38:41], v[88:91], v[18:33]
	v_mfma_f32_32x32x16_bf16 v[18:33], v[34:37], v[92:95], v[18:33]
	s_nop 11
	v_max_f32_e32 v18, 0, v18
	v_max_f32_e32 v19, 0, v19
	v_fma_f32 v18, v143, v18, 0
	v_fmac_f32_e32 v18, v142, v19
	v_max_f32_e32 v19, 0, v20
	v_fmac_f32_e32 v18, v141, v19
	v_max_f32_e32 v19, 0, v21
	v_fmac_f32_e32 v18, v140, v19
	v_max_f32_e32 v19, 0, v22
	v_fmac_f32_e32 v18, v139, v19
	v_max_f32_e32 v19, 0, v23
	v_fmac_f32_e32 v18, v138, v19
	v_max_f32_e32 v19, 0, v24
	v_fmac_f32_e32 v18, v137, v19
	v_max_f32_e32 v19, 0, v25
	v_fmac_f32_e32 v18, v136, v19
	v_max_f32_e32 v19, 0, v26
	v_fmac_f32_e32 v18, v135, v19
	v_max_f32_e32 v19, 0, v27
	v_fmac_f32_e32 v18, v134, v19
	v_max_f32_e32 v19, 0, v28
	v_fmac_f32_e32 v18, v133, v19
	v_max_f32_e32 v19, 0, v29
	v_fmac_f32_e32 v18, v132, v19
	v_max_f32_e32 v19, 0, v30
	v_fmac_f32_e32 v18, v131, v19
	v_max_f32_e32 v19, 0, v31
	v_fmac_f32_e32 v18, v130, v19
	v_max_f32_e32 v19, 0, v32
	v_fmac_f32_e32 v18, v129, v19
	v_max_f32_e32 v19, 0, v33
	v_fmac_f32_e32 v18, v128, v19
	v_ashrrev_i32_e32 v19, 31, v18
	v_bitop3_b32 v18, v19, v18, s8 bitop3:0x36
	v_cndmask_b32_e32 v204, 0, v18, vcc
	s_cmp_lt_u32 s0, 0x6c0
	s_cbranch_scc1 .Lix_z54
.Lix_b54:
	s_cmp_lt_u32 s0, 0x720
	s_cbranch_scc1 .Lix_w54
	s_add_u32 m0, s1, 0x1000
	s_nop 0
	global_load_lds_dwordx4 v112, s[22:23]
	s_add_u32 s22, s22, 0x1e800
	s_addc_u32 s23, s23, 0
	s_add_u32 m0, s1, 0x1400
	s_nop 0
	global_load_lds_dwordx4 v113, s[22:23]
	s_add_u32 s22, s22, 0x1e800
	s_addc_u32 s23, s23, 0
	s_add_u32 m0, s1, 0x1800
	s_nop 0
	global_load_lds_dwordx4 v112, s[22:23]
	s_add_u32 s22, s22, 0x1e800
	s_addc_u32 s23, s23, 0
	s_add_u32 m0, s1, 0x1c00
	s_nop 0
	global_load_lds_dwordx4 v113, s[22:23]
	s_add_u32 s22, s22, 0x1e800
	s_addc_u32 s23, s23, 0
	s_waitcnt vmcnt(8)
	s_branch .Lix_r54

; #define MFMA(a, b, c) __builtin_amdgcn_mfma_f32_32x32x16_bf16((a), (b), (c), 0, 0, 0)
; DI void indexer_phase(const u16* __restrict__ P, unsigned* __restrict__ mask) {
;     ...
;         const u16* kp = P + (brow + 32 * kb + r32) * 7808 + 3584 + 8 * hi;
; #pragma unroll
;         for (int s = 0; s < 4; ++s) { const bf16x8 bk = *(const bf16x8*)(kp + 16 * s); a = MFMA(aq[s], bk, a); }
.Lix_r54:
	s_cmp_lt_u32 s0, 0x6e0
	s_cbranch_scc1 .Lix_n54
	ds_read_b128 v[80:83], v114 offset:12288
	ds_read_b128 v[84:87], v115 offset:12288
	ds_read_b128 v[88:91], v116 offset:12288
	ds_read_b128 v[92:95], v117 offset:12288
	s_waitcnt lgkmcnt(4)
	s_branch .Lix_m54

; #define MFMA(a, b, c) __builtin_amdgcn_mfma_f32_32x32x16_bf16((a), (b), (c), 0, 0, 0)
; DI unsigned ordkey(float f) { const unsigned b = __float_as_uint(f); return b ^ ((unsigned)((int)b >> 31) | 0x80000000u); }
; DI void indexer_phase(const u16* __restrict__ P, unsigned* __restrict__ mask) {
;     ...
;     for (int kb = 0; kb < 64; ++kb) {
;       unsigned u = 0u;
;       if (kb <= kbmax) {
;         f32x16 a;
; #pragma unroll
;         for (int r = 0; r < 16; ++r) a[r] = 0.f;
;         const u16* kp = P + (brow + 32 * kb + r32) * 7808 + 3584 + 8 * hi;
; #pragma unroll
;         for (int s = 0; s < 4; ++s) { const bf16x8 bk = *(const bf16x8*)(kp + 16 * s); a = MFMA(aq[s], bk, a); }
;         float v = 0.f;
; #pragma unroll
;         for (int i = 0; i < 16; ++i) v = fmaf(wv[i], fmaxf(a[i], 0.f), v);
;         u = (32 * kb + r32 <= tme) ? ordkey(v) : 0u;
;       }
;       sc[kb] = u;
.Lix_m54:
	v_cmp_le_i32_e32 vcc, 0x6c0, v16
	v_mfma_f32_32x32x16_bf16 v[18:33], v[46:49], v[64:67], 0
	v_mfma_f32_32x32x16_bf16 v[18:33], v[42:45], v[68:71], v[18:33]
	v_mfma_f32_32x32x16_bf16 v[18:33], v[38:41], v[72:75], v[18:33]
	v_mfma_f32_32x32x16_bf16 v[18:33], v[34:37], v[76:79], v[18:33]
	s_nop 11
	v_max_f32_e32 v18, 0, v18
	v_max_f32_e32 v19, 0, v19
	v_fma_f32 v18, v143, v18, 0
	v_fmac_f32_e32 v18, v142, v19
	v_max_f32_e32 v19, 0, v20
	v_fmac_f32_e32 v18, v141, v19
	v_max_f32_e32 v19, 0, v21
	v_fmac_f32_e32 v18, v140, v19
	v_max_f32_e32 v19, 0, v22
	v_fmac_f32_e32 v18, v139, v19
	v_max_f32_e32 v19, 0, v23
	v_fmac_f32_e32 v18, v138, v19
	v_max_f32_e32 v19, 0, v24
	v_fmac_f32_e32 v18, v137, v19
	v_max_f32_e32 v19, 0, v25
	v_fmac_f32_e32 v18, v136, v19
	v_max_f32_e32 v19, 0, v26
	v_fmac_f32_e32 v18, v135, v19
	v_max_f32_e32 v19, 0, v27
	v_fmac_f32_e32 v18, v134, v19
	v_max_f32_e32 v19, 0, v28
	v_fmac_f32_e32 v18, v133, v19
	v_max_f32_e32 v19, 0, v29
	v_fmac_f32_e32 v18, v132, v19
	v_max_f32_e32 v19, 0, v30
	v_fmac_f32_e32 v18, v131, v19
	v_max_f32_e32 v19, 0, v31
	v_fmac_f32_e32 v18, v130, v19
	v_max_f32_e32 v19, 0, v32
	v_fmac_f32_e32 v18, v129, v19
	v_max_f32_e32 v19, 0, v33
	v_fmac_f32_e32 v18, v128, v19
	v_ashrrev_i32_e32 v19, 31, v18
	v_bitop3_b32 v18, v19, v18, s8 bitop3:0x36
	v_cndmask_b32_e32 v203, 0, v18, vcc
	s_cmp_lt_u32 s0, 0x6e0
	s_cbranch_scc1 .Lix_z55
.Lix_b55:
	s_cmp_lt_u32 s0, 0x740
	s_cbranch_scc1 .Lix_w55
	s_add_u32 m0, s1, 0x2000
	s_nop 0
	global_load_lds_dwordx4 v112, s[22:23]
	s_add_u32 s22, s22, 0x1e800
	s_addc_u32 s23, s23, 0
	s_add_u32 m0, s1, 0x2400
	s_nop 0
	global_load_lds_dwordx4 v113, s[22:23]
	s_add_u32 s22, s22, 0x1e800
	s_addc_u32 s23, s23, 0
	s_add_u32 m0, s1, 0x2800
	s_nop 0
	global_load_lds_dwordx4 v112, s[22:23]
	s_add_u32 s22, s22, 0x1e800
	s_addc_u32 s23, s23, 0
	s_add_u32 m0, s1, 0x2c00
	s_nop 0
	global_load_lds_dwordx4 v113, s[22:23]
	s_add_u32 s22, s22, 0x1e800
	s_addc_u32 s23, s23, 0
	s_waitcnt vmcnt(8)
	s_branch .Lix_r55

; #define MFMA(a, b, c) __builtin_amdgcn_mfma_f32_32x32x16_bf16((a), (b), (c), 0, 0, 0)
; DI void indexer_phase(const u16* __restrict__ P, unsigned* __restrict__ mask) {
;     ...
;         const u16* kp = P + (brow + 32 * kb + r32) * 7808 + 3584 + 8 * hi;
; #pragma unroll
;         for (int s = 0; s < 4; ++s) { const bf16x8 bk = *(const bf16x8*)(kp + 16 * s); a = MFMA(aq[s], bk, a); }
.Lix_r55:
	s_cmp_lt_u32 s0, 0x700
	s_cbranch_scc1 .Lix_n55
	ds_read_b128 v[64:67], v114
	ds_read_b128 v[68:71], v115
	ds_read_b128 v[72:75], v116
	ds_read_b128 v[76:79], v117
	s_waitcnt lgkmcnt(4)
	s_branch .Lix_m55

; #define MFMA(a, b, c) __builtin_amdgcn_mfma_f32_32x32x16_bf16((a), (b), (c), 0, 0, 0)
; DI unsigned ordkey(float f) { const unsigned b = __float_as_uint(f); return b ^ ((unsigned)((int)b >> 31) | 0x80000000u); }
; DI void indexer_phase(const u16* __restrict__ P, unsigned* __restrict__ mask) {
;     ...
;     for (int kb = 0; kb < 64; ++kb) {
;       unsigned u = 0u;
;       if (kb <= kbmax) {
;         f32x16 a;
; #pragma unroll
;         for (int r = 0; r < 16; ++r) a[r] = 0.f;
;         const u16* kp = P + (brow + 32 * kb + r32) * 7808 + 3584 + 8 * hi;
; #pragma unroll
;         for (int s = 0; s < 4; ++s) { const bf16x8 bk = *(const bf16x8*)(kp + 16 * s); a = MFMA(aq[s], bk, a); }
;         float v = 0.f;
; #pragma unroll
;         for (int i = 0; i < 16; ++i) v = fmaf(wv[i], fmaxf(a[i], 0.f), v);
;         u = (32 * kb + r32 <= tme) ? ordkey(v) : 0u;
;       }
;       sc[kb] = u;
.Lix_m55:
	v_cmp_le_i32_e32 vcc, 0x6e0, v16
	v_mfma_f32_32x32x16_bf16 v[18:33], v[46:49], v[80:83], 0
	v_mfma_f32_32x32x16_bf16 v[18:33], v[42:45], v[84:87], v[18:33]
	v_mfma_f32_32x32x16_bf16 v[18:33], v[38:41], v[88:91], v[18:33]
	v_mfma_f32_32x32x16_bf16 v[18:33], v[34:37], v[92:95], v[18:33]
	s_nop 11
	v_max_f32_e32 v18, 0, v18
	v_max_f32_e32 v19, 0, v19
	v_fma_f32 v18, v143, v18, 0
	v_fmac_f32_e32 v18, v142, v19
	v_max_f32_e32 v19, 0, v20
	v_fmac_f32_e32 v18, v141, v19
	v_max_f32_e32 v19, 0, v21
	v_fmac_f32_e32 v18, v140, v19
	v_max_f32_e32 v19, 0, v22
	v_fmac_f32_e32 v18, v139, v19
	v_max_f32_e32 v19, 0, v23
	v_fmac_f32_e32 v18, v138, v19
	v_max_f32_e32 v19, 0, v24
	v_fmac_f32_e32 v18, v137, v19
	v_max_f32_e32 v19, 0, v25
	v_fmac_f32_e32 v18, v136, v19
	v_max_f32_e32 v19, 0, v26
	v_fmac_f32_e32 v18, v135, v19
	v_max_f32_e32 v19, 0, v27
	v_fmac_f32_e32 v18, v134, v19
	v_max_f32_e32 v19, 0, v28
	v_fmac_f32_e32 v18, v133, v19
	v_max_f32_e32 v19, 0, v29
	v_fmac_f32_e32 v18, v132, v19
	v_max_f32_e32 v19, 0, v30
	v_fmac_f32_e32 v18, v131, v19
	v_max_f32_e32 v19, 0, v31
	v_fmac_f32_e32 v18, v130, v19
	v_max_f32_e32 v19, 0, v32
	v_fmac_f32_e32 v18, v129, v19
	v_max_f32_e32 v19, 0, v33
	v_fmac_f32_e32 v18, v128, v19
	v_ashrrev_i32_e32 v19, 31, v18
	v_bitop3_b32 v18, v19, v18, s8 bitop3:0x36
	v_cndmask_b32_e32 v206, 0, v18, vcc
	s_cmp_lt_u32 s0, 0x700
	s_cbranch_scc1 .Lix_z56
.Lix_b56:
	s_cmp_lt_u32 s0, 0x760
	s_cbranch_scc1 .Lix_w56
	s_add_u32 m0, s1, 0x3000
	s_nop 0
	global_load_lds_dwordx4 v112, s[22:23]
	s_add_u32 s22, s22, 0x1e800
	s_addc_u32 s23, s23, 0
	s_add_u32 m0, s1, 0x3400
	s_nop 0
	global_load_lds_dwordx4 v113, s[22:23]
	s_add_u32 s22, s22, 0x1e800
	s_addc_u32 s23, s23, 0
	s_add_u32 m0, s1, 0x3800
	s_nop 0
	global_load_lds_dwordx4 v112, s[22:23]
	s_add_u32 s22, s22, 0x1e800
	s_addc_u32 s23, s23, 0
	s_add_u32 m0, s1, 0x3c00
	s_nop 0
	global_load_lds_dwordx4 v113, s[22:23]
	s_add_u32 s22, s22, 0x1e800
	s_addc_u32 s23, s23, 0
	s_waitcnt vmcnt(8)
	s_branch .Lix_r56

; #define MFMA(a, b, c) __builtin_amdgcn_mfma_f32_32x32x16_bf16((a), (b), (c), 0, 0, 0)
; DI void indexer_phase(const u16* __restrict__ P, unsigned* __restrict__ mask) {
;     ...
;         const u16* kp = P + (brow + 32 * kb + r32) * 7808 + 3584 + 8 * hi;
; #pragma unroll
;         for (int s = 0; s < 4; ++s) { const bf16x8 bk = *(const bf16x8*)(kp + 16 * s); a = MFMA(aq[s], bk, a); }
.Lix_r56:
	s_cmp_lt_u32 s0, 0x720
	s_cbranch_scc1 .Lix_n56
	ds_read_b128 v[80:83], v114 offset:4096
	ds_read_b128 v[84:87], v115 offset:4096
	ds_read_b128 v[88:91], v116 offset:4096
	ds_read_b128 v[92:95], v117 offset:4096
	s_waitcnt lgkmcnt(4)
	s_branch .Lix_m56

; #define MFMA(a, b, c) __builtin_amdgcn_mfma_f32_32x32x16_bf16((a), (b), (c), 0, 0, 0)
; DI unsigned ordkey(float f) { const unsigned b = __float_as_uint(f); return b ^ ((unsigned)((int)b >> 31) | 0x80000000u); }
; DI void indexer_phase(const u16* __restrict__ P, unsigned* __restrict__ mask) {
;     ...
;     for (int kb = 0; kb < 64; ++kb) {
;       unsigned u = 0u;
;       if (kb <= kbmax) {
;         f32x16 a;
; #pragma unroll
;         for (int r = 0; r < 16; ++r) a[r] = 0.f;
;         const u16* kp = P + (brow + 32 * kb + r32) * 7808 + 3584 + 8 * hi;
; #pragma unroll
;         for (int s = 0; s < 4; ++s) { const bf16x8 bk = *(const bf16x8*)(kp + 16 * s); a = MFMA(aq[s], bk, a); }
;         float v = 0.f;
; #pragma unroll
;         for (int i = 0; i < 16; ++i) v = fmaf(wv[i], fmaxf(a[i], 0.f), v);
;         u = (32 * kb + r32 <= tme) ? ordkey(v) : 0u;
;       }
;       sc[kb] = u;
.Lix_m56:
	v_cmp_le_i32_e32 vcc, 0x700, v16
	v_mfma_f32_32x32x16_bf16 v[18:33], v[46:49], v[64:67], 0
	v_mfma_f32_32x32x16_bf16 v[18:33], v[42:45], v[68:71], v[18:33]
	v_mfma_f32_32x32x16_bf16 v[18:33], v[38:41], v[72:75], v[18:33]
	v_mfma_f32_32x32x16_bf16 v[18:33], v[34:37], v[76:79], v[18:33]
	s_nop 11
	v_max_f32_e32 v18, 0, v18
	v_max_f32_e32 v19, 0, v19
	v_fma_f32 v18, v143, v18, 0
	v_fmac_f32_e32 v18, v142, v19
	v_max_f32_e32 v19, 0, v20
	v_fmac_f32_e32 v18, v141, v19
	v_max_f32_e32 v19, 0, v21
	v_fmac_f32_e32 v18, v140, v19
	v_max_f32_e32 v19, 0, v22
	v_fmac_f32_e32 v18, v139, v19
	v_max_f32_e32 v19, 0, v23
	v_fmac_f32_e32 v18, v138, v19
	v_max_f32_e32 v19, 0, v24
	v_fmac_f32_e32 v18, v137, v19
	v_max_f32_e32 v19, 0, v25
	v_fmac_f32_e32 v18, v136, v19
	v_max_f32_e32 v19, 0, v26
	v_fmac_f32_e32 v18, v135, v19
	v_max_f32_e32 v19, 0, v27
	v_fmac_f32_e32 v18, v134, v19
	v_max_f32_e32 v19, 0, v28
	v_fmac_f32_e32 v18, v133, v19
	v_max_f32_e32 v19, 0, v29
	v_fmac_f32_e32 v18, v132, v19
	v_max_f32_e32 v19, 0, v30
	v_fmac_f32_e32 v18, v131, v19
	v_max_f32_e32 v19, 0, v31
	v_fmac_f32_e32 v18, v130, v19
	v_max_f32_e32 v19, 0, v32
	v_fmac_f32_e32 v18, v129, v19
	v_max_f32_e32 v19, 0, v33
	v_fmac_f32_e32 v18, v128, v19
	v_ashrrev_i32_e32 v19, 31, v18
	v_bitop3_b32 v18, v19, v18, s8 bitop3:0x36
	v_cndmask_b32_e32 v205, 0, v18, vcc
	s_cmp_lt_u32 s0, 0x720
	s_cbranch_scc1 .Lix_z57
.Lix_b57:
	s_cmp_lt_u32 s0, 0x780
	s_cbranch_scc1 .Lix_w57
	s_add_u32 m0, s1, 0
	s_nop 0
	global_load_lds_dwordx4 v112, s[22:23]
	s_add_u32 s22, s22, 0x1e800
	s_addc_u32 s23, s23, 0
	s_add_u32 m0, s1, 0x400
	s_nop 0
	global_load_lds_dwordx4 v113, s[22:23]
	s_add_u32 s22, s22, 0x1e800
	s_addc_u32 s23, s23, 0
	s_add_u32 m0, s1, 0x800
	s_nop 0
	global_load_lds_dwordx4 v112, s[22:23]
	s_add_u32 s22, s22, 0x1e800
	s_addc_u32 s23, s23, 0
	s_add_u32 m0, s1, 0xc00
	s_nop 0
	global_load_lds_dwordx4 v113, s[22:23]
	s_add_u32 s22, s22, 0x1e800
	s_addc_u32 s23, s23, 0
	s_waitcnt vmcnt(8)
	s_branch .Lix_r57

; #define MFMA(a, b, c) __builtin_amdgcn_mfma_f32_32x32x16_bf16((a), (b), (c), 0, 0, 0)
; DI void indexer_phase(const u16* __restrict__ P, unsigned* __restrict__ mask) {
;     ...
;         const u16* kp = P + (brow + 32 * kb + r32) * 7808 + 3584 + 8 * hi;
; #pragma unroll
;         for (int s = 0; s < 4; ++s) { const bf16x8 bk = *(const bf16x8*)(kp + 16 * s); a = MFMA(aq[s], bk, a); }
.Lix_r57:
	s_cmp_lt_u32 s0, 0x740
	s_cbranch_scc1 .Lix_n57
	ds_read_b128 v[64:67], v114 offset:8192
	ds_read_b128 v[68:71], v115 offset:8192
	ds_read_b128 v[72:75], v116 offset:8192
	ds_read_b128 v[76:79], v117 offset:8192
	s_waitcnt lgkmcnt(4)
	s_branch .Lix_m57

; #define MFMA(a, b, c) __builtin_amdgcn_mfma_f32_32x32x16_bf16((a), (b), (c), 0, 0, 0)
; DI unsigned ordkey(float f) { const unsigned b = __float_as_uint(f); return b ^ ((unsigned)((int)b >> 31) | 0x80000000u); }
; DI void indexer_phase(const u16* __restrict__ P, unsigned* __restrict__ mask) {
;     ...
;     for (int kb = 0; kb < 64; ++kb) {
;       unsigned u = 0u;
;       if (kb <= kbmax) {
;         f32x16 a;
; #pragma unroll
;         for (int r = 0; r < 16; ++r) a[r] = 0.f;
;         const u16* kp = P + (brow + 32 * kb + r32) * 7808 + 3584 + 8 * hi;
; #pragma unroll
;         for (int s = 0; s < 4; ++s) { const bf16x8 bk = *(const bf16x8*)(kp + 16 * s); a = MFMA(aq[s], bk, a); }
;         float v = 0.f;
; #pragma unroll
;         for (int i = 0; i < 16; ++i) v = fmaf(wv[i], fmaxf(a[i], 0.f), v);
;         u = (32 * kb + r32 <= tme) ? ordkey(v) : 0u;
;       }
;       sc[kb] = u;
.Lix_m57:
	v_cmp_le_i32_e32 vcc, 0x720, v16
	v_mfma_f32_32x32x16_bf16 v[18:33], v[46:49], v[80:83], 0
	v_mfma_f32_32x32x16_bf16 v[18:33], v[42:45], v[84:87], v[18:33]
	v_mfma_f32_32x32x16_bf16 v[18:33], v[38:41], v[88:91], v[18:33]
	v_mfma_f32_32x32x16_bf16 v[18:33], v[34:37], v[92:95], v[18:33]
	s_nop 11
	v_max_f32_e32 v18, 0, v18
	v_max_f32_e32 v19, 0, v19
	v_fma_f32 v18, v143, v18, 0
	v_fmac_f32_e32 v18, v142, v19
	v_max_f32_e32 v19, 0, v20
	v_fmac_f32_e32 v18, v141, v19
	v_max_f32_e32 v19, 0, v21
	v_fmac_f32_e32 v18, v140, v19
	v_max_f32_e32 v19, 0, v22
	v_fmac_f32_e32 v18, v139, v19
	v_max_f32_e32 v19, 0, v23
	v_fmac_f32_e32 v18, v138, v19
	v_max_f32_e32 v19, 0, v24
	v_fmac_f32_e32 v18, v137, v19
	v_max_f32_e32 v19, 0, v25
	v_fmac_f32_e32 v18, v136, v19
	v_max_f32_e32 v19, 0, v26
	v_fmac_f32_e32 v18, v135, v19
	v_max_f32_e32 v19, 0, v27
	v_fmac_f32_e32 v18, v134, v19
	v_max_f32_e32 v19, 0, v28
	v_fmac_f32_e32 v18, v133, v19
	v_max_f32_e32 v19, 0, v29
	v_fmac_f32_e32 v18, v132, v19
	v_max_f32_e32 v19, 0, v30
	v_fmac_f32_e32 v18, v131, v19
	v_max_f32_e32 v19, 0, v31
	v_fmac_f32_e32 v18, v130, v19
	v_max_f32_e32 v19, 0, v32
	v_fmac_f32_e32 v18, v129, v19
	v_max_f32_e32 v19, 0, v33
	v_fmac_f32_e32 v18, v128, v19
	v_ashrrev_i32_e32 v19, 31, v18
	v_bitop3_b32 v18, v19, v18, s8 bitop3:0x36
	v_cndmask_b32_e32 v236, 0, v18, vcc
	s_cmp_lt_u32 s0, 0x740
	s_cbranch_scc1 .Lix_z58
.Lix_b58:
	s_cmp_lt_u32 s0, 0x7a0
	s_cbranch_scc1 .Lix_w58
	s_add_u32 m0, s1, 0x1000
	s_nop 0
	global_load_lds_dwordx4 v112, s[22:23]
	s_add_u32 s22, s22, 0x1e800
	s_addc_u32 s23, s23, 0
	s_add_u32 m0, s1, 0x1400
	s_nop 0
	global_load_lds_dwordx4 v113, s[22:23]
	s_add_u32 s22, s22, 0x1e800
	s_addc_u32 s23, s23, 0
	s_add_u32 m0, s1, 0x1800
	s_nop 0
	global_load_lds_dwordx4 v112, s[22:23]
	s_add_u32 s22, s22, 0x1e800
	s_addc_u32 s23, s23, 0
	s_add_u32 m0, s1, 0x1c00
	s_nop 0
	global_load_lds_dwordx4 v113, s[22:23]
	s_add_u32 s22, s22, 0x1e800
	s_addc_u32 s23, s23, 0
	s_waitcnt vmcnt(8)
	s_branch .Lix_r58

; #define MFMA(a, b, c) __builtin_amdgcn_mfma_f32_32x32x16_bf16((a), (b), (c), 0, 0, 0)
; DI void indexer_phase(const u16* __restrict__ P, unsigned* __restrict__ mask) {
;     ...
;         const u16* kp = P + (brow + 32 * kb + r32) * 7808 + 3584 + 8 * hi;
; #pragma unroll
;         for (int s = 0; s < 4; ++s) { const bf16x8 bk = *(const bf16x8*)(kp + 16 * s); a = MFMA(aq[s], bk, a); }
.Lix_r58:
	s_cmp_lt_u32 s0, 0x760
	s_cbranch_scc1 .Lix_n58
	ds_read_b128 v[80:83], v114 offset:12288
	ds_read_b128 v[84:87], v115 offset:12288
	ds_read_b128 v[88:91], v116 offset:12288
	ds_read_b128 v[92:95], v117 offset:12288
	s_waitcnt lgkmcnt(4)
	s_branch .Lix_m58

; #define MFMA(a, b, c) __builtin_amdgcn_mfma_f32_32x32x16_bf16((a), (b), (c), 0, 0, 0)
; DI unsigned ordkey(float f) { const unsigned b = __float_as_uint(f); return b ^ ((unsigned)((int)b >> 31) | 0x80000000u); }
; DI void indexer_phase(const u16* __restrict__ P, unsigned* __restrict__ mask) {
;     ...
;     for (int kb = 0; kb < 64; ++kb) {
;       unsigned u = 0u;
;       if (kb <= kbmax) {
;         f32x16 a;
; #pragma unroll
;         for (int r = 0; r < 16; ++r) a[r] = 0.f;
;         const u16* kp = P + (brow + 32 * kb + r32) * 7808 + 3584 + 8 * hi;
; #pragma unroll
;         for (int s = 0; s < 4; ++s) { const bf16x8 bk = *(const bf16x8*)(kp + 16 * s); a = MFMA(aq[s], bk, a); }
;         float v = 0.f;
; #pragma unroll
;         for (int i = 0; i < 16; ++i) v = fmaf(wv[i], fmaxf(a[i], 0.f), v);
;         u = (32 * kb + r32 <= tme) ? ordkey(v) : 0u;
;       }
;       sc[kb] = u;
.Lix_m58:
	v_cmp_le_i32_e32 vcc, 0x740, v16
	v_mfma_f32_32x32x16_bf16 v[18:33], v[46:49], v[64:67], 0
	v_mfma_f32_32x32x16_bf16 v[18:33], v[42:45], v[68:71], v[18:33]
	v_mfma_f32_32x32x16_bf16 v[18:33], v[38:41], v[72:75], v[18:33]
	v_mfma_f32_32x32x16_bf16 v[18:33], v[34:37], v[76:79], v[18:33]
	s_nop 11
	v_max_f32_e32 v18, 0, v18
	v_max_f32_e32 v19, 0, v19
	v_fma_f32 v18, v143, v18, 0
	v_fmac_f32_e32 v18, v142, v19
	v_max_f32_e32 v19, 0, v20
	v_fmac_f32_e32 v18, v141, v19
	v_max_f32_e32 v19, 0, v21
	v_fmac_f32_e32 v18, v140, v19
	v_max_f32_e32 v19, 0, v22
	v_fmac_f32_e32 v18, v139, v19
	v_max_f32_e32 v19, 0, v23
	v_fmac_f32_e32 v18, v138, v19
	v_max_f32_e32 v19, 0, v24
	v_fmac_f32_e32 v18, v137, v19
	v_max_f32_e32 v19, 0, v25
	v_fmac_f32_e32 v18, v136, v19
	v_max_f32_e32 v19, 0, v26
	v_fmac_f32_e32 v18, v135, v19
	v_max_f32_e32 v19, 0, v27
	v_fmac_f32_e32 v18, v134, v19
	v_max_f32_e32 v19, 0, v28
	v_fmac_f32_e32 v18, v133, v19
	v_max_f32_e32 v19, 0, v29
	v_fmac_f32_e32 v18, v132, v19
	v_max_f32_e32 v19, 0, v30
	v_fmac_f32_e32 v18, v131, v19
	v_max_f32_e32 v19, 0, v31
	v_fmac_f32_e32 v18, v130, v19
	v_max_f32_e32 v19, 0, v32
	v_fmac_f32_e32 v18, v129, v19
	v_max_f32_e32 v19, 0, v33
	v_fmac_f32_e32 v18, v128, v19
	v_ashrrev_i32_e32 v19, 31, v18
	v_bitop3_b32 v18, v19, v18, s8 bitop3:0x36
	v_cndmask_b32_e32 v207, 0, v18, vcc
	s_cmp_lt_u32 s0, 0x760
	s_cbranch_scc1 .Lix_z59
.Lix_b59:
	s_cmp_lt_u32 s0, 0x7c0
	s_cbranch_scc1 .Lix_w59
	s_add_u32 m0, s1, 0x2000
	s_nop 0
	global_load_lds_dwordx4 v112, s[22:23]
	s_add_u32 s22, s22, 0x1e800
	s_addc_u32 s23, s23, 0
	s_add_u32 m0, s1, 0x2400
	s_nop 0
	global_load_lds_dwordx4 v113, s[22:23]
	s_add_u32 s22, s22, 0x1e800
	s_addc_u32 s23, s23, 0
	s_add_u32 m0, s1, 0x2800
	s_nop 0
	global_load_lds_dwordx4 v112, s[22:23]
	s_add_u32 s22, s22, 0x1e800
	s_addc_u32 s23, s23, 0
	s_add_u32 m0, s1, 0x2c00
	s_nop 0
	global_load_lds_dwordx4 v113, s[22:23]
	s_add_u32 s22, s22, 0x1e800
	s_addc_u32 s23, s23, 0
	s_waitcnt vmcnt(8)
	s_branch .Lix_r59

; #define MFMA(a, b, c) __builtin_amdgcn_mfma_f32_32x32x16_bf16((a), (b), (c), 0, 0, 0)
; DI void indexer_phase(const u16* __restrict__ P, unsigned* __restrict__ mask) {
;     ...
;         const u16* kp = P + (brow + 32 * kb + r32) * 7808 + 3584 + 8 * hi;
; #pragma unroll
;         for (int s = 0; s < 4; ++s) { const bf16x8 bk = *(const bf16x8*)(kp + 16 * s); a = MFMA(aq[s], bk, a); }
.Lix_r59:
	s_cmp_lt_u32 s0, 0x780
	s_cbranch_scc1 .Lix_n59
	ds_read_b128 v[64:67], v114
	ds_read_b128 v[68:71], v115
	ds_read_b128 v[72:75], v116
	ds_read_b128 v[76:79], v117
	s_waitcnt lgkmcnt(4)
	s_branch .Lix_m59

; #define MFMA(a, b, c) __builtin_amdgcn_mfma_f32_32x32x16_bf16((a), (b), (c), 0, 0, 0)
; DI unsigned ordkey(float f) { const unsigned b = __float_as_uint(f); return b ^ ((unsigned)((int)b >> 31) | 0x80000000u); }
; DI void indexer_phase(const u16* __restrict__ P, unsigned* __restrict__ mask) {
;     ...
;     for (int kb = 0; kb < 64; ++kb) {
;       unsigned u = 0u;
;       if (kb <= kbmax) {
;         f32x16 a;
; #pragma unroll
;         for (int r = 0; r < 16; ++r) a[r] = 0.f;
;         const u16* kp = P + (brow + 32 * kb + r32) * 7808 + 3584 + 8 * hi;
; #pragma unroll
;         for (int s = 0; s < 4; ++s) { const bf16x8 bk = *(const bf16x8*)(kp + 16 * s); a = MFMA(aq[s], bk, a); }
;         float v = 0.f;
; #pragma unroll
;         for (int i = 0; i < 16; ++i) v = fmaf(wv[i], fmaxf(a[i], 0.f), v);
;         u = (32 * kb + r32 <= tme) ? ordkey(v) : 0u;
;       }
;       sc[kb] = u;
;     }
.Lix_m59:
	v_cmp_le_i32_e32 vcc, 0x760, v16
	v_mfma_f32_32x32x16_bf16 v[18:33], v[46:49], v[80:83], 0
	v_mfma_f32_32x32x16_bf16 v[18:33], v[42:45], v[84:87], v[18:33]
	v_mfma_f32_32x32x16_bf16 v[18:33], v[38:41], v[88:91], v[18:33]
	v_mfma_f32_32x32x16_bf16 v[18:33], v[34:37], v[92:95], v[18:33]
	s_nop 11
	v_max_f32_e32 v18, 0, v18
	v_max_f32_e32 v19, 0, v19
	v_fma_f32 v18, v143, v18, 0
	v_fmac_f32_e32 v18, v142, v19
	v_max_f32_e32 v19, 0, v20
	v_fmac_f32_e32 v18, v141, v19
	v_max_f32_e32 v19, 0, v21
	v_fmac_f32_e32 v18, v140, v19
	v_max_f32_e32 v19, 0, v22
	v_fmac_f32_e32 v18, v139, v19
	v_max_f32_e32 v19, 0, v23
	v_fmac_f32_e32 v18, v138, v19
	v_max_f32_e32 v19, 0, v24
	v_fmac_f32_e32 v18, v137, v19
	v_max_f32_e32 v19, 0, v25
	v_fmac_f32_e32 v18, v136, v19
	v_max_f32_e32 v19, 0, v26
	v_fmac_f32_e32 v18, v135, v19
	v_max_f32_e32 v19, 0, v27
	v_fmac_f32_e32 v18, v134, v19
	v_max_f32_e32 v19, 0, v28
	v_fmac_f32_e32 v18, v133, v19
	v_max_f32_e32 v19, 0, v29
	v_fmac_f32_e32 v18, v132, v19
	v_max_f32_e32 v19, 0, v30
	v_fmac_f32_e32 v18, v131, v19
	v_max_f32_e32 v19, 0, v31
	v_fmac_f32_e32 v18, v130, v19
	v_max_f32_e32 v19, 0, v32
	v_fmac_f32_e32 v18, v129, v19
	v_max_f32_e32 v19, 0, v33
	v_fmac_f32_e32 v18, v128, v19
	v_ashrrev_i32_e32 v19, 31, v18
	v_bitop3_b32 v18, v19, v18, s8 bitop3:0x36
	v_cndmask_b32_e32 v238, 0, v18, vcc
	s_cmp_lt_u32 s0, 0x780
	s_cbranch_scc1 .Lix_z60
.Lix_b60:
	s_cmp_lt_u32 s0, 0x7e0
	s_cbranch_scc1 .Lix_w60
	s_add_u32 m0, s1, 0x3000
	s_nop 0
	global_load_lds_dwordx4 v112, s[22:23]
	s_add_u32 s22, s22, 0x1e800
	s_addc_u32 s23, s23, 0
	s_add_u32 m0, s1, 0x3400
	s_nop 0
	global_load_lds_dwordx4 v113, s[22:23]
	s_add_u32 s22, s22, 0x1e800
	s_addc_u32 s23, s23, 0
	s_add_u32 m0, s1, 0x3800
	s_nop 0
	global_load_lds_dwordx4 v112, s[22:23]
	s_add_u32 s22, s22, 0x1e800
	s_addc_u32 s23, s23, 0
	s_add_u32 m0, s1, 0x3c00
	s_nop 0
	global_load_lds_dwordx4 v113, s[22:23]
	s_add_u32 s22, s22, 0x1e800
	s_addc_u32 s23, s23, 0
	s_waitcnt vmcnt(8)
	s_branch .Lix_r60

; #define MFMA(a, b, c) __builtin_amdgcn_mfma_f32_32x32x16_bf16((a), (b), (c), 0, 0, 0)
; DI void indexer_phase(const u16* __restrict__ P, unsigned* __restrict__ mask) {
;     ...
;     for (int kb = 0; kb < 64; ++kb) {
;       unsigned u = 0u;
;       if (kb <= kbmax) {
;         f32x16 a;
; #pragma unroll
;         for (int r = 0; r < 16; ++r) a[r] = 0.f;
;         const u16* kp = P + (brow + 32 * kb + r32) * 7808 + 3584 + 8 * hi;
; #pragma unroll
;         for (int s = 0; s < 4; ++s) { const bf16x8 bk = *(const bf16x8*)(kp + 16 * s); a = MFMA(aq[s], bk, a); }
.Lix_r60:
	s_cmp_lt_u32 s0, 0x7a0
	s_cbranch_scc1 .Lix_n60
	ds_read_b128 v[80:83], v114 offset:4096
	ds_read_b128 v[84:87], v115 offset:4096
	ds_read_b128 v[88:91], v116 offset:4096
	ds_read_b128 v[92:95], v117 offset:4096
	s_waitcnt lgkmcnt(4)
	s_branch .Lix_m60

; #define MFMA(a, b, c) __builtin_amdgcn_mfma_f32_32x32x16_bf16((a), (b), (c), 0, 0, 0)
; DI unsigned ordkey(float f) { const unsigned b = __float_as_uint(f); return b ^ ((unsigned)((int)b >> 31) | 0x80000000u); }
; DI void indexer_phase(const u16* __restrict__ P, unsigned* __restrict__ mask) {
;     ...
;     for (int kb = 0; kb < 64; ++kb) {
;       unsigned u = 0u;
;       if (kb <= kbmax) {
;         f32x16 a;
; #pragma unroll
;         for (int r = 0; r < 16; ++r) a[r] = 0.f;
;         const u16* kp = P + (brow + 32 * kb + r32) * 7808 + 3584 + 8 * hi;
; #pragma unroll
;         for (int s = 0; s < 4; ++s) { const bf16x8 bk = *(const bf16x8*)(kp + 16 * s); a = MFMA(aq[s], bk, a); }
;         float v = 0.f;
; #pragma unroll
;         for (int i = 0; i < 16; ++i) v = fmaf(wv[i], fmaxf(a[i], 0.f), v);
;         u = (32 * kb + r32 <= tme) ? ordkey(v) : 0u;
;       }
;       sc[kb] = u;
;     }
.Lix_m60:
	v_cmp_le_i32_e32 vcc, 0x780, v16
	v_mfma_f32_32x32x16_bf16 v[18:33], v[46:49], v[64:67], 0
	v_mfma_f32_32x32x16_bf16 v[18:33], v[42:45], v[68:71], v[18:33]
	v_mfma_f32_32x32x16_bf16 v[18:33], v[38:41], v[72:75], v[18:33]
	v_mfma_f32_32x32x16_bf16 v[18:33], v[34:37], v[76:79], v[18:33]
	s_nop 11
	v_max_f32_e32 v18, 0, v18
	v_max_f32_e32 v19, 0, v19
	v_fma_f32 v18, v143, v18, 0
	v_fmac_f32_e32 v18, v142, v19
	v_max_f32_e32 v19, 0, v20
	v_fmac_f32_e32 v18, v141, v19
	v_max_f32_e32 v19, 0, v21
	v_fmac_f32_e32 v18, v140, v19
	v_max_f32_e32 v19, 0, v22
	v_fmac_f32_e32 v18, v139, v19
	v_max_f32_e32 v19, 0, v23
	v_fmac_f32_e32 v18, v138, v19
	v_max_f32_e32 v19, 0, v24
	v_fmac_f32_e32 v18, v137, v19
	v_max_f32_e32 v19, 0, v25
	v_fmac_f32_e32 v18, v136, v19
	v_max_f32_e32 v19, 0, v26
	v_fmac_f32_e32 v18, v135, v19
	v_max_f32_e32 v19, 0, v27
	v_fmac_f32_e32 v18, v134, v19
	v_max_f32_e32 v19, 0, v28
	v_fmac_f32_e32 v18, v133, v19
	v_max_f32_e32 v19, 0, v29
	v_fmac_f32_e32 v18, v132, v19
	v_max_f32_e32 v19, 0, v30
	v_fmac_f32_e32 v18, v131, v19
	v_max_f32_e32 v19, 0, v31
	v_fmac_f32_e32 v18, v130, v19
	v_max_f32_e32 v19, 0, v32
	v_fmac_f32_e32 v18, v129, v19
	v_max_f32_e32 v19, 0, v33
	v_fmac_f32_e32 v18, v128, v19
	v_ashrrev_i32_e32 v19, 31, v18
	v_bitop3_b32 v18, v19, v18, s8 bitop3:0x36
	v_cndmask_b32_e32 v237, 0, v18, vcc
	s_cmp_lt_u32 s0, 0x7a0
	s_cbranch_scc1 .Lix_z61
.Lix_b61:
	s_waitcnt vmcnt(0)
	s_cmp_lt_u32 s0, 0x7c0
	s_cbranch_scc1 .Lix_n61
	ds_read_b128 v[64:67], v114 offset:8192
	ds_read_b128 v[68:71], v115 offset:8192
	ds_read_b128 v[72:75], v116 offset:8192
	ds_read_b128 v[76:79], v117 offset:8192
	s_waitcnt lgkmcnt(4)
	s_branch .Lix_m61

; #define MFMA(a, b, c) __builtin_amdgcn_mfma_f32_32x32x16_bf16((a), (b), (c), 0, 0, 0)
; DI unsigned ordkey(float f) { const unsigned b = __float_as_uint(f); return b ^ ((unsigned)((int)b >> 31) | 0x80000000u); }
; DI void indexer_phase(const u16* __restrict__ P, unsigned* __restrict__ mask) {
;     ...
;     for (int kb = 0; kb < 64; ++kb) {
;       unsigned u = 0u;
;       if (kb <= kbmax) {
;         f32x16 a;
; #pragma unroll
;         for (int r = 0; r < 16; ++r) a[r] = 0.f;
;         const u16* kp = P + (brow + 32 * kb + r32) * 7808 + 3584 + 8 * hi;
; #pragma unroll
;         for (int s = 0; s < 4; ++s) { const bf16x8 bk = *(const bf16x8*)(kp + 16 * s); a = MFMA(aq[s], bk, a); }
;         float v = 0.f;
; #pragma unroll
;         for (int i = 0; i < 16; ++i) v = fmaf(wv[i], fmaxf(a[i], 0.f), v);
;         u = (32 * kb + r32 <= tme) ? ordkey(v) : 0u;
;       }
;       sc[kb] = u;
;     }
.Lix_m61:
	v_cmp_le_i32_e32 vcc, 0x7a0, v16
	v_mfma_f32_32x32x16_bf16 v[18:33], v[46:49], v[80:83], 0
	v_mfma_f32_32x32x16_bf16 v[18:33], v[42:45], v[84:87], v[18:33]
	v_mfma_f32_32x32x16_bf16 v[18:33], v[38:41], v[88:91], v[18:33]
	v_mfma_f32_32x32x16_bf16 v[18:33], v[34:37], v[92:95], v[18:33]
	s_nop 11
	v_max_f32_e32 v18, 0, v18
	v_max_f32_e32 v19, 0, v19
	v_fma_f32 v18, v143, v18, 0
	v_fmac_f32_e32 v18, v142, v19
	v_max_f32_e32 v19, 0, v20
	v_fmac_f32_e32 v18, v141, v19
	v_max_f32_e32 v19, 0, v21
	v_fmac_f32_e32 v18, v140, v19
	v_max_f32_e32 v19, 0, v22
	v_fmac_f32_e32 v18, v139, v19
	v_max_f32_e32 v19, 0, v23
	v_fmac_f32_e32 v18, v138, v19
	v_max_f32_e32 v19, 0, v24
	v_fmac_f32_e32 v18, v137, v19
	v_max_f32_e32 v19, 0, v25
	v_fmac_f32_e32 v18, v136, v19
	v_max_f32_e32 v19, 0, v26
	v_fmac_f32_e32 v18, v135, v19
	v_max_f32_e32 v19, 0, v27
	v_fmac_f32_e32 v18, v134, v19
	v_max_f32_e32 v19, 0, v28
	v_fmac_f32_e32 v18, v133, v19
	v_max_f32_e32 v19, 0, v29
	v_fmac_f32_e32 v18, v132, v19
	v_max_f32_e32 v19, 0, v30
	v_fmac_f32_e32 v18, v131, v19
	v_max_f32_e32 v19, 0, v31
	v_fmac_f32_e32 v18, v130, v19
	v_max_f32_e32 v19, 0, v32
	v_fmac_f32_e32 v18, v129, v19
	v_max_f32_e32 v19, 0, v33
	v_fmac_f32_e32 v18, v128, v19
	v_ashrrev_i32_e32 v19, 31, v18
	v_bitop3_b32 v18, v19, v18, s8 bitop3:0x36
	v_cndmask_b32_e32 v240, 0, v18, vcc
	s_cmp_lt_u32 s0, 0x7c0
	s_cbranch_scc1 .Lix_z62
.Lix_b62:
	s_waitcnt vmcnt(0)
	s_cmp_lt_u32 s0, 0x7e0
	s_cbranch_scc1 .Lix_n62
	ds_read_b128 v[80:83], v114 offset:12288
	ds_read_b128 v[84:87], v115 offset:12288
	ds_read_b128 v[88:91], v116 offset:12288
	ds_read_b128 v[92:95], v117 offset:12288
	s_waitcnt lgkmcnt(4)
	s_branch .Lix_m62

; #define MFMA(a, b, c) __builtin_amdgcn_mfma_f32_32x32x16_bf16((a), (b), (c), 0, 0, 0)
; DI unsigned ordkey(float f) { const unsigned b = __float_as_uint(f); return b ^ ((unsigned)((int)b >> 31) | 0x80000000u); }
; DI void indexer_phase(const u16* __restrict__ P, unsigned* __restrict__ mask) {
;     ...
;     for (int kb = 0; kb < 64; ++kb) {
;       unsigned u = 0u;
;       if (kb <= kbmax) {
;         f32x16 a;
; #pragma unroll
;         for (int r = 0; r < 16; ++r) a[r] = 0.f;
;         const u16* kp = P + (brow + 32 * kb + r32) * 7808 + 3584 + 8 * hi;
; #pragma unroll
;         for (int s = 0; s < 4; ++s) { const bf16x8 bk = *(const bf16x8*)(kp + 16 * s); a = MFMA(aq[s], bk, a); }
;         float v = 0.f;
; #pragma unroll
;         for (int i = 0; i < 16; ++i) v = fmaf(wv[i], fmaxf(a[i], 0.f), v);
;         u = (32 * kb + r32 <= tme) ? ordkey(v) : 0u;
;       }
;       sc[kb] = u;
;     }
.Lix_m62:
	v_cmp_le_i32_e32 vcc, 0x7c0, v16
	v_mfma_f32_32x32x16_bf16 v[18:33], v[46:49], v[64:67], 0
	v_mfma_f32_32x32x16_bf16 v[18:33], v[42:45], v[68:71], v[18:33]
	v_mfma_f32_32x32x16_bf16 v[18:33], v[38:41], v[72:75], v[18:33]
	v_mfma_f32_32x32x16_bf16 v[18:33], v[34:37], v[76:79], v[18:33]
	s_nop 11
	v_max_f32_e32 v18, 0, v18
	v_max_f32_e32 v19, 0, v19
	v_fma_f32 v18, v143, v18, 0
	v_fmac_f32_e32 v18, v142, v19
	v_max_f32_e32 v19, 0, v20
	v_fmac_f32_e32 v18, v141, v19
	v_max_f32_e32 v19, 0, v21
	v_fmac_f32_e32 v18, v140, v19
	v_max_f32_e32 v19, 0, v22
	v_fmac_f32_e32 v18, v139, v19
	v_max_f32_e32 v19, 0, v23
	v_fmac_f32_e32 v18, v138, v19
	v_max_f32_e32 v19, 0, v24
	v_fmac_f32_e32 v18, v137, v19
	v_max_f32_e32 v19, 0, v25
	v_fmac_f32_e32 v18, v136, v19
	v_max_f32_e32 v19, 0, v26
	v_fmac_f32_e32 v18, v135, v19
	v_max_f32_e32 v19, 0, v27
	v_fmac_f32_e32 v18, v134, v19
	v_max_f32_e32 v19, 0, v28
	v_fmac_f32_e32 v18, v133, v19
	v_max_f32_e32 v19, 0, v29
	v_fmac_f32_e32 v18, v132, v19
	v_max_f32_e32 v19, 0, v30
	v_fmac_f32_e32 v18, v131, v19
	v_max_f32_e32 v19, 0, v31
	v_fmac_f32_e32 v18, v130, v19
	v_max_f32_e32 v19, 0, v32
	v_fmac_f32_e32 v18, v129, v19
	v_max_f32_e32 v19, 0, v33
	v_fmac_f32_e32 v18, v128, v19
	v_ashrrev_i32_e32 v19, 31, v18
	v_bitop3_b32 v18, v19, v18, s8 bitop3:0x36
	v_cndmask_b32_e32 v239, 0, v18, vcc
	s_cmp_lt_u32 s0, 0x7e0
	s_cbranch_scc1 .Lix_z63
.Lix_b63:
	s_waitcnt vmcnt(0)
	s_waitcnt lgkmcnt(0)
	v_cmp_le_i32_e32 vcc, 0x7e0, v16
	v_mfma_f32_32x32x16_bf16 v[18:33], v[46:49], v[80:83], 0
	v_mfma_f32_32x32x16_bf16 v[18:33], v[42:45], v[84:87], v[18:33]
	v_mfma_f32_32x32x16_bf16 v[18:33], v[38:41], v[88:91], v[18:33]
	v_mfma_f32_32x32x16_bf16 v[18:33], v[34:37], v[92:95], v[18:33]
	s_nop 11
	v_max_f32_e32 v18, 0, v18
	v_max_f32_e32 v19, 0, v19
	v_fma_f32 v18, v143, v18, 0
	v_fmac_f32_e32 v18, v142, v19
	v_max_f32_e32 v19, 0, v20
	v_fmac_f32_e32 v18, v141, v19
	v_max_f32_e32 v19, 0, v21
	v_fmac_f32_e32 v18, v140, v19
	v_max_f32_e32 v19, 0, v22
	v_fmac_f32_e32 v18, v139, v19
	v_max_f32_e32 v19, 0, v23
	v_fmac_f32_e32 v18, v138, v19
	v_max_f32_e32 v19, 0, v24
	v_fmac_f32_e32 v18, v137, v19
	v_max_f32_e32 v19, 0, v25
	v_fmac_f32_e32 v18, v136, v19
	v_max_f32_e32 v19, 0, v26
	v_fmac_f32_e32 v18, v135, v19
	v_max_f32_e32 v19, 0, v27
	v_fmac_f32_e32 v18, v134, v19
	v_max_f32_e32 v19, 0, v28
	v_fmac_f32_e32 v18, v133, v19
	v_max_f32_e32 v19, 0, v29
	v_fmac_f32_e32 v18, v132, v19
	v_max_f32_e32 v19, 0, v30
	v_fmac_f32_e32 v18, v131, v19
	v_max_f32_e32 v19, 0, v31
	v_fmac_f32_e32 v18, v130, v19
	v_max_f32_e32 v19, 0, v32
	v_fmac_f32_e32 v18, v129, v19
	v_max_f32_e32 v19, 0, v33
	v_fmac_f32_e32 v18, v128, v19
	v_ashrrev_i32_e32 v19, 31, v18
	v_bitop3_b32 v18, v19, v18, s8 bitop3:0x36
	v_cndmask_b32_e32 v18, 0, v18, vcc
	s_branch .Lix_done
